# up and down GEMM k-loops software-pipelined like inproj; wave_sum xor butterflies in norm_in/gated/row_update via DPP row_ror instead of ds_bpermute
# speedup vs baseline: 1.0631x; 1.0239x over previous
.LBB0_94:
	s_or_b64 exec, exec, s[22:23]
	v_lshl_add_u64 v[18:19], v[18:19], 2, s[10:11]
	v_lshl_add_u64 v[52:53], v[18:19], 0, s[14:15]
	v_lshl_add_u64 v[64:65], v[52:53], 0, v[32:33]
	global_load_dwordx4 v[20:23], v[34:35], off offset:16
	global_load_dwordx4 v[24:27], v[34:35], off
	global_load_dwordx4 v[28:31], v[64:65], off
	global_load_dwordx4 v[48:51], v[64:65], off offset:16
	v_lshl_add_u64 v[72:73], v[18:19], 0, v[32:33]
	global_load_dwordx4 v[64:67], v[72:73], off
	global_load_dwordx4 v[68:71], v[72:73], off offset:16
	v_mul_f32_e32 v18, v5, v5
	v_fmac_f32_e32 v18, v4, v4
	v_fmac_f32_e32 v18, v6, v6
	v_fmac_f32_e32 v18, v7, v7
	v_fmac_f32_e32 v18, v0, v0
	v_fmac_f32_e32 v18, v1, v1
	v_fmac_f32_e32 v18, v2, v2
	v_fmac_f32_e32 v18, v3, v3
	v_fmac_f32_e32 v18, v12, v12
	v_fmac_f32_e32 v18, v13, v13
	v_fmac_f32_e32 v18, v14, v14
	v_fmac_f32_e32 v18, v15, v15
	v_fmac_f32_e32 v18, v8, v8
	v_fmac_f32_e32 v18, v9, v9
	v_fmac_f32_e32 v18, v10, v10
	v_fmac_f32_e32 v18, v11, v11
	v_mov_b32_e32 v19, v18
	s_nop 1
	v_permlane32_swap_b32_e32 v18, v19
	v_add_f32_e32 v18, v18, v19
	v_mov_b32_e32 v19, v18
	s_nop 1
	v_permlane16_swap_b32_e32 v18, v19
	v_add_f32_e32 v18, v18, v19
	s_nop 1
	v_mov_b32_dpp v19, v18 row_ror:8 row_mask:0xf bank_mask:0xf
	v_lshl_add_u64 v[16:17], s[8:9], 0, v[16:17]
	s_waitcnt lgkmcnt(0)
	v_add_f32_e32 v18, v18, v19
	s_nop 1
	v_mov_b32_dpp v19, v18 row_ror:4 row_mask:0xf bank_mask:0xf
	s_waitcnt lgkmcnt(0)
	v_add_f32_e32 v47, v18, v19
	s_nop 1
	v_mov_b32_dpp v63, v47 row_ror:2 row_mask:0xf bank_mask:0xf
	v_cndmask_b32_e32 v18, v46, v43, vcc
	v_cndmask_b32_e64 v19, v39, 0, vcc
	v_lshlrev_b64 v[18:19], 11, v[18:19]
	v_mov_b32_e32 v39, v33
	s_waitcnt lgkmcnt(0)
	v_add_f32_e32 v46, v47, v63
	s_nop 1
	v_mov_b32_dpp v47, v46 row_ror:1 row_mask:0xf bank_mask:0xf
	v_lshl_add_u64 v[16:17], v[16:17], 0, v[18:19]
	v_lshl_add_u64 v[76:77], v[16:17], 0, v[38:39]
	v_mov_b32_e32 v43, v33
	v_lshl_add_u64 v[74:75], v[52:53], 0, v[42:43]
	s_waitcnt lgkmcnt(0)
	v_add_f32_e32 v46, v46, v47
	v_fmamk_f32 v46, v46, 0x3a800000, v62
	v_mul_f32_e32 v47, 0x4b800000, v46
	v_cmp_gt_f32_e32 vcc, s29, v46
	s_nop 1
	v_cndmask_b32_e32 v46, v46, v47, vcc
	v_rsq_f32_e32 v46, v46
	s_nop 0
	v_mul_f32_e32 v16, 0x45800000, v46
	v_cndmask_b32_e32 v78, v46, v16, vcc
	v_pk_mul_f32 v[16:17], v[4:5], v[78:79] op_sel_hi:[1,0]
	v_pk_mul_f32 v[18:19], v[6:7], v[78:79] op_sel_hi:[1,0]
	v_pk_mul_f32 v[46:47], v[0:1], v[78:79] op_sel_hi:[1,0]
	v_pk_mul_f32 v[52:53], v[2:3], v[78:79] op_sel_hi:[1,0]
	s_waitcnt vmcnt(5)
	v_pk_mul_f32 v[20:21], v[20:21], v[46:47]
	s_waitcnt vmcnt(4)
	v_pk_mul_f32 v[16:17], v[24:25], v[16:17]
	v_pk_mul_f32 v[18:19], v[26:27], v[18:19]
	v_pk_mul_f32 v[22:23], v[22:23], v[52:53]
	s_waitcnt vmcnt(3)
	v_pk_add_f32 v[24:25], v[28:29], 1.0 op_sel_hi:[1,0]
	v_pk_add_f32 v[26:27], v[30:31], 1.0 op_sel_hi:[1,0]
	s_waitcnt vmcnt(2)
	v_pk_add_f32 v[28:29], v[48:49], 1.0 op_sel_hi:[1,0]
	v_pk_add_f32 v[30:31], v[50:51], 1.0 op_sel_hi:[1,0]
	s_waitcnt vmcnt(1)
	v_pk_fma_f32 v[16:17], v[16:17], v[24:25], v[64:65]
	v_pk_fma_f32 v[18:19], v[18:19], v[26:27], v[66:67]
	s_waitcnt vmcnt(0)
	v_pk_fma_f32 v[20:21], v[20:21], v[28:29], v[68:69]
	v_pk_fma_f32 v[22:23], v[22:23], v[30:31], v[70:71]
	v_cvt_pk_bf16_f32 v16, v16, v17
	v_cvt_pk_bf16_f32 v17, v18, v19
	v_cvt_pk_bf16_f32 v18, v20, v21
	v_cvt_pk_bf16_f32 v19, v22, v23
	global_store_dwordx4 v[76:77], v[16:19], off
	global_load_dwordx4 v[16:19], v[34:35], off offset:2048
	s_nop 0
	global_load_dwordx4 v[20:23], v[74:75], off
	global_load_dwordx4 v[24:27], v[34:35], off offset:2064
	global_load_dwordx4 v[28:31], v[74:75], off offset:16
	global_load_dwordx4 v[46:49], v[72:73], off offset:2048
	global_load_dwordx4 v[50:53], v[72:73], off offset:2064
	v_pk_mul_f32 v[64:65], v[12:13], v[78:79] op_sel_hi:[1,0]
	v_pk_mul_f32 v[66:67], v[14:15], v[78:79] op_sel_hi:[1,0]
	v_pk_mul_f32 v[68:69], v[8:9], v[78:79] op_sel_hi:[1,0]
	v_pk_mul_f32 v[70:71], v[10:11], v[78:79] op_sel_hi:[1,0]
	s_waitcnt vmcnt(5)
	v_pk_mul_f32 v[16:17], v[64:65], v[16:17]
	s_waitcnt vmcnt(4)
	v_pk_add_f32 v[20:21], v[20:21], 1.0 op_sel_hi:[1,0]
	v_pk_mul_f32 v[18:19], v[66:67], v[18:19]
	v_pk_add_f32 v[22:23], v[22:23], 1.0 op_sel_hi:[1,0]
	s_waitcnt vmcnt(3)
	v_pk_mul_f32 v[24:25], v[68:69], v[24:25]
	s_waitcnt vmcnt(2)
	v_pk_add_f32 v[28:29], v[28:29], 1.0 op_sel_hi:[1,0]
	v_pk_mul_f32 v[26:27], v[70:71], v[26:27]
	v_pk_add_f32 v[30:31], v[30:31], 1.0 op_sel_hi:[1,0]
	s_waitcnt vmcnt(1)
	v_pk_fma_f32 v[16:17], v[16:17], v[20:21], v[46:47]
	v_pk_fma_f32 v[18:19], v[18:19], v[22:23], v[48:49]
	s_waitcnt vmcnt(0)
	v_pk_fma_f32 v[20:21], v[24:25], v[28:29], v[50:51]
	v_pk_fma_f32 v[22:23], v[26:27], v[30:31], v[52:53]
	v_cvt_pk_bf16_f32 v16, v16, v17
	v_cvt_pk_bf16_f32 v17, v18, v19
	v_cvt_pk_bf16_f32 v18, v20, v21
	v_cvt_pk_bf16_f32 v19, v22, v23
	global_store_dwordx4 v[76:77], v[16:19], off offset:1024

.LBB0_98:
	s_or_b64 exec, exec, s[22:23]
	v_mov_b64_e32 v[52:53], 0xc000
	v_mov_b64_e32 v[50:51], 0x6400000
	s_and_saveexec_b64 s[4:5], s[2:3]
	v_ashrrev_i32_e32 v47, 31, v63
	v_lshrrev_b32_e32 v47, 20, v47
	v_add_u32_e32 v47, v63, v47
	v_ashrrev_i32_e32 v47, 12, v47
	v_mul_hi_i32_i24_e32 v53, 0x1800, v47
	v_mul_i32_i24_e32 v52, 0x1800, v47
	v_mov_b64_e32 v[50:51], 0x2400000
	s_or_b64 exec, exec, s[4:5]
	v_lshl_add_u64 v[52:53], v[52:53], 2, s[10:11]
	v_lshl_add_u64 v[88:89], v[52:53], 0, s[14:15]
	v_lshl_add_u64 v[80:81], v[88:89], 0, v[32:33]
	global_load_dwordx4 v[64:67], v[34:35], off offset:16
	global_load_dwordx4 v[68:71], v[34:35], off
	global_load_dwordx4 v[72:75], v[80:81], off
	global_load_dwordx4 v[76:79], v[80:81], off offset:16
	v_lshl_add_u64 v[52:53], v[52:53], 0, v[32:33]
	global_load_dwordx4 v[80:83], v[52:53], off
	global_load_dwordx4 v[84:87], v[52:53], off offset:16
	s_waitcnt vmcnt(8)
	v_mul_f32_e32 v90, v29, v29
	v_pk_fma_f32 v[90:91], v[28:29], v[28:29], v[90:91] op_sel_hi:[1,1,0]
	v_mul_f32_e32 v92, v31, v31
	v_pk_fma_f32 v[90:91], v[30:31], v[30:31], v[90:91]
	v_mul_f32_e32 v94, v25, v25
	v_pk_add_f32 v[90:91], v[90:91], v[92:93] op_sel_hi:[1,0]
	v_mul_f32_e32 v96, v27, v27
	v_pk_fma_f32 v[90:91], v[24:25], v[24:25], v[90:91]
	s_waitcnt vmcnt(6)
	v_mul_f32_e32 v98, v21, v21
	v_pk_add_f32 v[90:91], v[90:91], v[94:95] op_sel_hi:[1,0]
	v_mul_f32_e32 v100, v23, v23
	v_pk_fma_f32 v[90:91], v[26:27], v[26:27], v[90:91]
	v_mul_f32_e32 v102, v17, v17
	v_pk_add_f32 v[90:91], v[90:91], v[96:97] op_sel_hi:[1,0]
	v_mul_f32_e32 v104, v19, v19
	v_pk_fma_f32 v[90:91], v[20:21], v[20:21], v[90:91]
	v_lshl_add_u64 v[50:51], s[8:9], 0, v[50:51]
	v_pk_add_f32 v[90:91], v[90:91], v[98:99] op_sel_hi:[1,0]
	v_lshlrev_b64 v[48:49], 11, v[48:49]
	v_pk_fma_f32 v[90:91], v[22:23], v[22:23], v[90:91]
	v_lshl_add_u64 v[48:49], v[50:51], 0, v[48:49]
	v_pk_add_f32 v[90:91], v[90:91], v[100:101] op_sel_hi:[1,0]
	v_lshl_add_u64 v[88:89], v[88:89], 0, v[44:45]
	v_pk_fma_f32 v[90:91], v[16:17], v[16:17], v[90:91]
	s_waitcnt vmcnt(3)
	v_pk_add_f32 v[50:51], v[74:75], 1.0 op_sel_hi:[1,0]
	v_pk_add_f32 v[90:91], v[90:91], v[102:103] op_sel_hi:[1,0]
	s_nop 0
	v_pk_fma_f32 v[90:91], v[18:19], v[18:19], v[90:91]
	s_nop 0
	v_pk_add_f32 v[90:91], v[90:91], v[104:105] op_sel_hi:[1,0]
	s_nop 0
	v_mov_b32_e32 v47, v90
	s_nop 1
	v_permlane32_swap_b32_e32 v90, v47
	v_add_f32_e32 v47, v90, v47
	v_mov_b32_e32 v63, v47
	s_nop 1
	v_permlane16_swap_b32_e32 v47, v63
	v_add_f32_e32 v47, v47, v63
	s_nop 1
	v_mov_b32_dpp v63, v47 row_ror:8 row_mask:0xf bank_mask:0xf
	v_lshl_add_u64 v[90:91], v[48:49], 0, v[40:41]
	s_waitcnt lgkmcnt(0)
	v_add_f32_e32 v47, v47, v63
	s_nop 1
	v_mov_b32_dpp v63, v47 row_ror:4 row_mask:0xf bank_mask:0xf
	s_waitcnt lgkmcnt(0)
	v_add_f32_e32 v47, v47, v63
	s_nop 1
	v_mov_b32_dpp v63, v47 row_ror:2 row_mask:0xf bank_mask:0xf
	s_waitcnt lgkmcnt(0)
	v_add_f32_e32 v47, v47, v63
	s_nop 1
	v_mov_b32_dpp v63, v47 row_ror:1 row_mask:0xf bank_mask:0xf
	s_waitcnt lgkmcnt(0)
	v_add_f32_e32 v47, v47, v63
	v_fmamk_f32 v47, v47, 0x3a800000, v62
	v_mul_f32_e32 v63, 0x4b800000, v47
	v_cmp_gt_f32_e64 s[2:3], s29, v47
	s_nop 1
	v_cndmask_b32_e64 v47, v47, v63, s[2:3]
	v_rsq_f32_e32 v47, v47
	s_nop 0
	v_mul_f32_e32 v48, 0x45800000, v47
	v_cndmask_b32_e64 v92, v47, v48, s[2:3]
	v_pk_mul_f32 v[28:29], v[28:29], v[92:93] op_sel_hi:[1,0]
	v_pk_mul_f32 v[30:31], v[30:31], v[92:93] op_sel_hi:[1,0]
	v_pk_mul_f32 v[24:25], v[24:25], v[92:93] op_sel_hi:[1,0]
	v_pk_mul_f32 v[26:27], v[26:27], v[92:93] op_sel_hi:[1,0]
	v_pk_mul_f32 v[28:29], v[68:69], v[28:29]
	v_pk_mul_f32 v[30:31], v[70:71], v[30:31]
	v_pk_mul_f32 v[24:25], v[64:65], v[24:25]
	v_pk_mul_f32 v[26:27], v[66:67], v[26:27]
	v_pk_add_f32 v[48:49], v[72:73], 1.0 op_sel_hi:[1,0]
	s_waitcnt vmcnt(2)
	v_pk_add_f32 v[64:65], v[76:77], 1.0 op_sel_hi:[1,0]
	v_pk_add_f32 v[66:67], v[78:79], 1.0 op_sel_hi:[1,0]
	s_waitcnt vmcnt(1)
	v_pk_fma_f32 v[28:29], v[28:29], v[48:49], v[80:81]
	v_pk_fma_f32 v[30:31], v[30:31], v[50:51], v[82:83]
	s_waitcnt vmcnt(0)
	v_pk_fma_f32 v[48:49], v[24:25], v[64:65], v[84:85]
	v_pk_fma_f32 v[50:51], v[26:27], v[66:67], v[86:87]
	v_cvt_pk_bf16_f32 v24, v28, v29
	v_cvt_pk_bf16_f32 v25, v30, v31
	v_cvt_pk_bf16_f32 v26, v48, v49
	v_cvt_pk_bf16_f32 v27, v50, v51
	global_store_dwordx4 v[90:91], v[24:27], off
	global_load_dwordx4 v[24:27], v[34:35], off offset:2048
	s_nop 0
	global_load_dwordx4 v[28:31], v[88:89], off
	global_load_dwordx4 v[48:51], v[34:35], off offset:2064
	global_load_dwordx4 v[64:67], v[88:89], off offset:16
	global_load_dwordx4 v[68:71], v[52:53], off offset:2048
	global_load_dwordx4 v[72:75], v[52:53], off offset:2064
	v_pk_mul_f32 v[20:21], v[20:21], v[92:93] op_sel_hi:[1,0]
	v_pk_mul_f32 v[22:23], v[22:23], v[92:93] op_sel_hi:[1,0]
	v_pk_mul_f32 v[16:17], v[16:17], v[92:93] op_sel_hi:[1,0]
	v_pk_mul_f32 v[18:19], v[18:19], v[92:93] op_sel_hi:[1,0]
	s_waitcnt vmcnt(5)
	v_pk_mul_f32 v[20:21], v[20:21], v[24:25]
	s_waitcnt vmcnt(4)
	v_pk_add_f32 v[24:25], v[28:29], 1.0 op_sel_hi:[1,0]
	v_pk_mul_f32 v[22:23], v[22:23], v[26:27]
	v_pk_add_f32 v[26:27], v[30:31], 1.0 op_sel_hi:[1,0]
	s_waitcnt vmcnt(3)
	v_pk_mul_f32 v[16:17], v[16:17], v[48:49]
	s_waitcnt vmcnt(2)
	v_pk_add_f32 v[28:29], v[64:65], 1.0 op_sel_hi:[1,0]
	v_pk_mul_f32 v[18:19], v[18:19], v[50:51]
	v_pk_add_f32 v[30:31], v[66:67], 1.0 op_sel_hi:[1,0]
	s_waitcnt vmcnt(1)
	v_pk_fma_f32 v[20:21], v[20:21], v[24:25], v[68:69]
	v_pk_fma_f32 v[22:23], v[22:23], v[26:27], v[70:71]
	s_waitcnt vmcnt(0)
	v_pk_fma_f32 v[24:25], v[16:17], v[28:29], v[72:73]
	v_pk_fma_f32 v[26:27], v[18:19], v[30:31], v[74:75]
	v_cvt_pk_bf16_f32 v16, v20, v21
	v_cvt_pk_bf16_f32 v17, v22, v23
	v_cvt_pk_bf16_f32 v18, v24, v25
	v_cvt_pk_bf16_f32 v19, v26, v27
	global_store_dwordx4 v[90:91], v[16:19], off offset:1024
	s_and_saveexec_b64 s[4:5], vcc
	s_cbranch_execz .LBB0_95
	v_cmp_lt_i32_e32 vcc, s28, v46
	v_cmp_gt_i32_e64 s[2:3], s27, v46
	v_mov_b64_e32 v[18:19], 0xc000
	v_mov_b64_e32 v[16:17], 0x6400000
	s_and_saveexec_b64 s[22:23], s[2:3]
	s_cbranch_execz .LBB0_94
	v_lshrrev_b32_e32 v16, 20, v39
	v_add_u32_e32 v16, v46, v16
	v_ashrrev_i32_e32 v16, 12, v16
	v_mul_hi_i32_i24_e32 v19, 0x1800, v16
	v_mul_i32_i24_e32 v18, 0x1800, v16
	v_mov_b64_e32 v[16:17], 0x2400000
	s_branch .LBB0_94

.LBB0_1961:
	v_lshl_add_u64 v[28:29], v[16:17], 0, v[8:9]
	v_lshl_add_u64 v[22:23], v[18:19], 0, v[8:9]
	global_load_dword v30, v[10:11], off
	global_load_dword v35, v[10:11], off offset:64
	global_load_dword v65, v[12:13], off
	global_load_dword v66, v[12:13], off offset:64
	global_load_dwordx4 v[0:3], v[14:15], off offset:16
	global_load_dwordx4 v[4:7], v[14:15], off
	global_load_dwordx4 v[24:27], v[22:23], off offset:-1024
	global_load_dwordx4 v[36:39], v[22:23], off
	v_add_co_u32_e32 v22, vcc, 0x8800000, v28
	v_lshl_add_u64 v[16:17], v[16:17], 0, s[4:5]
	s_nop 0
	v_addc_co_u32_e32 v23, vcc, 0, v29, vcc
	v_add_co_u32_e32 v56, vcc, s11, v28
	global_load_dwordx4 v[40:43], v[22:23], off
	global_load_dwordx4 v[44:47], v[22:23], off offset:1024
	v_addc_co_u32_e32 v57, vcc, 0, v29, vcc
	v_add_co_u32_e32 v28, vcc, s12, v28
	global_load_dwordx4 v[48:51], v[56:57], off
	global_load_dwordx4 v[52:55], v[56:57], off offset:1024
	v_addc_co_u32_e32 v29, vcc, 0, v29, vcc
	global_load_dwordx4 v[56:59], v[28:29], off
	global_load_dwordx4 v[60:63], v[28:29], off offset:1024
	v_lshl_add_u64 v[18:19], v[18:19], 0, s[6:7]
	s_waitcnt vmcnt(12)
	v_add_f32_e32 v64, v30, v35
	s_waitcnt vmcnt(10)
	v_add_f32_e32 v30, v65, v66
	s_waitcnt vmcnt(7)
	v_lshlrev_b32_e32 v66, 16, v24
	v_and_b32_e32 v67, 0xffff0000, v24
	v_lshlrev_b32_e32 v68, 16, v25
	v_and_b32_e32 v69, 0xffff0000, v25
	v_lshlrev_b32_e32 v72, 16, v27
	v_and_b32_e32 v73, 0xffff0000, v27
	v_lshlrev_b32_e32 v70, 16, v26
	v_and_b32_e32 v71, 0xffff0000, v26
	s_waitcnt vmcnt(5)
	v_lshlrev_b32_e32 v80, 16, v42
	v_and_b32_e32 v81, 0xffff0000, v42
	v_lshlrev_b32_e32 v42, 16, v43
	v_and_b32_e32 v43, 0xffff0000, v43
	v_lshlrev_b32_e32 v78, 16, v40
	s_waitcnt vmcnt(3)
	v_lshlrev_b32_e32 v88, 16, v50
	v_and_b32_e32 v89, 0xffff0000, v50
	v_lshlrev_b32_e32 v50, 16, v51
	v_and_b32_e32 v51, 0xffff0000, v51
	v_and_b32_e32 v79, 0xffff0000, v40
	v_lshlrev_b32_e32 v40, 16, v41
	v_and_b32_e32 v41, 0xffff0000, v41
	v_lshlrev_b32_e32 v86, 16, v48
	v_and_b32_e32 v87, 0xffff0000, v48
	v_lshlrev_b32_e32 v48, 16, v49
	v_and_b32_e32 v49, 0xffff0000, v49
	s_waitcnt vmcnt(1)
	v_lshlrev_b32_e32 v24, 16, v56
	v_and_b32_e32 v25, 0xffff0000, v56
	v_lshlrev_b32_e32 v28, 16, v57
	v_and_b32_e32 v29, 0xffff0000, v57
	v_lshlrev_b32_e32 v56, 16, v58
	v_and_b32_e32 v57, 0xffff0000, v58
	v_lshlrev_b32_e32 v58, 16, v59
	v_and_b32_e32 v59, 0xffff0000, v59
	v_pk_add_f32 v[42:43], v[42:43], v[50:51]
	v_lshlrev_b32_e32 v82, 16, v44
	v_and_b32_e32 v83, 0xffff0000, v44
	v_lshlrev_b32_e32 v44, 16, v45
	v_and_b32_e32 v45, 0xffff0000, v45
	v_lshlrev_b32_e32 v84, 16, v46
	v_and_b32_e32 v85, 0xffff0000, v46
	v_lshlrev_b32_e32 v46, 16, v47
	v_and_b32_e32 v47, 0xffff0000, v47
	v_lshlrev_b32_e32 v90, 16, v52
	v_and_b32_e32 v91, 0xffff0000, v52
	v_lshlrev_b32_e32 v52, 16, v53
	v_and_b32_e32 v53, 0xffff0000, v53
	v_lshlrev_b32_e32 v92, 16, v54
	v_and_b32_e32 v93, 0xffff0000, v54
	v_lshlrev_b32_e32 v54, 16, v55
	v_and_b32_e32 v55, 0xffff0000, v55
	v_pk_add_f32 v[50:51], v[80:81], v[88:89]
	v_pk_add_f32 v[40:41], v[40:41], v[48:49]
	v_pk_add_f32 v[48:49], v[78:79], v[86:87]
	v_pk_fma_f32 v[42:43], v[64:65], v[72:73], v[42:43] op_sel_hi:[0,1,1]
	v_mul_f32_e32 v65, 0xbfb8aa3b, v59
	v_lshlrev_b32_e32 v74, 16, v36
	v_and_b32_e32 v75, 0xffff0000, v36
	v_lshlrev_b32_e32 v36, 16, v37
	v_and_b32_e32 v37, 0xffff0000, v37
	v_lshlrev_b32_e32 v76, 16, v38
	v_and_b32_e32 v77, 0xffff0000, v38
	v_lshlrev_b32_e32 v38, 16, v39
	v_and_b32_e32 v39, 0xffff0000, v39
	s_waitcnt vmcnt(0)
	v_lshlrev_b32_e32 v26, 16, v60
	v_and_b32_e32 v27, 0xffff0000, v60
	v_lshlrev_b32_e32 v94, 16, v62
	v_and_b32_e32 v95, 0xffff0000, v62
	v_lshlrev_b32_e32 v62, 16, v63
	v_and_b32_e32 v63, 0xffff0000, v63
	v_pk_add_f32 v[46:47], v[46:47], v[54:55]
	v_pk_add_f32 v[54:55], v[84:85], v[92:93]
	v_pk_add_f32 v[44:45], v[44:45], v[52:53]
	v_pk_add_f32 v[52:53], v[82:83], v[90:91]
	v_pk_fma_f32 v[50:51], v[64:65], v[70:71], v[50:51] op_sel_hi:[0,1,1]
	v_pk_fma_f32 v[40:41], v[64:65], v[68:69], v[40:41] op_sel_hi:[0,1,1]
	v_mul_f32_e32 v69, 0xbfb8aa3b, v24
	v_pk_fma_f32 v[48:49], v[64:65], v[66:67], v[48:49] op_sel_hi:[0,1,1]
	v_mul_f32_e32 v64, 0xbfb8aa3b, v25
	v_lshlrev_b32_e32 v60, 16, v61
	v_and_b32_e32 v61, 0xffff0000, v61
	v_mul_f32_e32 v72, 0xbfb8aa3b, v56
	v_mul_f32_e32 v70, 0xbfb8aa3b, v57
	v_mul_f32_e32 v71, 0xbfb8aa3b, v28
	v_mul_f32_e32 v66, 0xbfb8aa3b, v62
	v_pk_fma_f32 v[38:39], v[30:31], v[38:39], v[46:47] op_sel_hi:[0,1,1]
	v_mul_f32_e32 v67, 0xbfb8aa3b, v63
	v_mul_f32_e32 v73, 0xbfb8aa3b, v94
	v_pk_fma_f32 v[46:47], v[30:31], v[76:77], v[54:55] op_sel_hi:[0,1,1]
	v_pk_fma_f32 v[36:37], v[30:31], v[36:37], v[44:45] op_sel_hi:[0,1,1]
	v_mul_f32_e32 v77, 0xbfb8aa3b, v26
	v_pk_fma_f32 v[44:45], v[30:31], v[74:75], v[52:53] op_sel_hi:[0,1,1]
	v_mul_f32_e32 v30, 0xbfb8aa3b, v27
	v_exp_f32_e32 v69, v69
	v_exp_f32_e32 v64, v64
	v_mul_f32_e32 v35, 0xbfb8aa3b, v58
	v_mul_f32_e32 v68, 0xbfb8aa3b, v29
	v_mul_f32_e32 v54, 0xbfb8aa3b, v95
	v_mul_f32_e32 v55, 0xbfb8aa3b, v60
	v_mul_f32_e32 v76, 0xbfb8aa3b, v61
	v_exp_f32_e32 v52, v65
	v_exp_f32_e32 v53, v72
	v_exp_f32_e32 v65, v70
	v_exp_f32_e32 v70, v71
	v_exp_f32_e32 v66, v66
	v_exp_f32_e32 v67, v67
	v_exp_f32_e32 v71, v73
	v_exp_f32_e32 v73, v77
	v_exp_f32_e32 v30, v30
	v_exp_f32_e32 v35, v35
	v_exp_f32_e32 v68, v68
	v_exp_f32_e32 v54, v54
	v_exp_f32_e32 v55, v55
	v_exp_f32_e32 v72, v76
	v_add_f32_e32 v69, 1.0, v69
	v_add_f32_e32 v76, 1.0, v64
	v_add_f32_e32 v74, 1.0, v52
	v_add_f32_e32 v75, 1.0, v53
	v_add_f32_e32 v77, 1.0, v66
	v_add_f32_e32 v78, 1.0, v67
	v_add_f32_e32 v82, 1.0, v73
	v_add_f32_e32 v30, 1.0, v30
	v_rcp_f32_e32 v66, v69
	v_rcp_f32_e32 v67, v76
	v_add_f32_e32 v35, 1.0, v35
	v_add_f32_e32 v65, 1.0, v65
	v_add_f32_e32 v70, 1.0, v70
	v_add_f32_e32 v68, 1.0, v68
	v_add_f32_e32 v79, 1.0, v54
	v_add_f32_e32 v80, 1.0, v55
	v_add_f32_e32 v81, 1.0, v72
	v_rcp_f32_e32 v53, v74
	v_rcp_f32_e32 v54, v75
	v_rcp_f32_e32 v74, v82
	v_rcp_f32_e32 v75, v30
	v_rcp_f32_e32 v52, v35
	v_rcp_f32_e32 v55, v65
	v_rcp_f32_e32 v64, v70
	v_rcp_f32_e32 v65, v68
	v_rcp_f32_e32 v72, v80
	v_rcp_f32_e32 v73, v81
	v_add_f32_e32 v71, 1.0, v71
	v_pk_mul_f32 v[24:25], v[66:67], v[24:25]
	v_rcp_f32_e32 v70, v71
	v_rcp_f32_e32 v71, v79
	v_pk_mul_f32 v[26:27], v[74:75], v[26:27]
	v_pk_mul_f32 v[24:25], v[24:25], v[48:49]
	v_rcp_f32_e32 v68, v77
	v_rcp_f32_e32 v69, v78
	v_pk_mul_f32 v[52:53], v[52:53], v[58:59]
	v_pk_mul_f32 v[28:29], v[64:65], v[28:29]
	v_pk_mul_f32 v[60:61], v[72:73], v[60:61]
	v_pk_mul_f32 v[26:27], v[26:27], v[44:45]
	v_mul_f32_e32 v30, v25, v25
	v_pk_mul_f32 v[42:43], v[52:53], v[42:43]
	v_pk_mul_f32 v[28:29], v[28:29], v[40:41]
	v_pk_mul_f32 v[36:37], v[60:61], v[36:37]
	v_mul_f32_e32 v52, v27, v27
	v_pk_fma_f32 v[60:61], v[24:25], v[24:25], v[30:31] op_sel_hi:[1,1,0]
	v_pk_mul_f32 v[54:55], v[54:55], v[56:57]
	v_mul_f32_e32 v44, v29, v29
	v_pk_fma_f32 v[52:53], v[26:27], v[26:27], v[52:53] op_sel_hi:[1,1,0]
	v_pk_fma_f32 v[60:61], v[28:29], v[28:29], v[60:61]
	v_pk_mul_f32 v[58:59], v[70:71], v[94:95]
	v_pk_mul_f32 v[50:51], v[54:55], v[50:51]
	v_mul_f32_e32 v54, v37, v37
	v_pk_fma_f32 v[52:53], v[36:37], v[36:37], v[52:53]
	v_pk_add_f32 v[44:45], v[44:45], v[60:61] op_sel_hi:[0,1]
	v_pk_mul_f32 v[56:57], v[68:69], v[62:63]
	v_pk_mul_f32 v[40:41], v[58:59], v[46:47]
	v_mul_f32_e32 v46, v51, v51
	v_pk_add_f32 v[52:53], v[54:55], v[52:53] op_sel_hi:[0,1]
	v_pk_fma_f32 v[44:45], v[50:51], v[50:51], v[44:45]
	v_pk_mul_f32 v[38:39], v[56:57], v[38:39]
	v_mul_f32_e32 v56, v41, v41
	v_pk_fma_f32 v[52:53], v[40:41], v[40:41], v[52:53]
	v_pk_add_f32 v[44:45], v[46:47], v[44:45] op_sel_hi:[0,1]
	v_mul_f32_e32 v48, v43, v43
	v_pk_add_f32 v[46:47], v[56:57], v[52:53] op_sel_hi:[0,1]
	v_pk_fma_f32 v[44:45], v[42:43], v[42:43], v[44:45]
	v_mul_f32_e32 v58, v39, v39
	v_pk_fma_f32 v[46:47], v[38:39], v[38:39], v[46:47]
	v_pk_add_f32 v[44:45], v[48:49], v[44:45] op_sel_hi:[0,1]
	v_pk_add_f32 v[46:47], v[58:59], v[46:47] op_sel_hi:[0,1]
	v_mov_b32_e32 v49, v44
	v_mov_b32_e32 v48, v46
	s_nop 0
	v_permlane16_swap_b32_e32 v44, v49
	v_permlane16_swap_b32_e32 v46, v48
	v_mov_b32_e32 v47, v44
	v_pk_add_f32 v[44:45], v[46:47], v[48:49]
	s_nop 1
	v_mov_b32_dpp v47, v45 row_ror:8 row_mask:0xf bank_mask:0xf
	s_nop 1
	v_mov_b32_dpp v46, v44 row_ror:8 row_mask:0xf bank_mask:0xf
	s_waitcnt lgkmcnt(0)
	v_pk_add_f32 v[44:45], v[44:45], v[46:47]
	s_nop 1
	v_mov_b32_dpp v47, v45 row_ror:4 row_mask:0xf bank_mask:0xf
	s_nop 1
	v_mov_b32_dpp v46, v44 row_ror:4 row_mask:0xf bank_mask:0xf
	s_waitcnt lgkmcnt(0)
	v_pk_add_f32 v[44:45], v[44:45], v[46:47]
	s_nop 1
	v_mov_b32_dpp v47, v45 row_ror:2 row_mask:0xf bank_mask:0xf
	s_nop 1
	v_mov_b32_dpp v46, v44 row_ror:2 row_mask:0xf bank_mask:0xf
	s_waitcnt lgkmcnt(0)
	v_pk_add_f32 v[44:45], v[44:45], v[46:47]
	s_nop 1
	v_mov_b32_dpp v47, v45 row_ror:1 row_mask:0xf bank_mask:0xf
	s_nop 1
	v_mov_b32_dpp v46, v44 row_ror:1 row_mask:0xf bank_mask:0xf
	s_waitcnt lgkmcnt(0)
	v_pk_add_f32 v[44:45], v[44:45], v[46:47]
	s_nop 0
	v_pk_fma_f32 v[44:45], v[44:45], s[10:11], v[20:21] op_sel_hi:[1,0,0]
	v_add_u32_e32 v21, s66, v21
	v_mul_f32_e32 v30, 0x4b800000, v45
	v_cmp_gt_f32_e32 vcc, s13, v45
	s_nop 1
	v_cndmask_b32_e32 v30, v45, v30, vcc
	v_rsq_f32_e32 v30, v30
	s_nop 0
	v_mul_f32_e32 v35, 0x45800000, v30
	v_cndmask_b32_e32 v30, v30, v35, vcc
	v_pk_mul_f32 v[24:25], v[24:25], v[30:31] op_sel_hi:[1,0]
	v_pk_mul_f32 v[28:29], v[28:29], v[30:31] op_sel_hi:[1,0]
	v_pk_mul_f32 v[46:47], v[50:51], v[30:31] op_sel_hi:[1,0]
	v_pk_mul_f32 v[42:43], v[42:43], v[30:31] op_sel_hi:[1,0]
	v_pk_mul_f32 v[4:5], v[24:25], v[4:5]
	v_pk_mul_f32 v[6:7], v[28:29], v[6:7]
	v_pk_mul_f32 v[24:25], v[46:47], v[0:1]
	v_pk_mul_f32 v[28:29], v[42:43], v[2:3]
	v_cvt_pk_bf16_f32 v0, v4, v5
	v_cvt_pk_bf16_f32 v1, v6, v7
	v_cvt_pk_bf16_f32 v2, v24, v25
	v_cvt_pk_bf16_f32 v3, v28, v29
	global_store_dwordx4 v[22:23], v[0:3], off
	global_load_dwordx4 v[0:3], v[14:15], off offset:2048
	s_nop 0
	global_load_dwordx4 v[4:7], v[14:15], off offset:2064
	v_cmp_lt_i32_e32 vcc, s14, v21
	s_or_b64 s[8:9], vcc, s[8:9]
	v_mul_f32_e32 v24, 0x4b800000, v44
	v_cmp_gt_f32_e32 vcc, s13, v44
	s_nop 1
	v_cndmask_b32_e32 v24, v44, v24, vcc
	v_rsq_f32_e32 v24, v24
	s_nop 0
	v_mul_f32_e32 v25, 0x45800000, v24
	v_cndmask_b32_e32 v24, v24, v25, vcc
	v_pk_mul_f32 v[26:27], v[26:27], v[24:25] op_sel_hi:[1,0]
	v_pk_mul_f32 v[28:29], v[36:37], v[24:25] op_sel_hi:[1,0]
	v_pk_mul_f32 v[36:37], v[40:41], v[24:25] op_sel_hi:[1,0]
	v_pk_mul_f32 v[24:25], v[38:39], v[24:25] op_sel_hi:[1,0]
	s_waitcnt vmcnt(1)
	v_pk_mul_f32 v[0:1], v[26:27], v[0:1]
	v_pk_mul_f32 v[2:3], v[28:29], v[2:3]
	s_waitcnt vmcnt(0)
	v_pk_mul_f32 v[4:5], v[36:37], v[4:5]
	v_pk_mul_f32 v[6:7], v[24:25], v[6:7]
	v_cvt_pk_bf16_f32 v0, v0, v1
	v_cvt_pk_bf16_f32 v1, v2, v3
	v_cvt_pk_bf16_f32 v2, v4, v5
	v_cvt_pk_bf16_f32 v3, v6, v7
	global_store_dwordx4 v[22:23], v[0:3], off offset:1024
	s_andn2_b64 exec, exec, s[8:9]
	s_cbranch_execnz .LBB0_1961

.LBB0_2265:
	s_or_b64 exec, exec, s[4:5]
	v_ashrrev_i32_e32 v136, 31, v130
	v_lshrrev_b32_e32 v136, 20, v136
	v_add_u32_e32 v130, v130, v136
	v_ashrrev_i32_e32 v130, 12, v130
	v_mul_hi_i32_i24_e32 v137, 0x1800, v130
	v_mul_i32_i24_e32 v136, 0x1800, v130
	v_lshlrev_b64 v[136:137], 2, v[136:137]
	v_lshl_add_u64 v[152:153], v[102:103], 0, v[136:137]
	global_load_dwordx4 v[144:147], v[152:153], off
	global_load_dwordx4 v[148:151], v[152:153], off offset:16
	s_waitcnt vmcnt(14)
	v_mov_b32_e32 v130, v142
	s_nop 1
	v_permlane32_swap_b32_e32 v142, v130
	v_add_f32_e32 v130, v142, v130
	v_mov_b32_e32 v142, v130
	s_nop 1
	v_permlane16_swap_b32_e32 v130, v142
	v_add_f32_e32 v130, v130, v142
	s_nop 1
	v_mov_b32_dpp v155, v130 row_ror:8 row_mask:0xf bank_mask:0xf
	v_lshlrev_b32_e32 v158, 16, v88
	v_lshlrev_b32_e32 v160, 16, v90
	v_lshlrev_b32_e32 v154, 16, v92
	v_lshlrev_b32_e32 v156, 16, v94
	s_waitcnt lgkmcnt(0)
	v_add_f32_e32 v130, v130, v155
	s_nop 1
	v_mov_b32_dpp v157, v130 row_ror:4 row_mask:0xf bank_mask:0xf
	v_and_b32_e32 v155, 0xffff0000, v92
	v_lshlrev_b32_e32 v92, 16, v93
	v_and_b32_e32 v93, 0xffff0000, v93
	v_lshl_add_u64 v[142:143], v[128:129], 0, s[58:59]
	s_waitcnt lgkmcnt(0)
	v_add_f32_e32 v130, v130, v157
	s_nop 1
	v_mov_b32_dpp v159, v130 row_ror:2 row_mask:0xf bank_mask:0xf
	v_and_b32_e32 v157, 0xffff0000, v94
	v_lshlrev_b32_e32 v94, 16, v95
	v_and_b32_e32 v95, 0xffff0000, v95
	v_lshl_add_u64 v[124:125], v[108:109], 0, v[124:125]
	s_waitcnt lgkmcnt(0)
	v_add_f32_e32 v130, v130, v159
	s_nop 1
	v_mov_b32_dpp v161, v130 row_ror:1 row_mask:0xf bank_mask:0xf
	v_and_b32_e32 v159, 0xffff0000, v88
	v_lshlrev_b32_e32 v88, 16, v89
	v_and_b32_e32 v89, 0xffff0000, v89
	v_lshl_add_u64 v[110:111], v[110:111], 0, s[38:39]
	s_waitcnt lgkmcnt(0)
	v_add_f32_e32 v130, v130, v161
	v_fmamk_f32 v130, v130, 0x3a800000, v188
	v_mul_f32_e32 v161, 0x4b800000, v130
	v_cmp_gt_f32_e32 vcc, s67, v130
	v_lshl_add_u64 v[112:113], v[112:113], 0, s[40:41]
	s_nop 0
	v_cndmask_b32_e32 v130, v130, v161, vcc
	v_rsq_f32_e32 v130, v130
	v_and_b32_e32 v161, 0xffff0000, v90
	v_lshlrev_b32_e32 v90, 16, v91
	v_and_b32_e32 v91, 0xffff0000, v91
	v_mul_f32_e32 v162, 0x45800000, v130
	v_cndmask_b32_e32 v130, v130, v162, vcc
	s_waitcnt vmcnt(6)
	v_pk_mul_f32 v[158:159], v[130:131], v[158:159] op_sel_hi:[0,1]
	v_pk_mul_f32 v[88:89], v[130:131], v[88:89] op_sel_hi:[0,1]
	v_pk_mul_f32 v[160:161], v[130:131], v[160:161] op_sel_hi:[0,1]
	v_pk_mul_f32 v[90:91], v[130:131], v[90:91] op_sel_hi:[0,1]
	v_pk_mul_f32 v[158:159], v[4:5], v[158:159]
	v_pk_mul_f32 v[88:89], v[6:7], v[88:89]
	v_pk_mul_f32 v[160:161], v[0:1], v[160:161]
	v_pk_mul_f32 v[90:91], v[2:3], v[90:91]
	s_waitcnt vmcnt(1)
	v_pk_fma_f32 v[144:145], v[144:145], v[158:159], v[154:155]
	v_pk_fma_f32 v[92:93], v[146:147], v[88:89], v[92:93]
	s_waitcnt vmcnt(0)
	v_pk_fma_f32 v[146:147], v[148:149], v[160:161], v[156:157]
	v_pk_fma_f32 v[94:95], v[150:151], v[90:91], v[94:95]
	v_cvt_pk_bf16_f32 v88, v144, v145
	v_cvt_pk_bf16_f32 v89, v92, v93
	v_cvt_pk_bf16_f32 v90, v146, v147
	v_cvt_pk_bf16_f32 v91, v94, v95
	global_store_dwordx4 v[142:143], v[88:91], off
	global_load_dwordx4 v[92:95], v[152:153], off offset:2048
	s_nop 0
	global_load_dwordx4 v[142:145], v[152:153], off offset:2064
	v_and_b32_e32 v163, 0xffff0000, v88
	v_lshlrev_b32_e32 v162, 16, v88
	v_mul_f32_e32 v88, v163, v163
	v_lshlrev_b32_e32 v164, 16, v89
	v_and_b32_e32 v165, 0xffff0000, v89
	v_pk_fma_f32 v[88:89], v[162:163], v[162:163], v[88:89] op_sel_hi:[1,1,0]
	v_lshlrev_b32_e32 v166, 16, v90
	v_and_b32_e32 v167, 0xffff0000, v90
	v_mul_f32_e32 v90, v165, v165
	v_pk_fma_f32 v[88:89], v[164:165], v[164:165], v[88:89]
	v_lshlrev_b32_e32 v152, 16, v80
	v_and_b32_e32 v153, 0xffff0000, v80
	v_lshlrev_b32_e32 v80, 16, v81
	v_and_b32_e32 v81, 0xffff0000, v81
	v_lshlrev_b32_e32 v154, 16, v82
	v_and_b32_e32 v155, 0xffff0000, v82
	v_lshlrev_b32_e32 v82, 16, v83
	v_and_b32_e32 v83, 0xffff0000, v83
	v_pk_add_f32 v[88:89], v[90:91], v[88:89] op_sel_hi:[0,1]
	v_pk_mul_f32 v[152:153], v[130:131], v[152:153] op_sel_hi:[0,1]
	v_pk_mul_f32 v[80:81], v[130:131], v[80:81] op_sel_hi:[0,1]
	v_pk_mul_f32 v[154:155], v[130:131], v[154:155] op_sel_hi:[0,1]
	v_pk_mul_f32 v[82:83], v[130:131], v[82:83] op_sel_hi:[0,1]
	v_mul_f32_e32 v130, v167, v167
	v_pk_fma_f32 v[88:89], v[166:167], v[166:167], v[88:89]
	v_lshlrev_b32_e32 v148, 16, v84
	v_and_b32_e32 v149, 0xffff0000, v84
	v_lshlrev_b32_e32 v84, 16, v85
	v_and_b32_e32 v85, 0xffff0000, v85
	v_lshlrev_b32_e32 v150, 16, v86
	v_and_b32_e32 v151, 0xffff0000, v86
	v_lshlrev_b32_e32 v86, 16, v87
	v_and_b32_e32 v87, 0xffff0000, v87
	v_pk_mul_f32 v[152:153], v[20:21], v[152:153]
	v_pk_mul_f32 v[80:81], v[22:23], v[80:81]
	v_pk_mul_f32 v[154:155], v[16:17], v[154:155]
	v_pk_mul_f32 v[82:83], v[18:19], v[82:83]
	v_lshlrev_b32_e32 v168, 16, v91
	v_and_b32_e32 v169, 0xffff0000, v91
	v_pk_add_f32 v[88:89], v[130:131], v[88:89] op_sel_hi:[0,1]
	v_pk_fma_f32 v[170:171], v[168:169], v[168:169], v[88:89]
	v_lshl_add_u64 v[146:147], v[128:129], 0, s[60:61]
	v_lshl_add_u64 v[160:161], v[104:105], 0, v[136:137]
	v_lshl_add_u64 v[136:137], v[106:107], 0, v[136:137]
	v_mov_b32_e32 v156, v134
	s_nop 1
	v_permlane32_swap_b32_e32 v134, v156
	v_add_f32_e32 v156, v134, v156
	v_mul_f32_e32 v134, v169, v169
	v_mov_b32_e32 v158, v156
	s_nop 1
	v_permlane16_swap_b32_e32 v156, v158
	v_add_co_u32_e64 v128, s[4:5], s69, v128
	s_waitcnt vmcnt(1)
	v_pk_fma_f32 v[88:89], v[152:153], v[92:93], v[148:149]
	v_pk_fma_f32 v[84:85], v[80:81], v[94:95], v[84:85]
	s_waitcnt vmcnt(0)
	v_pk_fma_f32 v[90:91], v[154:155], v[142:143], v[150:151]
	v_pk_fma_f32 v[86:87], v[82:83], v[144:145], v[86:87]
	v_cvt_pk_bf16_f32 v80, v88, v89
	v_cvt_pk_bf16_f32 v81, v84, v85
	v_cvt_pk_bf16_f32 v82, v90, v91
	v_cvt_pk_bf16_f32 v83, v86, v87
	global_store_dwordx4 v[146:147], v[80:83], off
	global_load_dwordx4 v[84:87], v[136:137], off offset:16
	global_load_dwordx4 v[88:91], v[136:137], off
	global_load_dwordx4 v[92:95], v[160:161], off offset:16
	global_load_dwordx4 v[142:145], v[160:161], off
	v_pk_add_f32 v[146:147], v[134:135], v[170:171] op_sel_hi:[0,1]
	v_lshlrev_b32_e32 v148, 16, v80
	v_and_b32_e32 v149, 0xffff0000, v80
	v_lshlrev_b32_e32 v150, 16, v81
	v_and_b32_e32 v151, 0xffff0000, v81
	v_lshlrev_b32_e32 v152, 16, v82
	v_and_b32_e32 v153, 0xffff0000, v82
	v_pk_fma_f32 v[80:81], v[148:149], v[148:149], v[146:147]
	v_mul_f32_e32 v82, v149, v149
	v_pk_add_f32 v[80:81], v[82:83], v[80:81] op_sel_hi:[0,1]
	v_mul_f32_e32 v130, v151, v151
	v_pk_fma_f32 v[80:81], v[150:151], v[150:151], v[80:81]
	v_mul_f32_e32 v134, v153, v153
	v_pk_add_f32 v[80:81], v[130:131], v[80:81] op_sel_hi:[0,1]
	v_pk_fma_f32 v[80:81], v[152:153], v[152:153], v[80:81]
	v_lshlrev_b32_e32 v154, 16, v83
	v_and_b32_e32 v155, 0xffff0000, v83
	v_pk_add_f32 v[80:81], v[134:135], v[80:81] op_sel_hi:[0,1]
	v_mul_f32_e32 v146, v155, v155
	v_pk_fma_f32 v[80:81], v[154:155], v[154:155], v[80:81]
	v_addc_co_u32_e64 v129, s[4:5], 0, v129, s[4:5]
	v_pk_add_f32 v[80:81], v[146:147], v[80:81] op_sel_hi:[0,1]
	v_mov_b32_e32 v81, v80
	s_nop 1
	v_permlane32_swap_b32_e32 v80, v81
	v_add_f32_e32 v157, v80, v81
	v_mov_b32_e32 v159, v157
	s_nop 1
	v_permlane16_swap_b32_e32 v157, v159
	v_pk_add_f32 v[80:81], v[156:157], v[158:159]
	s_nop 1
	v_mov_b32_dpp v83, v81 row_ror:8 row_mask:0xf bank_mask:0xf
	s_nop 1
	v_mov_b32_dpp v82, v80 row_ror:8 row_mask:0xf bank_mask:0xf
	s_waitcnt lgkmcnt(0)
	v_pk_add_f32 v[80:81], v[80:81], v[82:83]
	s_nop 1
	v_mov_b32_dpp v83, v81 row_ror:4 row_mask:0xf bank_mask:0xf
	s_nop 1
	v_mov_b32_dpp v82, v80 row_ror:4 row_mask:0xf bank_mask:0xf
	s_waitcnt lgkmcnt(0)
	v_pk_add_f32 v[80:81], v[80:81], v[82:83]
	s_nop 1
	v_mov_b32_dpp v83, v81 row_ror:2 row_mask:0xf bank_mask:0xf
	s_nop 1
	v_mov_b32_dpp v82, v80 row_ror:2 row_mask:0xf bank_mask:0xf
	s_waitcnt lgkmcnt(0)
	v_pk_add_f32 v[82:83], v[80:81], v[82:83]
	s_nop 1
	v_mov_b32_dpp v147, v83 row_ror:1 row_mask:0xf bank_mask:0xf
	s_nop 1
	v_mov_b32_dpp v146, v82 row_ror:1 row_mask:0xf bank_mask:0xf
	v_mov_b64_e32 v[80:81], s[68:69]
	s_waitcnt lgkmcnt(0)
	v_pk_add_f32 v[82:83], v[82:83], v[146:147]
	s_nop 0
	v_pk_fma_f32 v[146:147], v[82:83], s[62:63], v[80:81] op_sel_hi:[1,0,0]
	s_waitcnt vmcnt(3)
	v_pk_add_f32 v[84:85], v[84:85], 1.0 op_sel_hi:[1,0]
	v_mul_f32_e32 v82, 0x4b800000, v147
	v_cmp_gt_f32_e32 vcc, s67, v147
	s_waitcnt vmcnt(2)
	v_pk_add_f32 v[90:91], v[90:91], 1.0 op_sel_hi:[1,0]
	v_pk_add_f32 v[88:89], v[88:89], 1.0 op_sel_hi:[1,0]
	v_cndmask_b32_e32 v82, v147, v82, vcc
	v_rsq_f32_e32 v82, v82
	v_pk_add_f32 v[86:87], v[86:87], 1.0 op_sel_hi:[1,0]
	v_mul_f32_e32 v83, 0x45800000, v82
	v_cndmask_b32_e32 v130, v82, v83, vcc
	v_pk_mul_f32 v[82:83], v[130:131], v[162:163] op_sel_hi:[0,1]
	v_pk_mul_f32 v[156:157], v[130:131], v[164:165] op_sel_hi:[0,1]
	v_pk_mul_f32 v[158:159], v[130:131], v[166:167] op_sel_hi:[0,1]
	v_pk_mul_f32 v[162:163], v[130:131], v[168:169] op_sel_hi:[0,1]
	v_pk_mul_f32 v[82:83], v[12:13], v[82:83]
	v_pk_mul_f32 v[156:157], v[14:15], v[156:157]
	v_pk_mul_f32 v[158:159], v[8:9], v[158:159]
	v_pk_mul_f32 v[162:163], v[10:11], v[162:163]
	s_waitcnt vmcnt(0)
	v_pk_fma_f32 v[82:83], v[88:89], v[82:83], v[142:143]
	v_pk_fma_f32 v[88:89], v[156:157], v[90:91], v[144:145]
	v_pk_fma_f32 v[84:85], v[158:159], v[84:85], v[92:93]
	v_pk_fma_f32 v[86:87], v[162:163], v[86:87], v[94:95]
	v_cvt_pk_bf16_f32 v82, v82, v83
	v_cvt_pk_bf16_f32 v83, v88, v89
	v_cvt_pk_bf16_f32 v84, v84, v85
	v_cvt_pk_bf16_f32 v85, v86, v87
	global_store_dwordx4 v[128:129], v[82:85], off
	global_load_dwordx4 v[84:87], v[136:137], off offset:2048
	s_nop 0
	global_load_dwordx4 v[88:91], v[136:137], off offset:2064
	global_load_dwordx4 v[92:95], v[160:161], off offset:2048
	global_load_dwordx4 v[142:145], v[160:161], off offset:2064
	v_ashrrev_i32_e32 v82, 31, v122
	v_lshrrev_b32_e32 v82, 20, v82
	v_add_u32_e32 v82, v122, v82
	v_pk_mul_f32 v[148:149], v[130:131], v[148:149] op_sel_hi:[0,1]
	v_pk_mul_f32 v[150:151], v[130:131], v[150:151] op_sel_hi:[0,1]
	v_pk_mul_f32 v[152:153], v[130:131], v[152:153] op_sel_hi:[0,1]
	v_pk_mul_f32 v[154:155], v[130:131], v[154:155] op_sel_hi:[0,1]
	v_ashrrev_i32_e32 v82, 12, v82
	v_pk_mul_f32 v[148:149], v[28:29], v[148:149]
	v_pk_mul_f32 v[150:151], v[30:31], v[150:151]
	v_pk_mul_f32 v[152:153], v[24:25], v[152:153]
	v_pk_mul_f32 v[154:155], v[26:27], v[154:155]
	v_mul_hi_i32_i24_e32 v83, 0x1800, v82
	v_mul_i32_i24_e32 v82, 0x1800, v82
	v_lshlrev_b64 v[82:83], 2, v[82:83]
	v_lshl_add_u64 v[136:137], v[102:103], 0, v[82:83]
	v_mul_f32_e32 v130, 0x4b800000, v146
	v_cmp_gt_f32_e32 vcc, s67, v146
	s_waitcnt vmcnt(3)
	v_pk_add_f32 v[84:85], v[84:85], 1.0 op_sel_hi:[1,0]
	v_pk_add_f32 v[86:87], v[86:87], 1.0 op_sel_hi:[1,0]
	s_waitcnt vmcnt(2)
	v_pk_add_f32 v[88:89], v[88:89], 1.0 op_sel_hi:[1,0]
	v_pk_add_f32 v[90:91], v[90:91], 1.0 op_sel_hi:[1,0]
	s_waitcnt vmcnt(1)
	v_pk_fma_f32 v[84:85], v[148:149], v[84:85], v[92:93]
	v_pk_fma_f32 v[86:87], v[150:151], v[86:87], v[94:95]
	s_waitcnt vmcnt(0)
	v_pk_fma_f32 v[88:89], v[152:153], v[88:89], v[142:143]
	v_pk_fma_f32 v[90:91], v[154:155], v[90:91], v[144:145]
	v_cvt_pk_bf16_f32 v84, v84, v85
	v_cvt_pk_bf16_f32 v85, v86, v87
	v_cvt_pk_bf16_f32 v86, v88, v89
	v_cvt_pk_bf16_f32 v87, v90, v91
	global_store_dwordx4 v[128:129], v[84:87], off offset:1024
	global_load_dwordx4 v[84:87], v[136:137], off
	s_nop 0
	global_load_dwordx4 v[88:91], v[136:137], off offset:16
	v_cndmask_b32_e32 v130, v146, v130, vcc
	v_rsq_f32_e32 v130, v130
	v_lshlrev_b32_e32 v128, 16, v72
	v_and_b32_e32 v129, 0xffff0000, v72
	v_lshlrev_b32_e32 v72, 16, v73
	v_mul_f32_e32 v134, 0x45800000, v130
	v_and_b32_e32 v73, 0xffff0000, v73
	v_lshlrev_b32_e32 v142, 16, v74
	v_and_b32_e32 v143, 0xffff0000, v74
	v_lshlrev_b32_e32 v74, 16, v75
	v_and_b32_e32 v75, 0xffff0000, v75
	v_cndmask_b32_e32 v130, v130, v134, vcc
	v_pk_mul_f32 v[128:129], v[130:131], v[128:129] op_sel_hi:[0,1]
	v_pk_mul_f32 v[72:73], v[130:131], v[72:73] op_sel_hi:[0,1]
	v_pk_mul_f32 v[142:143], v[130:131], v[142:143] op_sel_hi:[0,1]
	v_pk_mul_f32 v[74:75], v[130:131], v[74:75] op_sel_hi:[0,1]
	v_lshlrev_b32_e32 v92, 16, v76
	v_and_b32_e32 v93, 0xffff0000, v76
	v_lshlrev_b32_e32 v76, 16, v77
	v_and_b32_e32 v77, 0xffff0000, v77
	v_lshlrev_b32_e32 v94, 16, v78
	v_and_b32_e32 v95, 0xffff0000, v78
	v_lshlrev_b32_e32 v78, 16, v79
	v_and_b32_e32 v79, 0xffff0000, v79
	v_pk_mul_f32 v[128:129], v[4:5], v[128:129]
	v_pk_mul_f32 v[72:73], v[6:7], v[72:73]
	v_pk_mul_f32 v[142:143], v[0:1], v[142:143]
	v_pk_mul_f32 v[74:75], v[2:3], v[74:75]
	v_lshl_add_u64 v[144:145], v[106:107], 0, v[82:83]
	s_waitcnt vmcnt(1)
	v_pk_fma_f32 v[84:85], v[84:85], v[128:129], v[92:93]
	v_pk_fma_f32 v[76:77], v[86:87], v[72:73], v[76:77]
	s_waitcnt vmcnt(0)
	v_pk_fma_f32 v[86:87], v[88:89], v[142:143], v[94:95]
	v_pk_fma_f32 v[78:79], v[90:91], v[74:75], v[78:79]
	v_cvt_pk_bf16_f32 v72, v84, v85
	v_cvt_pk_bf16_f32 v73, v76, v77
	v_cvt_pk_bf16_f32 v74, v86, v87
	v_cvt_pk_bf16_f32 v75, v78, v79
	global_store_dwordx4 v[126:127], v[72:75], off
	global_load_dwordx4 v[76:79], v[136:137], off offset:2048
	global_load_dwordx4 v[84:87], v[136:137], off offset:2064
	v_mov_b32_e32 v128, v131
	v_lshlrev_b32_e32 v92, 16, v64
	v_and_b32_e32 v93, 0xffff0000, v64
	v_lshlrev_b32_e32 v94, 16, v66
	v_and_b32_e32 v95, 0xffff0000, v66
	v_permlane32_swap_b32_e32 v131, v128
	v_lshl_add_u64 v[142:143], v[104:105], 0, v[82:83]
	v_pk_mul_f32 v[82:83], v[130:131], v[92:93] op_sel_hi:[0,1]
	v_pk_mul_f32 v[92:93], v[130:131], v[94:95] op_sel_hi:[0,1]
	v_and_b32_e32 v95, 0xffff0000, v72
	v_lshlrev_b32_e32 v64, 16, v65
	v_and_b32_e32 v65, 0xffff0000, v65
	v_lshlrev_b32_e32 v66, 16, v67
	v_and_b32_e32 v67, 0xffff0000, v67
	v_lshlrev_b32_e32 v94, 16, v72
	v_mul_f32_e32 v72, v95, v95
	v_add_f32_e32 v128, v131, v128
	v_pk_mul_f32 v[64:65], v[130:131], v[64:65] op_sel_hi:[0,1]
	v_pk_mul_f32 v[66:67], v[130:131], v[66:67] op_sel_hi:[0,1]
	v_lshlrev_b32_e32 v130, 16, v73
	v_and_b32_e32 v131, 0xffff0000, v73
	v_pk_fma_f32 v[72:73], v[94:95], v[94:95], v[72:73] op_sel_hi:[1,1,0]
	v_lshlrev_b32_e32 v146, 16, v74
	v_and_b32_e32 v147, 0xffff0000, v74
	v_mul_f32_e32 v74, v131, v131
	v_pk_fma_f32 v[72:73], v[130:131], v[130:131], v[72:73]
	v_lshlrev_b32_e32 v88, 16, v68
	v_pk_add_f32 v[72:73], v[74:75], v[72:73] op_sel_hi:[0,1]
	v_and_b32_e32 v89, 0xffff0000, v68
	v_lshlrev_b32_e32 v68, 16, v69
	v_and_b32_e32 v69, 0xffff0000, v69
	v_lshlrev_b32_e32 v90, 16, v70
	v_and_b32_e32 v91, 0xffff0000, v70
	v_lshlrev_b32_e32 v70, 16, v71
	v_and_b32_e32 v71, 0xffff0000, v71
	v_pk_mul_f32 v[82:83], v[20:21], v[82:83]
	v_pk_mul_f32 v[64:65], v[22:23], v[64:65]
	v_pk_mul_f32 v[92:93], v[16:17], v[92:93]
	v_pk_mul_f32 v[66:67], v[18:19], v[66:67]
	v_mul_f32_e32 v134, v147, v147
	v_pk_fma_f32 v[72:73], v[146:147], v[146:147], v[72:73]
	v_lshlrev_b32_e32 v148, 16, v75
	v_and_b32_e32 v149, 0xffff0000, v75
	v_pk_add_f32 v[152:153], v[134:135], v[72:73] op_sel_hi:[0,1]
	v_mul_f32_e32 v150, v149, v149
	v_mov_b32_e32 v136, v128
	s_nop 1
	v_permlane16_swap_b32_e32 v128, v136
	s_waitcnt vmcnt(1)
	v_pk_fma_f32 v[72:73], v[82:83], v[76:77], v[88:89]
	v_pk_fma_f32 v[68:69], v[64:65], v[78:79], v[68:69]
	s_waitcnt vmcnt(0)
	v_pk_fma_f32 v[74:75], v[92:93], v[84:85], v[90:91]
	v_pk_fma_f32 v[70:71], v[66:67], v[86:87], v[70:71]
	v_cvt_pk_bf16_f32 v64, v72, v73
	v_cvt_pk_bf16_f32 v65, v68, v69
	v_cvt_pk_bf16_f32 v66, v74, v75
	v_cvt_pk_bf16_f32 v67, v70, v71
	global_store_dwordx4 v[126:127], v[64:67], off offset:1024
	global_load_dwordx4 v[68:71], v[144:145], off offset:16
	global_load_dwordx4 v[72:75], v[144:145], off
	global_load_dwordx4 v[76:79], v[142:143], off offset:16
	global_load_dwordx4 v[82:85], v[142:143], off
	v_pk_fma_f32 v[86:87], v[148:149], v[148:149], v[152:153]
	v_lshlrev_b32_e32 v88, 16, v64
	v_pk_add_f32 v[86:87], v[150:151], v[86:87] op_sel_hi:[0,1]
	v_and_b32_e32 v89, 0xffff0000, v64
	v_lshlrev_b32_e32 v90, 16, v65
	v_and_b32_e32 v91, 0xffff0000, v65
	v_lshlrev_b32_e32 v92, 16, v66
	v_and_b32_e32 v93, 0xffff0000, v66
	v_pk_fma_f32 v[64:65], v[88:89], v[88:89], v[86:87]
	v_mul_f32_e32 v66, v89, v89
	v_pk_add_f32 v[64:65], v[66:67], v[64:65] op_sel_hi:[0,1]
	v_mul_f32_e32 v86, v91, v91
	v_pk_fma_f32 v[64:65], v[90:91], v[90:91], v[64:65]
	v_mul_f32_e32 v134, v93, v93
	v_pk_add_f32 v[64:65], v[86:87], v[64:65] op_sel_hi:[0,1]
	v_pk_fma_f32 v[64:65], v[92:93], v[92:93], v[64:65]
	v_lshlrev_b32_e32 v126, 16, v67
	v_and_b32_e32 v127, 0xffff0000, v67
	v_pk_add_f32 v[64:65], v[134:135], v[64:65] op_sel_hi:[0,1]
	v_mul_f32_e32 v150, v127, v127
	v_pk_fma_f32 v[64:65], v[126:127], v[126:127], v[64:65]
	s_waitcnt vmcnt(3)
	v_pk_add_f32 v[68:69], v[68:69], 1.0 op_sel_hi:[1,0]
	v_pk_add_f32 v[64:65], v[150:151], v[64:65] op_sel_hi:[0,1]
	v_mov_b32_e32 v65, v64
	s_nop 1
	v_permlane32_swap_b32_e32 v64, v65
	v_add_f32_e32 v129, v64, v65
	v_mov_b32_e32 v137, v129
	s_nop 1
	v_permlane16_swap_b32_e32 v129, v137
	v_pk_add_f32 v[64:65], v[128:129], v[136:137]
	s_nop 1
	v_mov_b32_dpp v67, v65 row_ror:8 row_mask:0xf bank_mask:0xf
	s_nop 1
	v_mov_b32_dpp v66, v64 row_ror:8 row_mask:0xf bank_mask:0xf
	s_waitcnt vmcnt(2)
	v_pk_add_f32 v[74:75], v[74:75], 1.0 op_sel_hi:[1,0]
	v_pk_add_f32 v[72:73], v[72:73], 1.0 op_sel_hi:[1,0]
	v_pk_add_f32 v[70:71], v[70:71], 1.0 op_sel_hi:[1,0]
	s_waitcnt lgkmcnt(0)
	v_pk_add_f32 v[64:65], v[64:65], v[66:67]
	s_nop 1
	v_mov_b32_dpp v67, v65 row_ror:4 row_mask:0xf bank_mask:0xf
	s_nop 1
	v_mov_b32_dpp v66, v64 row_ror:4 row_mask:0xf bank_mask:0xf
	s_waitcnt lgkmcnt(0)
	v_pk_add_f32 v[64:65], v[64:65], v[66:67]
	s_nop 1
	v_mov_b32_dpp v67, v65 row_ror:2 row_mask:0xf bank_mask:0xf
	s_nop 1
	v_mov_b32_dpp v66, v64 row_ror:2 row_mask:0xf bank_mask:0xf
	s_waitcnt lgkmcnt(0)
	v_pk_add_f32 v[64:65], v[64:65], v[66:67]
	s_nop 1
	v_mov_b32_dpp v67, v65 row_ror:1 row_mask:0xf bank_mask:0xf
	s_nop 1
	v_mov_b32_dpp v66, v64 row_ror:1 row_mask:0xf bank_mask:0xf
	s_waitcnt lgkmcnt(0)
	v_pk_add_f32 v[64:65], v[64:65], v[66:67]
	s_nop 0
	v_pk_fma_f32 v[86:87], v[64:65], s[62:63], v[80:81] op_sel_hi:[1,0,0]
	s_nop 0
	v_mul_f32_e32 v64, 0x4b800000, v87
	v_cmp_gt_f32_e32 vcc, s67, v87
	s_nop 1
	v_cndmask_b32_e32 v64, v87, v64, vcc
	v_rsq_f32_e32 v64, v64
	s_nop 0
	v_mul_f32_e32 v65, 0x45800000, v64
	v_cndmask_b32_e32 v128, v64, v65, vcc
	v_pk_mul_f32 v[64:65], v[128:129], v[94:95] op_sel_hi:[0,1]
	v_pk_mul_f32 v[66:67], v[128:129], v[130:131] op_sel_hi:[0,1]
	v_pk_mul_f32 v[94:95], v[128:129], v[146:147] op_sel_hi:[0,1]
	v_pk_mul_f32 v[130:131], v[128:129], v[148:149] op_sel_hi:[0,1]
	v_pk_mul_f32 v[64:65], v[12:13], v[64:65]
	v_pk_mul_f32 v[66:67], v[14:15], v[66:67]
	v_pk_mul_f32 v[94:95], v[8:9], v[94:95]
	v_pk_mul_f32 v[130:131], v[10:11], v[130:131]
	s_waitcnt vmcnt(0)
	v_pk_fma_f32 v[64:65], v[72:73], v[64:65], v[82:83]
	v_pk_fma_f32 v[66:67], v[66:67], v[74:75], v[84:85]
	v_pk_fma_f32 v[68:69], v[94:95], v[68:69], v[76:77]
	v_pk_fma_f32 v[70:71], v[130:131], v[70:71], v[78:79]
	v_cvt_pk_bf16_f32 v64, v64, v65
	v_cvt_pk_bf16_f32 v65, v66, v67
	v_cvt_pk_bf16_f32 v66, v68, v69
	v_cvt_pk_bf16_f32 v67, v70, v71
	global_store_dwordx4 v[124:125], v[64:67], off
	global_load_dwordx4 v[66:69], v[144:145], off offset:2048
	s_nop 0
	global_load_dwordx4 v[70:73], v[144:145], off offset:2064
	global_load_dwordx4 v[74:77], v[142:143], off offset:2048
	global_load_dwordx4 v[82:85], v[142:143], off offset:2064
	v_add_u32_e32 v129, s66, v122
	v_ashrrev_i32_e32 v64, 31, v129
	v_lshrrev_b32_e32 v64, 20, v64
	v_add_u32_e32 v64, v129, v64
	v_pk_mul_f32 v[88:89], v[128:129], v[88:89] op_sel_hi:[0,1]
	v_pk_mul_f32 v[90:91], v[128:129], v[90:91] op_sel_hi:[0,1]
	v_pk_mul_f32 v[92:93], v[128:129], v[92:93] op_sel_hi:[0,1]
	v_pk_mul_f32 v[94:95], v[128:129], v[126:127] op_sel_hi:[0,1]
	v_ashrrev_i32_e32 v64, 12, v64
	v_pk_mul_f32 v[88:89], v[28:29], v[88:89]
	v_pk_mul_f32 v[90:91], v[30:31], v[90:91]
	v_pk_mul_f32 v[92:93], v[24:25], v[92:93]
	v_pk_mul_f32 v[94:95], v[26:27], v[94:95]
	v_mul_hi_i32_i24_e32 v65, 0x1800, v64
	v_mul_i32_i24_e32 v64, 0x1800, v64
	v_lshlrev_b64 v[64:65], 2, v[64:65]
	v_lshl_add_u64 v[78:79], v[102:103], 0, v[64:65]
	v_cmp_gt_f32_e32 vcc, s67, v86
	s_waitcnt vmcnt(3)
	v_pk_add_f32 v[66:67], v[66:67], 1.0 op_sel_hi:[1,0]
	v_pk_add_f32 v[68:69], v[68:69], 1.0 op_sel_hi:[1,0]
	s_waitcnt vmcnt(2)
	v_pk_add_f32 v[70:71], v[70:71], 1.0 op_sel_hi:[1,0]
	v_pk_add_f32 v[72:73], v[72:73], 1.0 op_sel_hi:[1,0]
	s_waitcnt vmcnt(1)
	v_pk_fma_f32 v[66:67], v[88:89], v[66:67], v[74:75]
	v_pk_fma_f32 v[68:69], v[90:91], v[68:69], v[76:77]
	s_waitcnt vmcnt(0)
	v_pk_fma_f32 v[70:71], v[92:93], v[70:71], v[82:83]
	v_pk_fma_f32 v[72:73], v[94:95], v[72:73], v[84:85]
	v_cvt_pk_bf16_f32 v66, v66, v67
	v_cvt_pk_bf16_f32 v67, v68, v69
	v_cvt_pk_bf16_f32 v68, v70, v71
	v_cvt_pk_bf16_f32 v69, v72, v73
	global_store_dwordx4 v[124:125], v[66:69], off offset:1024
	global_load_dwordx4 v[66:69], v[78:79], off
	s_nop 0
	global_load_dwordx4 v[70:73], v[78:79], off offset:16
	v_mul_f32_e32 v85, 0x4b800000, v86
	v_cndmask_b32_e32 v85, v86, v85, vcc
	v_rsq_f32_e32 v86, v85
	v_lshlrev_b32_e32 v82, 16, v56
	v_and_b32_e32 v83, 0xffff0000, v56
	v_lshlrev_b32_e32 v56, 16, v57
	v_mul_f32_e32 v87, 0x45800000, v86
	v_and_b32_e32 v57, 0xffff0000, v57
	v_lshlrev_b32_e32 v84, 16, v58
	v_and_b32_e32 v85, 0xffff0000, v58
	v_lshlrev_b32_e32 v58, 16, v59
	v_and_b32_e32 v59, 0xffff0000, v59
	v_cndmask_b32_e32 v86, v86, v87, vcc
	v_pk_mul_f32 v[82:83], v[86:87], v[82:83] op_sel_hi:[0,1]
	v_pk_mul_f32 v[56:57], v[86:87], v[56:57] op_sel_hi:[0,1]
	v_pk_mul_f32 v[84:85], v[86:87], v[84:85] op_sel_hi:[0,1]
	v_pk_mul_f32 v[58:59], v[86:87], v[58:59] op_sel_hi:[0,1]
	v_lshlrev_b32_e32 v74, 16, v60
	v_and_b32_e32 v75, 0xffff0000, v60
	v_lshlrev_b32_e32 v60, 16, v61
	v_and_b32_e32 v61, 0xffff0000, v61
	v_lshlrev_b32_e32 v76, 16, v62
	v_and_b32_e32 v77, 0xffff0000, v62
	v_lshlrev_b32_e32 v62, 16, v63
	v_and_b32_e32 v63, 0xffff0000, v63
	v_pk_mul_f32 v[82:83], v[4:5], v[82:83]
	v_pk_mul_f32 v[56:57], v[6:7], v[56:57]
	v_pk_mul_f32 v[84:85], v[0:1], v[84:85]
	v_pk_mul_f32 v[58:59], v[2:3], v[58:59]
	v_lshl_add_u64 v[88:89], v[106:107], 0, v[64:65]
	s_waitcnt vmcnt(1)
	v_pk_fma_f32 v[66:67], v[66:67], v[82:83], v[74:75]
	v_pk_fma_f32 v[60:61], v[68:69], v[56:57], v[60:61]
	s_waitcnt vmcnt(0)
	v_pk_fma_f32 v[68:69], v[70:71], v[84:85], v[76:77]
	v_pk_fma_f32 v[62:63], v[72:73], v[58:59], v[62:63]
	v_cvt_pk_bf16_f32 v56, v66, v67
	v_cvt_pk_bf16_f32 v57, v60, v61
	v_cvt_pk_bf16_f32 v58, v68, v69
	v_cvt_pk_bf16_f32 v59, v62, v63
	global_store_dwordx4 v[120:121], v[56:59], off
	global_load_dwordx4 v[60:63], v[78:79], off offset:2048
	global_load_dwordx4 v[66:69], v[78:79], off offset:2064
	v_lshlrev_b32_e32 v74, 16, v48
	v_and_b32_e32 v75, 0xffff0000, v48
	v_lshlrev_b32_e32 v76, 16, v50
	v_and_b32_e32 v77, 0xffff0000, v50
	v_lshl_add_u64 v[84:85], v[104:105], 0, v[64:65]
	v_pk_mul_f32 v[64:65], v[86:87], v[74:75] op_sel_hi:[0,1]
	v_pk_mul_f32 v[74:75], v[86:87], v[76:77] op_sel_hi:[0,1]
	v_and_b32_e32 v77, 0xffff0000, v56
	v_lshlrev_b32_e32 v48, 16, v49
	v_and_b32_e32 v49, 0xffff0000, v49
	v_lshlrev_b32_e32 v50, 16, v51
	v_and_b32_e32 v51, 0xffff0000, v51
	v_lshlrev_b32_e32 v76, 16, v56
	v_mul_f32_e32 v56, v77, v77
	v_pk_mul_f32 v[48:49], v[86:87], v[48:49] op_sel_hi:[0,1]
	v_pk_mul_f32 v[50:51], v[86:87], v[50:51] op_sel_hi:[0,1]
	v_lshlrev_b32_e32 v86, 16, v57
	v_and_b32_e32 v87, 0xffff0000, v57
	v_pk_fma_f32 v[56:57], v[76:77], v[76:77], v[56:57] op_sel_hi:[1,1,0]
	v_lshlrev_b32_e32 v90, 16, v58
	v_and_b32_e32 v91, 0xffff0000, v58
	v_mul_f32_e32 v58, v87, v87
	v_pk_fma_f32 v[56:57], v[86:87], v[86:87], v[56:57]
	v_lshlrev_b32_e32 v70, 16, v52
	v_pk_add_f32 v[56:57], v[58:59], v[56:57] op_sel_hi:[0,1]
	v_and_b32_e32 v71, 0xffff0000, v52
	v_lshlrev_b32_e32 v52, 16, v53
	v_and_b32_e32 v53, 0xffff0000, v53
	v_lshlrev_b32_e32 v72, 16, v54
	v_and_b32_e32 v73, 0xffff0000, v54
	v_lshlrev_b32_e32 v54, 16, v55
	v_and_b32_e32 v55, 0xffff0000, v55
	v_pk_mul_f32 v[64:65], v[20:21], v[64:65]
	v_pk_mul_f32 v[48:49], v[22:23], v[48:49]
	v_pk_mul_f32 v[74:75], v[16:17], v[74:75]
	v_pk_mul_f32 v[50:51], v[18:19], v[50:51]
	v_mul_f32_e32 v94, v91, v91
	v_pk_fma_f32 v[56:57], v[90:91], v[90:91], v[56:57]
	v_lshlrev_b32_e32 v92, 16, v59
	v_and_b32_e32 v93, 0xffff0000, v59
	v_pk_add_f32 v[94:95], v[94:95], v[56:57] op_sel_hi:[0,1]
	v_mov_b32_e32 v78, v123
	s_nop 1
	v_permlane32_swap_b32_e32 v123, v78
	v_mul_f32_e32 v122, v93, v93
	v_add_f32_e32 v78, v123, v78
	v_mov_b32_e32 v82, v78
	s_nop 1
	v_permlane16_swap_b32_e32 v78, v82
	s_waitcnt vmcnt(1)
	v_pk_fma_f32 v[56:57], v[64:65], v[60:61], v[70:71]
	v_pk_fma_f32 v[52:53], v[48:49], v[62:63], v[52:53]
	s_waitcnt vmcnt(0)
	v_pk_fma_f32 v[58:59], v[74:75], v[66:67], v[72:73]
	v_pk_fma_f32 v[54:55], v[50:51], v[68:69], v[54:55]
	v_cvt_pk_bf16_f32 v48, v56, v57
	v_cvt_pk_bf16_f32 v49, v52, v53
	v_cvt_pk_bf16_f32 v50, v58, v59
	v_cvt_pk_bf16_f32 v51, v54, v55
	global_store_dwordx4 v[120:121], v[48:51], off offset:1024
	global_load_dwordx4 v[52:55], v[88:89], off offset:16
	global_load_dwordx4 v[56:59], v[88:89], off
	global_load_dwordx4 v[60:63], v[84:85], off offset:16
	global_load_dwordx4 v[64:67], v[84:85], off
	v_pk_fma_f32 v[68:69], v[92:93], v[92:93], v[94:95]
	v_lshlrev_b32_e32 v70, 16, v48
	v_pk_add_f32 v[68:69], v[122:123], v[68:69] op_sel_hi:[0,1]
	v_and_b32_e32 v71, 0xffff0000, v48
	v_lshlrev_b32_e32 v72, 16, v49
	v_and_b32_e32 v73, 0xffff0000, v49
	v_lshlrev_b32_e32 v74, 16, v50
	v_and_b32_e32 v75, 0xffff0000, v50
	v_pk_fma_f32 v[48:49], v[70:71], v[70:71], v[68:69]
	v_mul_f32_e32 v50, v71, v71
	v_pk_add_f32 v[48:49], v[50:51], v[48:49] op_sel_hi:[0,1]
	v_mul_f32_e32 v68, v73, v73
	v_pk_fma_f32 v[48:49], v[72:73], v[72:73], v[48:49]
	v_mul_f32_e32 v120, v75, v75
	v_pk_add_f32 v[48:49], v[68:69], v[48:49] op_sel_hi:[0,1]
	v_pk_fma_f32 v[48:49], v[74:75], v[74:75], v[48:49]
	v_lshlrev_b32_e32 v94, 16, v51
	v_and_b32_e32 v95, 0xffff0000, v51
	v_pk_add_f32 v[48:49], v[120:121], v[48:49] op_sel_hi:[0,1]
	v_mul_f32_e32 v122, v95, v95
	v_pk_fma_f32 v[48:49], v[94:95], v[94:95], v[48:49]
	s_waitcnt vmcnt(3)
	v_pk_add_f32 v[52:53], v[52:53], 1.0 op_sel_hi:[1,0]
	v_pk_add_f32 v[48:49], v[122:123], v[48:49] op_sel_hi:[0,1]
	v_mov_b32_e32 v49, v48
	s_nop 1
	v_permlane32_swap_b32_e32 v48, v49
	v_add_f32_e32 v79, v48, v49
	v_mov_b32_e32 v83, v79
	s_nop 1
	v_permlane16_swap_b32_e32 v79, v83
	v_pk_add_f32 v[48:49], v[78:79], v[82:83]
	s_nop 1
	v_mov_b32_dpp v51, v49 row_ror:8 row_mask:0xf bank_mask:0xf
	s_nop 1
	v_mov_b32_dpp v50, v48 row_ror:8 row_mask:0xf bank_mask:0xf
	s_waitcnt vmcnt(2)
	v_pk_add_f32 v[58:59], v[58:59], 1.0 op_sel_hi:[1,0]
	v_pk_add_f32 v[56:57], v[56:57], 1.0 op_sel_hi:[1,0]
	v_pk_add_f32 v[54:55], v[54:55], 1.0 op_sel_hi:[1,0]
	v_lshl_add_u64 v[78:79], v[108:109], 0, v[118:119]
	s_waitcnt lgkmcnt(0)
	v_pk_add_f32 v[48:49], v[48:49], v[50:51]
	s_nop 1
	v_mov_b32_dpp v51, v49 row_ror:4 row_mask:0xf bank_mask:0xf
	s_nop 1
	v_mov_b32_dpp v50, v48 row_ror:4 row_mask:0xf bank_mask:0xf
	s_waitcnt lgkmcnt(0)
	v_pk_add_f32 v[48:49], v[48:49], v[50:51]
	s_nop 1
	v_mov_b32_dpp v51, v49 row_ror:2 row_mask:0xf bank_mask:0xf
	s_nop 1
	v_mov_b32_dpp v50, v48 row_ror:2 row_mask:0xf bank_mask:0xf
	s_waitcnt lgkmcnt(0)
	v_pk_add_f32 v[48:49], v[48:49], v[50:51]
	s_nop 1
	v_mov_b32_dpp v51, v49 row_ror:1 row_mask:0xf bank_mask:0xf
	s_nop 1
	v_mov_b32_dpp v50, v48 row_ror:1 row_mask:0xf bank_mask:0xf
	s_waitcnt lgkmcnt(0)
	v_pk_add_f32 v[48:49], v[48:49], v[50:51]
	s_nop 0
	v_pk_fma_f32 v[68:69], v[48:49], s[62:63], v[80:81] op_sel_hi:[1,0,0]
	s_nop 0
	v_mul_f32_e32 v48, 0x4b800000, v69
	v_cmp_gt_f32_e32 vcc, s67, v69
	s_nop 1
	v_cndmask_b32_e32 v48, v69, v48, vcc
	v_rsq_f32_e32 v48, v48
	s_nop 0
	v_mul_f32_e32 v49, 0x45800000, v48
	v_cndmask_b32_e32 v80, v48, v49, vcc
	v_pk_mul_f32 v[48:49], v[80:81], v[76:77] op_sel_hi:[0,1]
	v_pk_mul_f32 v[50:51], v[80:81], v[86:87] op_sel_hi:[0,1]
	v_pk_mul_f32 v[76:77], v[80:81], v[90:91] op_sel_hi:[0,1]
	v_pk_mul_f32 v[82:83], v[80:81], v[92:93] op_sel_hi:[0,1]
	v_pk_mul_f32 v[48:49], v[12:13], v[48:49]
	v_pk_mul_f32 v[50:51], v[14:15], v[50:51]
	v_pk_mul_f32 v[76:77], v[8:9], v[76:77]
	v_pk_mul_f32 v[82:83], v[10:11], v[82:83]
	s_waitcnt vmcnt(0)
	v_pk_fma_f32 v[48:49], v[56:57], v[48:49], v[64:65]
	v_pk_fma_f32 v[50:51], v[50:51], v[58:59], v[66:67]
	v_pk_fma_f32 v[52:53], v[76:77], v[52:53], v[60:61]
	v_pk_fma_f32 v[54:55], v[82:83], v[54:55], v[62:63]
	v_cvt_pk_bf16_f32 v48, v48, v49
	v_cvt_pk_bf16_f32 v49, v50, v51
	v_cvt_pk_bf16_f32 v50, v52, v53
	v_cvt_pk_bf16_f32 v51, v54, v55
	global_store_dwordx4 v[78:79], v[48:51], off
	global_load_dwordx4 v[48:51], v[88:89], off offset:2048
	s_nop 0
	global_load_dwordx4 v[52:55], v[88:89], off offset:2064
	global_load_dwordx4 v[56:59], v[84:85], off offset:2048
	global_load_dwordx4 v[60:63], v[84:85], off offset:2064
	v_add_u32_e32 v81, s66, v129
	v_ashrrev_i32_e32 v64, 31, v81
	v_lshrrev_b32_e32 v64, 20, v64
	v_add_u32_e32 v64, v81, v64
	v_pk_mul_f32 v[70:71], v[80:81], v[70:71] op_sel_hi:[0,1]
	v_pk_mul_f32 v[72:73], v[80:81], v[72:73] op_sel_hi:[0,1]
	v_pk_mul_f32 v[74:75], v[80:81], v[74:75] op_sel_hi:[0,1]
	v_pk_mul_f32 v[76:77], v[80:81], v[94:95] op_sel_hi:[0,1]
	v_ashrrev_i32_e32 v64, 12, v64
	v_pk_mul_f32 v[70:71], v[28:29], v[70:71]
	v_pk_mul_f32 v[72:73], v[30:31], v[72:73]
	v_pk_mul_f32 v[74:75], v[24:25], v[74:75]
	v_pk_mul_f32 v[76:77], v[26:27], v[76:77]
	v_mul_hi_i32_i24_e32 v65, 0x1800, v64
	v_mul_i32_i24_e32 v64, 0x1800, v64
	v_lshlrev_b64 v[64:65], 2, v[64:65]
	v_lshl_add_u64 v[66:67], v[102:103], 0, v[64:65]
	v_cmp_gt_f32_e32 vcc, s67, v68
	v_add_u32_e32 v130, s66, v81
	s_waitcnt vmcnt(3)
	v_pk_add_f32 v[48:49], v[48:49], 1.0 op_sel_hi:[1,0]
	v_pk_add_f32 v[50:51], v[50:51], 1.0 op_sel_hi:[1,0]
	s_waitcnt vmcnt(2)
	v_pk_add_f32 v[52:53], v[52:53], 1.0 op_sel_hi:[1,0]
	v_pk_add_f32 v[54:55], v[54:55], 1.0 op_sel_hi:[1,0]
	s_waitcnt vmcnt(1)
	v_pk_fma_f32 v[48:49], v[70:71], v[48:49], v[56:57]
	v_pk_fma_f32 v[50:51], v[72:73], v[50:51], v[58:59]
	s_waitcnt vmcnt(0)
	v_pk_fma_f32 v[52:53], v[74:75], v[52:53], v[60:61]
	v_pk_fma_f32 v[54:55], v[76:77], v[54:55], v[62:63]
	v_cvt_pk_bf16_f32 v48, v48, v49
	v_cvt_pk_bf16_f32 v49, v50, v51
	v_cvt_pk_bf16_f32 v50, v52, v53
	v_cvt_pk_bf16_f32 v51, v54, v55
	global_store_dwordx4 v[78:79], v[48:51], off offset:1024
	global_load_dwordx4 v[48:51], v[66:67], off
	s_nop 0
	global_load_dwordx4 v[52:55], v[66:67], off offset:16
	v_mul_f32_e32 v63, 0x4b800000, v68
	v_cndmask_b32_e32 v63, v68, v63, vcc
	v_rsq_f32_e32 v68, v63
	v_lshlrev_b32_e32 v60, 16, v40
	v_and_b32_e32 v61, 0xffff0000, v40
	v_lshlrev_b32_e32 v40, 16, v41
	v_mul_f32_e32 v69, 0x45800000, v68
	v_and_b32_e32 v41, 0xffff0000, v41
	v_lshlrev_b32_e32 v62, 16, v42
	v_and_b32_e32 v63, 0xffff0000, v42
	v_lshlrev_b32_e32 v42, 16, v43
	v_and_b32_e32 v43, 0xffff0000, v43
	v_cndmask_b32_e32 v68, v68, v69, vcc
	v_pk_mul_f32 v[60:61], v[68:69], v[60:61] op_sel_hi:[0,1]
	v_pk_mul_f32 v[40:41], v[68:69], v[40:41] op_sel_hi:[0,1]
	v_pk_mul_f32 v[62:63], v[68:69], v[62:63] op_sel_hi:[0,1]
	v_pk_mul_f32 v[42:43], v[68:69], v[42:43] op_sel_hi:[0,1]
	v_lshlrev_b32_e32 v56, 16, v44
	v_and_b32_e32 v57, 0xffff0000, v44
	v_lshlrev_b32_e32 v44, 16, v45
	v_and_b32_e32 v45, 0xffff0000, v45
	v_lshlrev_b32_e32 v58, 16, v46
	v_and_b32_e32 v59, 0xffff0000, v46
	v_lshlrev_b32_e32 v46, 16, v47
	v_and_b32_e32 v47, 0xffff0000, v47
	v_pk_mul_f32 v[60:61], v[4:5], v[60:61]
	v_pk_mul_f32 v[40:41], v[6:7], v[40:41]
	v_pk_mul_f32 v[62:63], v[0:1], v[62:63]
	v_pk_mul_f32 v[42:43], v[2:3], v[42:43]
	s_waitcnt vmcnt(1)
	v_pk_fma_f32 v[48:49], v[48:49], v[60:61], v[56:57]
	v_pk_fma_f32 v[44:45], v[50:51], v[40:41], v[44:45]
	s_waitcnt vmcnt(0)
	v_pk_fma_f32 v[50:51], v[52:53], v[62:63], v[58:59]
	v_pk_fma_f32 v[46:47], v[54:55], v[42:43], v[46:47]
	v_cvt_pk_bf16_f32 v40, v48, v49
	v_cvt_pk_bf16_f32 v41, v44, v45
	v_cvt_pk_bf16_f32 v42, v50, v51
	v_cvt_pk_bf16_f32 v43, v46, v47
	global_store_dwordx4 v[116:117], v[40:43], off
	global_load_dwordx4 v[44:47], v[66:67], off offset:2048
	global_load_dwordx4 v[48:51], v[66:67], off offset:2064
	v_lshlrev_b32_e32 v56, 16, v32
	v_and_b32_e32 v57, 0xffff0000, v32
	v_lshlrev_b32_e32 v32, 16, v33
	v_and_b32_e32 v33, 0xffff0000, v33
	v_lshlrev_b32_e32 v58, 16, v34
	v_and_b32_e32 v59, 0xffff0000, v34
	v_lshlrev_b32_e32 v34, 16, v35
	v_and_b32_e32 v35, 0xffff0000, v35
	v_lshl_add_u64 v[60:61], v[104:105], 0, v[64:65]
	v_lshl_add_u64 v[62:63], v[106:107], 0, v[64:65]
	v_pk_mul_f32 v[56:57], v[68:69], v[56:57] op_sel_hi:[0,1]
	v_pk_mul_f32 v[32:33], v[68:69], v[32:33] op_sel_hi:[0,1]
	v_pk_mul_f32 v[58:59], v[68:69], v[58:59] op_sel_hi:[0,1]
	v_pk_mul_f32 v[34:35], v[68:69], v[34:35] op_sel_hi:[0,1]
	v_and_b32_e32 v65, 0xffff0000, v40
	v_lshlrev_b32_e32 v52, 16, v36
	v_and_b32_e32 v53, 0xffff0000, v36
	v_lshlrev_b32_e32 v36, 16, v37
	v_and_b32_e32 v37, 0xffff0000, v37
	v_lshlrev_b32_e32 v54, 16, v38
	v_and_b32_e32 v55, 0xffff0000, v38
	v_lshlrev_b32_e32 v38, 16, v39
	v_and_b32_e32 v39, 0xffff0000, v39
	v_pk_mul_f32 v[56:57], v[20:21], v[56:57]
	v_pk_mul_f32 v[32:33], v[22:23], v[32:33]
	v_pk_mul_f32 v[58:59], v[16:17], v[58:59]
	v_pk_mul_f32 v[34:35], v[18:19], v[34:35]
	v_lshlrev_b32_e32 v64, 16, v40
	v_mul_f32_e32 v40, v65, v65
	v_lshlrev_b32_e32 v66, 16, v41
	v_and_b32_e32 v67, 0xffff0000, v41
	v_lshlrev_b32_e32 v68, 16, v42
	v_and_b32_e32 v69, 0xffff0000, v42
	v_lshlrev_b32_e32 v70, 16, v43
	v_and_b32_e32 v71, 0xffff0000, v43
	v_pk_fma_f32 v[78:79], v[64:65], v[64:65], v[40:41] op_sel_hi:[1,1,0]
	v_mul_f32_e32 v72, v67, v67
	v_mul_f32_e32 v74, v69, v69
	v_mul_f32_e32 v76, v71, v71
	s_waitcnt vmcnt(1)
	v_pk_fma_f32 v[40:41], v[56:57], v[44:45], v[52:53]
	v_pk_fma_f32 v[36:37], v[32:33], v[46:47], v[36:37]
	s_waitcnt vmcnt(0)
	v_pk_fma_f32 v[42:43], v[58:59], v[48:49], v[54:55]
	v_pk_fma_f32 v[38:39], v[34:35], v[50:51], v[38:39]
	v_cvt_pk_bf16_f32 v32, v40, v41
	v_cvt_pk_bf16_f32 v33, v36, v37
	v_cvt_pk_bf16_f32 v34, v42, v43
	v_cvt_pk_bf16_f32 v35, v38, v39
	global_store_dwordx4 v[116:117], v[32:35], off offset:1024
	global_load_dwordx4 v[36:39], v[62:63], off offset:16
	global_load_dwordx4 v[40:43], v[62:63], off
	global_load_dwordx4 v[44:47], v[60:61], off offset:16
	global_load_dwordx4 v[48:51], v[60:61], off
	v_pk_fma_f32 v[52:53], v[66:67], v[66:67], v[78:79]
	v_lshlrev_b32_e32 v54, 16, v32
	v_pk_add_f32 v[52:53], v[72:73], v[52:53] op_sel_hi:[0,1]
	v_pk_fma_f32 v[52:53], v[68:69], v[68:69], v[52:53]
	v_and_b32_e32 v55, 0xffff0000, v32
	v_pk_add_f32 v[52:53], v[74:75], v[52:53] op_sel_hi:[0,1]
	v_pk_fma_f32 v[52:53], v[70:71], v[70:71], v[52:53]
	v_lshlrev_b32_e32 v56, 16, v33
	v_pk_add_f32 v[52:53], v[76:77], v[52:53] op_sel_hi:[0,1]
	v_and_b32_e32 v57, 0xffff0000, v33
	v_lshlrev_b32_e32 v58, 16, v34
	v_and_b32_e32 v59, 0xffff0000, v34
	v_pk_fma_f32 v[32:33], v[54:55], v[54:55], v[52:53]
	v_mul_f32_e32 v34, v55, v55
	v_pk_add_f32 v[32:33], v[34:35], v[32:33] op_sel_hi:[0,1]
	v_mul_f32_e32 v52, v57, v57
	v_pk_fma_f32 v[32:33], v[56:57], v[56:57], v[32:33]
	v_mul_f32_e32 v74, v59, v59
	v_pk_add_f32 v[32:33], v[52:53], v[32:33] op_sel_hi:[0,1]
	v_pk_fma_f32 v[32:33], v[58:59], v[58:59], v[32:33]
	v_lshlrev_b32_e32 v72, 16, v35
	v_and_b32_e32 v73, 0xffff0000, v35
	v_pk_add_f32 v[32:33], v[74:75], v[32:33] op_sel_hi:[0,1]
	v_mul_f32_e32 v76, v73, v73
	v_pk_fma_f32 v[32:33], v[72:73], v[72:73], v[32:33]
	v_lshl_add_u64 v[52:53], v[108:109], 0, v[114:115]
	v_pk_add_f32 v[32:33], v[76:77], v[32:33] op_sel_hi:[0,1]
	v_mov_b32_e32 v33, v32
	s_nop 1
	v_permlane32_swap_b32_e32 v32, v33
	v_add_f32_e32 v32, v32, v33
	v_mov_b32_e32 v33, v32
	s_nop 1
	v_permlane16_swap_b32_e32 v32, v33
	v_add_f32_e32 v32, v32, v33
	s_nop 1
	v_mov_b32_dpp v33, v32 row_ror:8 row_mask:0xf bank_mask:0xf
	s_waitcnt lgkmcnt(0)
	v_add_f32_e32 v32, v32, v33
	s_nop 1
	v_mov_b32_dpp v33, v32 row_ror:4 row_mask:0xf bank_mask:0xf
	s_waitcnt lgkmcnt(0)
	v_add_f32_e32 v32, v32, v33
	s_nop 1
	v_mov_b32_dpp v33, v32 row_ror:2 row_mask:0xf bank_mask:0xf
	s_waitcnt lgkmcnt(0)
	v_add_f32_e32 v32, v32, v33
	s_nop 1
	v_mov_b32_dpp v33, v32 row_ror:1 row_mask:0xf bank_mask:0xf
	s_waitcnt lgkmcnt(0)
	v_add_f32_e32 v32, v32, v33
	v_fmamk_f32 v32, v32, 0x3a800000, v188
	v_mul_f32_e32 v33, 0x4b800000, v32
	v_cmp_gt_f32_e32 vcc, s67, v32
	s_waitcnt vmcnt(3)
	v_pk_add_f32 v[36:37], v[36:37], 1.0 op_sel_hi:[1,0]
	v_cndmask_b32_e32 v32, v32, v33, vcc
	v_rsq_f32_e32 v32, v32
	s_waitcnt vmcnt(2)
	v_pk_add_f32 v[42:43], v[42:43], 1.0 op_sel_hi:[1,0]
	v_pk_add_f32 v[40:41], v[40:41], 1.0 op_sel_hi:[1,0]
	v_pk_add_f32 v[38:39], v[38:39], 1.0 op_sel_hi:[1,0]
	v_mul_f32_e32 v33, 0x45800000, v32
	v_cndmask_b32_e32 v74, v32, v33, vcc
	v_pk_mul_f32 v[32:33], v[74:75], v[64:65] op_sel_hi:[0,1]
	v_pk_mul_f32 v[34:35], v[74:75], v[66:67] op_sel_hi:[0,1]
	v_pk_mul_f32 v[64:65], v[74:75], v[68:69] op_sel_hi:[0,1]
	v_pk_mul_f32 v[66:67], v[74:75], v[70:71] op_sel_hi:[0,1]
	v_pk_mul_f32 v[32:33], v[12:13], v[32:33]
	v_pk_mul_f32 v[34:35], v[14:15], v[34:35]
	v_pk_mul_f32 v[64:65], v[8:9], v[64:65]
	v_pk_mul_f32 v[66:67], v[10:11], v[66:67]
	s_waitcnt vmcnt(0)
	v_pk_fma_f32 v[32:33], v[40:41], v[32:33], v[48:49]
	v_pk_fma_f32 v[34:35], v[34:35], v[42:43], v[50:51]
	v_pk_fma_f32 v[36:37], v[64:65], v[36:37], v[44:45]
	v_pk_fma_f32 v[38:39], v[66:67], v[38:39], v[46:47]
	v_cvt_pk_bf16_f32 v32, v32, v33
	v_cvt_pk_bf16_f32 v33, v34, v35
	v_cvt_pk_bf16_f32 v34, v36, v37
	v_cvt_pk_bf16_f32 v35, v38, v39
	global_store_dwordx4 v[52:53], v[32:35], off
	global_load_dwordx4 v[32:35], v[62:63], off offset:2048
	s_nop 0
	global_load_dwordx4 v[36:39], v[62:63], off offset:2064
	global_load_dwordx4 v[40:43], v[60:61], off offset:2048
	global_load_dwordx4 v[44:47], v[60:61], off offset:2064
	v_pk_mul_f32 v[48:49], v[74:75], v[54:55] op_sel_hi:[0,1]
	v_pk_mul_f32 v[50:51], v[74:75], v[56:57] op_sel_hi:[0,1]
	v_pk_mul_f32 v[54:55], v[74:75], v[58:59] op_sel_hi:[0,1]
	v_pk_mul_f32 v[56:57], v[74:75], v[72:73] op_sel_hi:[0,1]
	v_pk_mul_f32 v[48:49], v[28:29], v[48:49]
	v_pk_mul_f32 v[50:51], v[30:31], v[50:51]
	v_pk_mul_f32 v[54:55], v[24:25], v[54:55]
	v_pk_mul_f32 v[56:57], v[26:27], v[56:57]
	v_cmp_lt_i32_e32 vcc, s46, v130
	s_or_b64 s[28:29], vcc, s[28:29]
	s_waitcnt vmcnt(3)
	v_pk_add_f32 v[32:33], v[32:33], 1.0 op_sel_hi:[1,0]
	v_pk_add_f32 v[34:35], v[34:35], 1.0 op_sel_hi:[1,0]
	s_waitcnt vmcnt(2)
	v_pk_add_f32 v[36:37], v[36:37], 1.0 op_sel_hi:[1,0]
	v_pk_add_f32 v[38:39], v[38:39], 1.0 op_sel_hi:[1,0]
	s_waitcnt vmcnt(1)
	v_pk_fma_f32 v[32:33], v[48:49], v[32:33], v[40:41]
	v_pk_fma_f32 v[34:35], v[50:51], v[34:35], v[42:43]
	s_waitcnt vmcnt(0)
	v_pk_fma_f32 v[36:37], v[54:55], v[36:37], v[44:45]
	v_pk_fma_f32 v[38:39], v[56:57], v[38:39], v[46:47]
	v_cvt_pk_bf16_f32 v32, v32, v33
	v_cvt_pk_bf16_f32 v33, v34, v35
	v_cvt_pk_bf16_f32 v34, v36, v37
	v_cvt_pk_bf16_f32 v35, v38, v39
	global_store_dwordx4 v[52:53], v[32:35], off offset:1024
	s_andn2_b64 exec, exec, s[28:29]
	s_cbranch_execz .LBB0_2274

.LBB0_2278:
	s_or_b64 exec, exec, s[4:5]
	v_ashrrev_i32_e32 v165, 31, v164
	v_lshrrev_b32_e32 v165, 20, v165
	v_add_u32_e32 v164, v164, v165
	v_ashrrev_i32_e32 v164, 12, v164
	v_mul_hi_i32_i24_e32 v165, 0x1800, v164
	v_mul_i32_i24_e32 v164, 0x1800, v164
	v_lshlrev_b64 v[164:165], 2, v[164:165]
	v_lshl_add_u64 v[168:169], v[138:139], 0, v[164:165]
	global_load_dwordx4 v[172:175], v[168:169], off
	global_load_dwordx4 v[176:179], v[168:169], off offset:16
	s_waitcnt vmcnt(20)
	v_mov_b32_e32 v166, v134
	s_nop 1
	v_permlane32_swap_b32_e32 v134, v166
	v_add_f32_e32 v134, v134, v166
	v_mov_b32_e32 v166, v134
	s_nop 1
	v_permlane16_swap_b32_e32 v134, v166
	v_add_f32_e32 v134, v134, v166
	s_nop 1
	v_mov_b32_dpp v166, v134 row_ror:8 row_mask:0xf bank_mask:0xf
	v_lshlrev_b32_e32 v180, 16, v124
	v_and_b32_e32 v181, 0xffff0000, v124
	v_lshlrev_b32_e32 v124, 16, v125
	v_and_b32_e32 v125, 0xffff0000, v125
	s_waitcnt lgkmcnt(0)
	v_add_f32_e32 v134, v134, v166
	s_nop 1
	v_mov_b32_dpp v166, v134 row_ror:4 row_mask:0xf bank_mask:0xf
	v_lshlrev_b32_e32 v182, 16, v126
	v_and_b32_e32 v183, 0xffff0000, v126
	v_lshlrev_b32_e32 v126, 16, v127
	v_and_b32_e32 v127, 0xffff0000, v127
	s_waitcnt lgkmcnt(0)
	v_add_f32_e32 v134, v134, v166
	s_nop 1
	v_mov_b32_dpp v166, v134 row_ror:2 row_mask:0xf bank_mask:0xf
	s_mov_b32 s4, 0x6400000
	v_lshl_add_u64 v[148:149], v[148:149], 0, s[38:39]
	v_lshl_add_u64 v[150:151], v[150:151], 0, s[40:41]
	v_lshl_add_u64 v[152:153], v[152:153], 0, s[42:43]
	s_waitcnt lgkmcnt(0)
	v_add_f32_e32 v134, v134, v166
	s_nop 1
	v_mov_b32_dpp v166, v134 row_ror:1 row_mask:0xf bank_mask:0xf
	s_waitcnt lgkmcnt(0)
	v_add_f32_e32 v134, v134, v166
	v_fmamk_f32 v134, v134, 0x3a800000, v188
	v_mul_f32_e32 v166, 0x4b800000, v134
	v_cmp_gt_f32_e32 vcc, s67, v134
	s_nop 1
	v_cndmask_b32_e32 v134, v134, v166, vcc
	v_rsq_f32_e32 v134, v134
	v_add_co_u32_e64 v166, s[4:5], s4, v162
	v_mul_f32_e32 v171, 0x45800000, v134
	v_cndmask_b32_e32 v134, v134, v171, vcc
	v_pk_mul_f32 v[180:181], v[134:135], v[180:181] op_sel_hi:[0,1]
	v_pk_mul_f32 v[124:125], v[134:135], v[124:125] op_sel_hi:[0,1]
	v_pk_mul_f32 v[182:183], v[134:135], v[182:183] op_sel_hi:[0,1]
	v_pk_mul_f32 v[126:127], v[134:135], v[126:127] op_sel_hi:[0,1]
	v_pk_mul_f32 v[180:181], v[4:5], v[180:181]
	v_pk_mul_f32 v[124:125], v[6:7], v[124:125]
	v_pk_mul_f32 v[182:183], v[0:1], v[182:183]
	v_pk_mul_f32 v[126:127], v[2:3], v[126:127]
	v_addc_co_u32_e64 v167, s[4:5], 0, v163, s[4:5]
	v_add_co_u32_e64 v162, s[4:5], s69, v162
	s_waitcnt vmcnt(1)
	v_pk_fma_f32 v[120:121], v[172:173], v[180:181], v[120:121]
	v_pk_fma_f32 v[122:123], v[174:175], v[124:125], v[122:123]
	s_waitcnt vmcnt(0)
	v_pk_fma_f32 v[124:125], v[176:177], v[182:183], v[116:117]
	v_pk_fma_f32 v[126:127], v[178:179], v[126:127], v[118:119]
	v_cvt_pk_bf16_f32 v116, v120, v121
	v_cvt_pk_bf16_f32 v117, v122, v123
	v_cvt_pk_bf16_f32 v118, v124, v125
	v_cvt_pk_bf16_f32 v119, v126, v127
	global_store_dwordx4 v[166:167], v[116:119], off
	global_load_dwordx4 v[124:127], v[168:169], off offset:2048
	global_load_dwordx4 v[120:123], v[168:169], off offset:2064
	v_mov_b32_e32 v168, v170
	v_lshlrev_b32_e32 v172, 16, v112
	v_and_b32_e32 v173, 0xffff0000, v112
	v_lshlrev_b32_e32 v174, 16, v114
	v_and_b32_e32 v175, 0xffff0000, v114
	v_permlane32_swap_b32_e32 v170, v168
	v_add_f32_e32 v180, v170, v168
	v_lshl_add_u64 v[168:169], v[140:141], 0, v[164:165]
	v_lshl_add_u64 v[170:171], v[142:143], 0, v[164:165]
	v_pk_mul_f32 v[164:165], v[134:135], v[172:173] op_sel_hi:[0,1]
	v_pk_mul_f32 v[172:173], v[134:135], v[174:175] op_sel_hi:[0,1]
	v_pk_mul_f32 v[202:203], v[16:17], v[172:173]
	v_and_b32_e32 v173, 0xffff0000, v116
	v_lshlrev_b32_e32 v112, 16, v113
	v_and_b32_e32 v113, 0xffff0000, v113
	v_lshlrev_b32_e32 v114, 16, v115
	v_and_b32_e32 v115, 0xffff0000, v115
	v_lshlrev_b32_e32 v172, 16, v116
	v_mul_f32_e32 v116, v173, v173
	v_pk_mul_f32 v[112:113], v[134:135], v[112:113] op_sel_hi:[0,1]
	v_pk_mul_f32 v[114:115], v[134:135], v[114:115] op_sel_hi:[0,1]
	v_lshlrev_b32_e32 v174, 16, v117
	v_and_b32_e32 v175, 0xffff0000, v117
	v_pk_fma_f32 v[116:117], v[172:173], v[172:173], v[116:117] op_sel_hi:[1,1,0]
	v_pk_mul_f32 v[164:165], v[20:21], v[164:165]
	v_pk_mul_f32 v[112:113], v[22:23], v[112:113]
	v_pk_mul_f32 v[114:115], v[18:19], v[114:115]
	v_lshlrev_b32_e32 v176, 16, v118
	v_and_b32_e32 v177, 0xffff0000, v118
	v_mul_f32_e32 v118, v175, v175
	v_pk_fma_f32 v[116:117], v[174:175], v[174:175], v[116:117]
	v_mul_f32_e32 v134, v177, v177
	v_pk_add_f32 v[116:117], v[118:119], v[116:117] op_sel_hi:[0,1]
	v_pk_fma_f32 v[116:117], v[176:177], v[176:177], v[116:117]
	v_lshlrev_b32_e32 v178, 16, v119
	v_and_b32_e32 v179, 0xffff0000, v119
	v_pk_add_f32 v[116:117], v[134:135], v[116:117] op_sel_hi:[0,1]
	v_pk_fma_f32 v[208:209], v[178:179], v[178:179], v[116:117]
	v_mul_f32_e32 v206, v179, v179
	v_mov_b32_e32 v182, v180
	s_nop 1
	v_permlane16_swap_b32_e32 v180, v182
	v_addc_co_u32_e64 v163, s[4:5], 0, v163, s[4:5]
	s_waitcnt vmcnt(1)
	v_pk_fma_f32 v[108:109], v[164:165], v[124:125], v[108:109]
	v_pk_fma_f32 v[110:111], v[112:113], v[126:127], v[110:111]
	s_waitcnt vmcnt(0)
	v_pk_fma_f32 v[104:105], v[202:203], v[120:121], v[104:105]
	v_pk_fma_f32 v[106:107], v[114:115], v[122:123], v[106:107]
	v_cvt_pk_bf16_f32 v202, v108, v109
	v_cvt_pk_bf16_f32 v203, v110, v111
	v_cvt_pk_bf16_f32 v204, v104, v105
	v_cvt_pk_bf16_f32 v205, v106, v107
	global_store_dwordx4 v[166:167], v[202:205], off offset:1024
	global_load_dwordx4 v[108:111], v[170:171], off offset:16
	global_load_dwordx4 v[116:119], v[170:171], off
	global_load_dwordx4 v[104:107], v[168:169], off offset:16
	global_load_dwordx4 v[112:115], v[168:169], off
	v_pk_add_f32 v[120:121], v[206:207], v[208:209] op_sel_hi:[0,1]
	v_lshlrev_b32_e32 v122, 16, v202
	v_and_b32_e32 v123, 0xffff0000, v202
	v_pk_fma_f32 v[120:121], v[122:123], v[122:123], v[120:121]
	v_mul_f32_e32 v134, v123, v123
	v_lshlrev_b32_e32 v124, 16, v203
	v_and_b32_e32 v125, 0xffff0000, v203
	v_pk_add_f32 v[120:121], v[134:135], v[120:121] op_sel_hi:[0,1]
	v_mul_f32_e32 v166, v125, v125
	v_pk_fma_f32 v[120:121], v[124:125], v[124:125], v[120:121]
	v_lshlrev_b32_e32 v126, 16, v204
	v_and_b32_e32 v127, 0xffff0000, v204
	v_pk_add_f32 v[120:121], v[166:167], v[120:121] op_sel_hi:[0,1]
	v_mul_f32_e32 v202, v127, v127
	v_pk_fma_f32 v[120:121], v[126:127], v[126:127], v[120:121]
	v_lshlrev_b32_e32 v164, 16, v205
	v_and_b32_e32 v165, 0xffff0000, v205
	v_pk_add_f32 v[120:121], v[202:203], v[120:121] op_sel_hi:[0,1]
	v_mul_f32_e32 v204, v165, v165
	v_pk_fma_f32 v[120:121], v[164:165], v[164:165], v[120:121]
	s_waitcnt vmcnt(3)
	v_pk_add_f32 v[108:109], v[108:109], 1.0 op_sel_hi:[1,0]
	v_pk_add_f32 v[120:121], v[204:205], v[120:121] op_sel_hi:[0,1]
	v_mov_b32_e32 v121, v120
	s_nop 1
	v_permlane32_swap_b32_e32 v120, v121
	v_add_f32_e32 v181, v120, v121
	v_mov_b32_e32 v183, v181
	s_nop 1
	v_permlane16_swap_b32_e32 v181, v183
	v_pk_add_f32 v[120:121], v[180:181], v[182:183]
	s_nop 1
	v_mov_b32_dpp v167, v121 row_ror:8 row_mask:0xf bank_mask:0xf
	s_nop 1
	v_mov_b32_dpp v166, v120 row_ror:8 row_mask:0xf bank_mask:0xf
	s_waitcnt vmcnt(2)
	v_pk_add_f32 v[118:119], v[118:119], 1.0 op_sel_hi:[1,0]
	v_pk_add_f32 v[116:117], v[116:117], 1.0 op_sel_hi:[1,0]
	v_pk_add_f32 v[110:111], v[110:111], 1.0 op_sel_hi:[1,0]
	s_waitcnt lgkmcnt(0)
	v_pk_add_f32 v[120:121], v[120:121], v[166:167]
	s_nop 1
	v_mov_b32_dpp v167, v121 row_ror:4 row_mask:0xf bank_mask:0xf
	s_nop 1
	v_mov_b32_dpp v166, v120 row_ror:4 row_mask:0xf bank_mask:0xf
	s_waitcnt lgkmcnt(0)
	v_pk_add_f32 v[120:121], v[120:121], v[166:167]
	s_nop 1
	v_mov_b32_dpp v167, v121 row_ror:2 row_mask:0xf bank_mask:0xf
	s_nop 1
	v_mov_b32_dpp v166, v120 row_ror:2 row_mask:0xf bank_mask:0xf
	s_waitcnt lgkmcnt(0)
	v_pk_add_f32 v[166:167], v[120:121], v[166:167]
	s_nop 1
	v_mov_b32_dpp v181, v167 row_ror:1 row_mask:0xf bank_mask:0xf
	s_nop 1
	v_mov_b32_dpp v180, v166 row_ror:1 row_mask:0xf bank_mask:0xf
	v_mov_b64_e32 v[120:121], s[68:69]
	s_waitcnt lgkmcnt(0)
	v_pk_add_f32 v[166:167], v[166:167], v[180:181]
	s_nop 0
	v_pk_fma_f32 v[166:167], v[166:167], s[62:63], v[120:121] op_sel_hi:[1,0,0]
	s_nop 0
	v_mul_f32_e32 v134, 0x4b800000, v167
	v_cmp_gt_f32_e32 vcc, s67, v167
	s_nop 1
	v_cndmask_b32_e32 v134, v167, v134, vcc
	v_rsq_f32_e32 v134, v134
	s_nop 0
	v_mul_f32_e32 v167, 0x45800000, v134
	v_cndmask_b32_e32 v134, v134, v167, vcc
	v_pk_mul_f32 v[172:173], v[134:135], v[172:173] op_sel_hi:[0,1]
	v_pk_mul_f32 v[174:175], v[134:135], v[174:175] op_sel_hi:[0,1]
	v_pk_mul_f32 v[176:177], v[134:135], v[176:177] op_sel_hi:[0,1]
	v_pk_mul_f32 v[178:179], v[134:135], v[178:179] op_sel_hi:[0,1]
	v_pk_mul_f32 v[172:173], v[12:13], v[172:173]
	v_pk_mul_f32 v[174:175], v[14:15], v[174:175]
	v_pk_mul_f32 v[176:177], v[8:9], v[176:177]
	v_pk_mul_f32 v[178:179], v[10:11], v[178:179]
	s_waitcnt vmcnt(0)
	v_pk_fma_f32 v[112:113], v[116:117], v[172:173], v[112:113]
	v_pk_fma_f32 v[114:115], v[174:175], v[118:119], v[114:115]
	v_pk_fma_f32 v[108:109], v[176:177], v[108:109], v[104:105]
	v_pk_fma_f32 v[110:111], v[178:179], v[110:111], v[106:107]
	v_cvt_pk_bf16_f32 v104, v112, v113
	v_cvt_pk_bf16_f32 v105, v114, v115
	v_cvt_pk_bf16_f32 v106, v108, v109
	v_cvt_pk_bf16_f32 v107, v110, v111
	global_store_dwordx4 v[162:163], v[104:107], off
	global_load_dwordx4 v[106:109], v[170:171], off offset:2048
	s_nop 0
	global_load_dwordx4 v[112:115], v[170:171], off offset:2064
	global_load_dwordx4 v[116:119], v[168:169], off offset:2048
	s_nop 0
	global_load_dwordx4 v[168:171], v[168:169], off offset:2064
	v_ashrrev_i32_e32 v104, 31, v158
	v_lshrrev_b32_e32 v104, 20, v104
	v_add_u32_e32 v104, v158, v104
	v_pk_mul_f32 v[122:123], v[134:135], v[122:123] op_sel_hi:[0,1]
	v_pk_mul_f32 v[124:125], v[134:135], v[124:125] op_sel_hi:[0,1]
	v_pk_mul_f32 v[126:127], v[134:135], v[126:127] op_sel_hi:[0,1]
	v_pk_mul_f32 v[164:165], v[134:135], v[164:165] op_sel_hi:[0,1]
	v_ashrrev_i32_e32 v104, 12, v104
	v_pk_mul_f32 v[122:123], v[28:29], v[122:123]
	v_pk_mul_f32 v[124:125], v[30:31], v[124:125]
	v_pk_mul_f32 v[126:127], v[24:25], v[126:127]
	v_pk_mul_f32 v[164:165], v[26:27], v[164:165]
	v_mul_hi_i32_i24_e32 v105, 0x1800, v104
	v_mul_i32_i24_e32 v104, 0x1800, v104
	v_lshlrev_b64 v[104:105], 2, v[104:105]
	v_lshl_add_u64 v[110:111], v[138:139], 0, v[104:105]
	v_cmp_gt_f32_e32 vcc, s67, v166
	s_waitcnt vmcnt(3)
	v_pk_add_f32 v[106:107], v[106:107], 1.0 op_sel_hi:[1,0]
	v_pk_add_f32 v[108:109], v[108:109], 1.0 op_sel_hi:[1,0]
	s_waitcnt vmcnt(2)
	v_pk_add_f32 v[112:113], v[112:113], 1.0 op_sel_hi:[1,0]
	v_pk_add_f32 v[114:115], v[114:115], 1.0 op_sel_hi:[1,0]
	s_waitcnt vmcnt(1)
	v_pk_fma_f32 v[106:107], v[122:123], v[106:107], v[116:117]
	v_pk_fma_f32 v[108:109], v[124:125], v[108:109], v[118:119]
	s_waitcnt vmcnt(0)
	v_pk_fma_f32 v[112:113], v[126:127], v[112:113], v[168:169]
	v_pk_fma_f32 v[114:115], v[164:165], v[114:115], v[170:171]
	v_cvt_pk_bf16_f32 v106, v106, v107
	v_cvt_pk_bf16_f32 v107, v108, v109
	v_cvt_pk_bf16_f32 v108, v112, v113
	v_cvt_pk_bf16_f32 v109, v114, v115
	global_store_dwordx4 v[162:163], v[106:109], off offset:1024
	global_load_dwordx4 v[112:115], v[110:111], off
	global_load_dwordx4 v[116:119], v[110:111], off offset:16
	v_lshlrev_b32_e32 v124, 16, v102
	v_and_b32_e32 v125, 0xffff0000, v102
	v_mul_f32_e32 v102, 0x4b800000, v166
	v_cndmask_b32_e32 v102, v166, v102, vcc
	v_rsq_f32_e32 v108, v102
	v_lshlrev_b32_e32 v122, 16, v100
	v_and_b32_e32 v123, 0xffff0000, v100
	v_lshlrev_b32_e32 v100, 16, v101
	v_mul_f32_e32 v109, 0x45800000, v108
	v_and_b32_e32 v101, 0xffff0000, v101
	v_lshlrev_b32_e32 v102, 16, v103
	v_and_b32_e32 v103, 0xffff0000, v103
	v_cndmask_b32_e32 v108, v108, v109, vcc
	v_pk_mul_f32 v[122:123], v[108:109], v[122:123] op_sel_hi:[0,1]
	v_pk_mul_f32 v[100:101], v[108:109], v[100:101] op_sel_hi:[0,1]
	v_pk_mul_f32 v[124:125], v[108:109], v[124:125] op_sel_hi:[0,1]
	v_pk_mul_f32 v[102:103], v[108:109], v[102:103] op_sel_hi:[0,1]
	v_pk_mul_f32 v[122:123], v[4:5], v[122:123]
	v_pk_mul_f32 v[100:101], v[6:7], v[100:101]
	v_pk_mul_f32 v[124:125], v[0:1], v[124:125]
	v_pk_mul_f32 v[102:103], v[2:3], v[102:103]
	v_lshl_add_u64 v[106:107], v[144:145], 0, v[160:161]
	v_mov_b32_e32 v109, v201
	s_nop 1
	v_permlane32_swap_b32_e32 v201, v109
	s_waitcnt vmcnt(1)
	v_pk_fma_f32 v[96:97], v[112:113], v[122:123], v[96:97]
	v_pk_fma_f32 v[98:99], v[114:115], v[100:101], v[98:99]
	s_waitcnt vmcnt(0)
	v_pk_fma_f32 v[100:101], v[116:117], v[124:125], v[92:93]
	v_pk_fma_f32 v[102:103], v[118:119], v[102:103], v[94:95]
	v_cvt_pk_bf16_f32 v92, v96, v97
	v_cvt_pk_bf16_f32 v93, v98, v99
	v_cvt_pk_bf16_f32 v94, v100, v101
	v_cvt_pk_bf16_f32 v95, v102, v103
	global_store_dwordx4 v[106:107], v[92:95], off
	global_load_dwordx4 v[100:103], v[110:111], off offset:2048
	global_load_dwordx4 v[96:99], v[110:111], off offset:2064
	v_lshlrev_b32_e32 v112, 16, v88
	v_and_b32_e32 v113, 0xffff0000, v88
	v_lshlrev_b32_e32 v88, 16, v89
	v_and_b32_e32 v89, 0xffff0000, v89
	v_lshlrev_b32_e32 v114, 16, v90
	v_and_b32_e32 v115, 0xffff0000, v90
	v_lshlrev_b32_e32 v90, 16, v91
	v_and_b32_e32 v91, 0xffff0000, v91
	v_and_b32_e32 v117, 0xffff0000, v92
	v_pk_mul_f32 v[112:113], v[108:109], v[112:113] op_sel_hi:[0,1]
	v_pk_mul_f32 v[88:89], v[108:109], v[88:89] op_sel_hi:[0,1]
	v_pk_mul_f32 v[114:115], v[108:109], v[114:115] op_sel_hi:[0,1]
	v_pk_mul_f32 v[90:91], v[108:109], v[90:91] op_sel_hi:[0,1]
	v_lshlrev_b32_e32 v116, 16, v92
	v_mul_f32_e32 v92, v117, v117
	v_pk_mul_f32 v[124:125], v[20:21], v[112:113]
	v_pk_mul_f32 v[88:89], v[22:23], v[88:89]
	v_pk_mul_f32 v[126:127], v[16:17], v[114:115]
	v_pk_mul_f32 v[90:91], v[18:19], v[90:91]
	v_lshlrev_b32_e32 v114, 16, v93
	v_and_b32_e32 v115, 0xffff0000, v93
	v_pk_fma_f32 v[92:93], v[116:117], v[116:117], v[92:93] op_sel_hi:[1,1,0]
	v_lshlrev_b32_e32 v112, 16, v94
	v_and_b32_e32 v113, 0xffff0000, v94
	v_mul_f32_e32 v94, v115, v115
	v_pk_fma_f32 v[92:93], v[114:115], v[114:115], v[92:93]
	v_lshl_add_u64 v[110:111], v[140:141], 0, v[104:105]
	v_pk_add_f32 v[92:93], v[94:95], v[92:93] op_sel_hi:[0,1]
	v_lshl_add_u64 v[104:105], v[142:143], 0, v[104:105]
	v_mul_f32_e32 v134, v113, v113
	v_pk_fma_f32 v[92:93], v[112:113], v[112:113], v[92:93]
	v_add_f32_e32 v118, v201, v109
	v_lshlrev_b32_e32 v108, 16, v95
	v_and_b32_e32 v109, 0xffff0000, v95
	v_pk_add_f32 v[164:165], v[134:135], v[92:93] op_sel_hi:[0,1]
	v_mul_f32_e32 v162, v109, v109
	v_mov_b32_e32 v122, v118
	s_nop 1
	v_permlane16_swap_b32_e32 v118, v122
	s_waitcnt vmcnt(1)
	v_pk_fma_f32 v[84:85], v[124:125], v[100:101], v[84:85]
	v_pk_fma_f32 v[86:87], v[88:89], v[102:103], v[86:87]
	s_waitcnt vmcnt(0)
	v_pk_fma_f32 v[80:81], v[126:127], v[96:97], v[80:81]
	v_pk_fma_f32 v[82:83], v[90:91], v[98:99], v[82:83]
	v_cvt_pk_bf16_f32 v100, v84, v85
	v_cvt_pk_bf16_f32 v101, v86, v87
	v_cvt_pk_bf16_f32 v102, v80, v81
	v_cvt_pk_bf16_f32 v103, v82, v83
	global_store_dwordx4 v[106:107], v[100:103], off offset:1024
	global_load_dwordx4 v[84:87], v[104:105], off offset:16
	global_load_dwordx4 v[92:95], v[104:105], off
	global_load_dwordx4 v[80:83], v[110:111], off offset:16
	global_load_dwordx4 v[88:91], v[110:111], off
	v_pk_fma_f32 v[96:97], v[108:109], v[108:109], v[164:165]
	v_lshlrev_b32_e32 v98, 16, v101
	v_pk_add_f32 v[106:107], v[162:163], v[96:97] op_sel_hi:[0,1]
	v_lshlrev_b32_e32 v96, 16, v100
	v_and_b32_e32 v97, 0xffff0000, v100
	v_pk_fma_f32 v[106:107], v[96:97], v[96:97], v[106:107]
	v_mul_f32_e32 v124, v97, v97
	v_and_b32_e32 v99, 0xffff0000, v101
	v_pk_add_f32 v[106:107], v[124:125], v[106:107] op_sel_hi:[0,1]
	v_mul_f32_e32 v126, v99, v99
	v_pk_fma_f32 v[106:107], v[98:99], v[98:99], v[106:107]
	v_lshlrev_b32_e32 v100, 16, v102
	v_and_b32_e32 v101, 0xffff0000, v102
	v_pk_add_f32 v[106:107], v[126:127], v[106:107] op_sel_hi:[0,1]
	v_mul_f32_e32 v134, v101, v101
	v_pk_fma_f32 v[106:107], v[100:101], v[100:101], v[106:107]
	v_lshlrev_b32_e32 v102, 16, v103
	v_and_b32_e32 v103, 0xffff0000, v103
	v_pk_add_f32 v[106:107], v[134:135], v[106:107] op_sel_hi:[0,1]
	v_mul_f32_e32 v162, v103, v103
	v_pk_fma_f32 v[106:107], v[102:103], v[102:103], v[106:107]
	s_waitcnt vmcnt(3)
	v_pk_add_f32 v[84:85], v[84:85], 1.0 op_sel_hi:[1,0]
	v_pk_add_f32 v[106:107], v[162:163], v[106:107] op_sel_hi:[0,1]
	v_mov_b32_e32 v107, v106
	s_nop 1
	v_permlane32_swap_b32_e32 v106, v107
	v_add_f32_e32 v119, v106, v107
	v_mov_b32_e32 v123, v119
	s_nop 1
	v_permlane16_swap_b32_e32 v119, v123
	v_pk_add_f32 v[106:107], v[118:119], v[122:123]
	s_nop 1
	v_mov_b32_dpp v119, v107 row_ror:8 row_mask:0xf bank_mask:0xf
	s_nop 1
	v_mov_b32_dpp v118, v106 row_ror:8 row_mask:0xf bank_mask:0xf
	s_waitcnt vmcnt(2)
	v_pk_add_f32 v[94:95], v[94:95], 1.0 op_sel_hi:[1,0]
	v_pk_add_f32 v[92:93], v[92:93], 1.0 op_sel_hi:[1,0]
	v_pk_add_f32 v[86:87], v[86:87], 1.0 op_sel_hi:[1,0]
	s_waitcnt lgkmcnt(0)
	v_pk_add_f32 v[106:107], v[106:107], v[118:119]
	s_nop 1
	v_mov_b32_dpp v119, v107 row_ror:4 row_mask:0xf bank_mask:0xf
	s_nop 1
	v_mov_b32_dpp v118, v106 row_ror:4 row_mask:0xf bank_mask:0xf
	s_waitcnt lgkmcnt(0)
	v_pk_add_f32 v[106:107], v[106:107], v[118:119]
	s_nop 1
	v_mov_b32_dpp v119, v107 row_ror:2 row_mask:0xf bank_mask:0xf
	s_nop 1
	v_mov_b32_dpp v118, v106 row_ror:2 row_mask:0xf bank_mask:0xf
	s_waitcnt lgkmcnt(0)
	v_pk_add_f32 v[106:107], v[106:107], v[118:119]
	s_nop 1
	v_mov_b32_dpp v119, v107 row_ror:1 row_mask:0xf bank_mask:0xf
	s_nop 1
	v_mov_b32_dpp v118, v106 row_ror:1 row_mask:0xf bank_mask:0xf
	s_waitcnt lgkmcnt(0)
	v_pk_add_f32 v[106:107], v[106:107], v[118:119]
	s_nop 0
	v_pk_fma_f32 v[106:107], v[106:107], s[62:63], v[120:121] op_sel_hi:[1,0,0]
	s_nop 0
	v_mul_f32_e32 v118, 0x4b800000, v107
	v_cmp_gt_f32_e32 vcc, s67, v107
	s_nop 1
	v_cndmask_b32_e32 v107, v107, v118, vcc
	v_rsq_f32_e32 v107, v107
	v_lshl_add_u64 v[118:119], v[146:147], 0, v[160:161]
	v_mul_f32_e32 v122, 0x45800000, v107
	v_cndmask_b32_e32 v122, v107, v122, vcc
	v_pk_mul_f32 v[116:117], v[122:123], v[116:117] op_sel_hi:[0,1]
	v_pk_mul_f32 v[114:115], v[122:123], v[114:115] op_sel_hi:[0,1]
	v_pk_mul_f32 v[112:113], v[122:123], v[112:113] op_sel_hi:[0,1]
	v_pk_mul_f32 v[108:109], v[122:123], v[108:109] op_sel_hi:[0,1]
	v_pk_mul_f32 v[116:117], v[12:13], v[116:117]
	v_pk_mul_f32 v[114:115], v[14:15], v[114:115]
	v_pk_mul_f32 v[112:113], v[8:9], v[112:113]
	v_pk_mul_f32 v[108:109], v[10:11], v[108:109]
	s_waitcnt vmcnt(0)
	v_pk_fma_f32 v[88:89], v[92:93], v[116:117], v[88:89]
	v_pk_fma_f32 v[90:91], v[114:115], v[94:95], v[90:91]
	v_pk_fma_f32 v[84:85], v[112:113], v[84:85], v[80:81]
	v_pk_fma_f32 v[86:87], v[108:109], v[86:87], v[82:83]
	v_cvt_pk_bf16_f32 v80, v88, v89
	v_cvt_pk_bf16_f32 v81, v90, v91
	v_cvt_pk_bf16_f32 v82, v84, v85
	v_cvt_pk_bf16_f32 v83, v86, v87
	global_store_dwordx4 v[118:119], v[80:83], off
	global_load_dwordx4 v[82:85], v[104:105], off offset:2048
	s_nop 0
	global_load_dwordx4 v[88:91], v[104:105], off offset:2064
	global_load_dwordx4 v[92:95], v[110:111], off offset:2048
	s_nop 0
	global_load_dwordx4 v[108:111], v[110:111], off offset:2064
	v_add_u32_e32 v104, s66, v158
	v_ashrrev_i32_e32 v80, 31, v104
	v_lshrrev_b32_e32 v80, 20, v80
	v_add_u32_e32 v80, v104, v80
	v_pk_mul_f32 v[96:97], v[122:123], v[96:97] op_sel_hi:[0,1]
	v_pk_mul_f32 v[98:99], v[122:123], v[98:99] op_sel_hi:[0,1]
	v_pk_mul_f32 v[100:101], v[122:123], v[100:101] op_sel_hi:[0,1]
	v_pk_mul_f32 v[102:103], v[122:123], v[102:103] op_sel_hi:[0,1]
	v_ashrrev_i32_e32 v80, 12, v80
	v_pk_mul_f32 v[96:97], v[28:29], v[96:97]
	v_pk_mul_f32 v[98:99], v[30:31], v[98:99]
	v_pk_mul_f32 v[100:101], v[24:25], v[100:101]
	v_pk_mul_f32 v[102:103], v[26:27], v[102:103]
	v_mul_hi_i32_i24_e32 v81, 0x1800, v80
	v_mul_i32_i24_e32 v80, 0x1800, v80
	v_lshlrev_b64 v[80:81], 2, v[80:81]
	v_lshl_add_u64 v[86:87], v[138:139], 0, v[80:81]
	v_cmp_gt_f32_e32 vcc, s67, v106
	s_waitcnt vmcnt(3)
	v_pk_add_f32 v[82:83], v[82:83], 1.0 op_sel_hi:[1,0]
	v_pk_add_f32 v[84:85], v[84:85], 1.0 op_sel_hi:[1,0]
	s_waitcnt vmcnt(2)
	v_pk_add_f32 v[88:89], v[88:89], 1.0 op_sel_hi:[1,0]
	v_pk_add_f32 v[90:91], v[90:91], 1.0 op_sel_hi:[1,0]
	s_waitcnt vmcnt(1)
	v_pk_fma_f32 v[82:83], v[96:97], v[82:83], v[92:93]
	v_pk_fma_f32 v[84:85], v[98:99], v[84:85], v[94:95]
	s_waitcnt vmcnt(0)
	v_pk_fma_f32 v[88:89], v[100:101], v[88:89], v[108:109]
	v_pk_fma_f32 v[90:91], v[102:103], v[90:91], v[110:111]
	v_cvt_pk_bf16_f32 v82, v82, v83
	v_cvt_pk_bf16_f32 v83, v84, v85
	v_cvt_pk_bf16_f32 v84, v88, v89
	v_cvt_pk_bf16_f32 v85, v90, v91
	global_store_dwordx4 v[118:119], v[82:85], off offset:1024
	global_load_dwordx4 v[88:91], v[86:87], off
	global_load_dwordx4 v[92:95], v[86:87], off offset:16
	v_lshlrev_b32_e32 v98, 16, v78
	v_and_b32_e32 v99, 0xffff0000, v78
	v_mul_f32_e32 v78, 0x4b800000, v106
	v_cndmask_b32_e32 v78, v106, v78, vcc
	v_rsq_f32_e32 v84, v78
	v_lshlrev_b32_e32 v96, 16, v76
	v_and_b32_e32 v97, 0xffff0000, v76
	v_lshlrev_b32_e32 v76, 16, v77
	v_mul_f32_e32 v85, 0x45800000, v84
	v_and_b32_e32 v77, 0xffff0000, v77
	v_lshlrev_b32_e32 v78, 16, v79
	v_and_b32_e32 v79, 0xffff0000, v79
	v_cndmask_b32_e32 v84, v84, v85, vcc
	v_pk_mul_f32 v[96:97], v[84:85], v[96:97] op_sel_hi:[0,1]
	v_pk_mul_f32 v[76:77], v[84:85], v[76:77] op_sel_hi:[0,1]
	v_pk_mul_f32 v[98:99], v[84:85], v[98:99] op_sel_hi:[0,1]
	v_pk_mul_f32 v[78:79], v[84:85], v[78:79] op_sel_hi:[0,1]
	v_pk_mul_f32 v[96:97], v[4:5], v[96:97]
	v_pk_mul_f32 v[76:77], v[6:7], v[76:77]
	v_pk_mul_f32 v[98:99], v[0:1], v[98:99]
	v_pk_mul_f32 v[78:79], v[2:3], v[78:79]
	v_lshl_add_u64 v[82:83], v[144:145], 0, v[156:157]
	v_mov_b32_e32 v85, v159
	s_nop 1
	v_permlane32_swap_b32_e32 v159, v85
	s_waitcnt vmcnt(1)
	v_pk_fma_f32 v[72:73], v[88:89], v[96:97], v[72:73]
	v_pk_fma_f32 v[74:75], v[90:91], v[76:77], v[74:75]
	s_waitcnt vmcnt(0)
	v_pk_fma_f32 v[76:77], v[92:93], v[98:99], v[68:69]
	v_pk_fma_f32 v[78:79], v[94:95], v[78:79], v[70:71]
	v_cvt_pk_bf16_f32 v68, v72, v73
	v_cvt_pk_bf16_f32 v69, v74, v75
	v_cvt_pk_bf16_f32 v70, v76, v77
	v_cvt_pk_bf16_f32 v71, v78, v79
	global_store_dwordx4 v[82:83], v[68:71], off
	global_load_dwordx4 v[76:79], v[86:87], off offset:2048
	global_load_dwordx4 v[72:75], v[86:87], off offset:2064
	v_lshlrev_b32_e32 v88, 16, v64
	v_and_b32_e32 v89, 0xffff0000, v64
	v_lshlrev_b32_e32 v64, 16, v65
	v_and_b32_e32 v65, 0xffff0000, v65
	v_lshlrev_b32_e32 v90, 16, v66
	v_and_b32_e32 v91, 0xffff0000, v66
	v_lshlrev_b32_e32 v66, 16, v67
	v_and_b32_e32 v67, 0xffff0000, v67
	v_and_b32_e32 v93, 0xffff0000, v68
	v_pk_mul_f32 v[88:89], v[84:85], v[88:89] op_sel_hi:[0,1]
	v_pk_mul_f32 v[64:65], v[84:85], v[64:65] op_sel_hi:[0,1]
	v_pk_mul_f32 v[90:91], v[84:85], v[90:91] op_sel_hi:[0,1]
	v_pk_mul_f32 v[66:67], v[84:85], v[66:67] op_sel_hi:[0,1]
	v_lshlrev_b32_e32 v92, 16, v68
	v_mul_f32_e32 v68, v93, v93
	v_pk_mul_f32 v[98:99], v[20:21], v[88:89]
	v_pk_mul_f32 v[64:65], v[22:23], v[64:65]
	v_pk_mul_f32 v[100:101], v[16:17], v[90:91]
	v_pk_mul_f32 v[66:67], v[18:19], v[66:67]
	v_lshlrev_b32_e32 v90, 16, v69
	v_and_b32_e32 v91, 0xffff0000, v69
	v_pk_fma_f32 v[68:69], v[92:93], v[92:93], v[68:69] op_sel_hi:[1,1,0]
	v_lshlrev_b32_e32 v88, 16, v70
	v_and_b32_e32 v89, 0xffff0000, v70
	v_mul_f32_e32 v70, v91, v91
	v_pk_fma_f32 v[68:69], v[90:91], v[90:91], v[68:69]
	v_lshl_add_u64 v[86:87], v[140:141], 0, v[80:81]
	v_pk_add_f32 v[68:69], v[70:71], v[68:69] op_sel_hi:[0,1]
	v_lshl_add_u64 v[80:81], v[142:143], 0, v[80:81]
	v_mul_f32_e32 v102, v89, v89
	v_pk_fma_f32 v[68:69], v[88:89], v[88:89], v[68:69]
	v_add_f32_e32 v94, v159, v85
	v_lshlrev_b32_e32 v84, 16, v71
	v_and_b32_e32 v85, 0xffff0000, v71
	v_pk_add_f32 v[102:103], v[102:103], v[68:69] op_sel_hi:[0,1]
	v_mul_f32_e32 v106, v85, v85
	v_mov_b32_e32 v96, v94
	s_nop 1
	v_permlane16_swap_b32_e32 v94, v96
	s_waitcnt vmcnt(1)
	v_pk_fma_f32 v[60:61], v[98:99], v[76:77], v[60:61]
	v_pk_fma_f32 v[62:63], v[64:65], v[78:79], v[62:63]
	s_waitcnt vmcnt(0)
	v_pk_fma_f32 v[56:57], v[100:101], v[72:73], v[56:57]
	v_pk_fma_f32 v[58:59], v[66:67], v[74:75], v[58:59]
	v_cvt_pk_bf16_f32 v76, v60, v61
	v_cvt_pk_bf16_f32 v77, v62, v63
	v_cvt_pk_bf16_f32 v78, v56, v57
	v_cvt_pk_bf16_f32 v79, v58, v59
	global_store_dwordx4 v[82:83], v[76:79], off offset:1024
	global_load_dwordx4 v[60:63], v[80:81], off offset:16
	global_load_dwordx4 v[68:71], v[80:81], off
	global_load_dwordx4 v[56:59], v[86:87], off offset:16
	global_load_dwordx4 v[64:67], v[86:87], off
	v_pk_fma_f32 v[72:73], v[84:85], v[84:85], v[102:103]
	v_lshlrev_b32_e32 v74, 16, v77
	v_pk_add_f32 v[82:83], v[106:107], v[72:73] op_sel_hi:[0,1]
	v_lshlrev_b32_e32 v72, 16, v76
	v_and_b32_e32 v73, 0xffff0000, v76
	v_pk_fma_f32 v[82:83], v[72:73], v[72:73], v[82:83]
	v_mul_f32_e32 v98, v73, v73
	v_and_b32_e32 v75, 0xffff0000, v77
	v_pk_add_f32 v[82:83], v[98:99], v[82:83] op_sel_hi:[0,1]
	v_mul_f32_e32 v100, v75, v75
	v_pk_fma_f32 v[82:83], v[74:75], v[74:75], v[82:83]
	v_lshlrev_b32_e32 v76, 16, v78
	v_and_b32_e32 v77, 0xffff0000, v78
	v_pk_add_f32 v[82:83], v[100:101], v[82:83] op_sel_hi:[0,1]
	v_mul_f32_e32 v102, v77, v77
	v_pk_fma_f32 v[82:83], v[76:77], v[76:77], v[82:83]
	v_lshlrev_b32_e32 v78, 16, v79
	v_and_b32_e32 v79, 0xffff0000, v79
	v_pk_add_f32 v[82:83], v[102:103], v[82:83] op_sel_hi:[0,1]
	v_mul_f32_e32 v106, v79, v79
	v_pk_fma_f32 v[82:83], v[78:79], v[78:79], v[82:83]
	s_waitcnt vmcnt(3)
	v_pk_add_f32 v[60:61], v[60:61], 1.0 op_sel_hi:[1,0]
	v_pk_add_f32 v[82:83], v[106:107], v[82:83] op_sel_hi:[0,1]
	v_mov_b32_e32 v83, v82
	s_nop 1
	v_permlane32_swap_b32_e32 v82, v83
	v_add_f32_e32 v95, v82, v83
	v_mov_b32_e32 v97, v95
	s_nop 1
	v_permlane16_swap_b32_e32 v95, v97
	v_pk_add_f32 v[82:83], v[94:95], v[96:97]
	s_nop 1
	v_mov_b32_dpp v95, v83 row_ror:8 row_mask:0xf bank_mask:0xf
	s_nop 1
	v_mov_b32_dpp v94, v82 row_ror:8 row_mask:0xf bank_mask:0xf
	s_waitcnt vmcnt(2)
	v_pk_add_f32 v[70:71], v[70:71], 1.0 op_sel_hi:[1,0]
	v_pk_add_f32 v[68:69], v[68:69], 1.0 op_sel_hi:[1,0]
	v_pk_add_f32 v[62:63], v[62:63], 1.0 op_sel_hi:[1,0]
	s_waitcnt lgkmcnt(0)
	v_pk_add_f32 v[82:83], v[82:83], v[94:95]
	s_nop 1
	v_mov_b32_dpp v95, v83 row_ror:4 row_mask:0xf bank_mask:0xf
	s_nop 1
	v_mov_b32_dpp v94, v82 row_ror:4 row_mask:0xf bank_mask:0xf
	s_waitcnt lgkmcnt(0)
	v_pk_add_f32 v[82:83], v[82:83], v[94:95]
	s_nop 1
	v_mov_b32_dpp v95, v83 row_ror:2 row_mask:0xf bank_mask:0xf
	s_nop 1
	v_mov_b32_dpp v94, v82 row_ror:2 row_mask:0xf bank_mask:0xf
	s_waitcnt lgkmcnt(0)
	v_pk_add_f32 v[82:83], v[82:83], v[94:95]
	s_nop 1
	v_mov_b32_dpp v95, v83 row_ror:1 row_mask:0xf bank_mask:0xf
	s_nop 1
	v_mov_b32_dpp v94, v82 row_ror:1 row_mask:0xf bank_mask:0xf
	s_waitcnt lgkmcnt(0)
	v_pk_add_f32 v[82:83], v[82:83], v[94:95]
	s_nop 0
	v_pk_fma_f32 v[82:83], v[82:83], s[62:63], v[120:121] op_sel_hi:[1,0,0]
	s_nop 0
	v_mul_f32_e32 v94, 0x4b800000, v83
	v_cmp_gt_f32_e32 vcc, s67, v83
	s_nop 1
	v_cndmask_b32_e32 v83, v83, v94, vcc
	v_rsq_f32_e32 v83, v83
	v_lshl_add_u64 v[94:95], v[146:147], 0, v[156:157]
	v_mul_f32_e32 v96, 0x45800000, v83
	v_cndmask_b32_e32 v100, v83, v96, vcc
	v_pk_mul_f32 v[92:93], v[100:101], v[92:93] op_sel_hi:[0,1]
	v_pk_mul_f32 v[90:91], v[100:101], v[90:91] op_sel_hi:[0,1]
	v_pk_mul_f32 v[88:89], v[100:101], v[88:89] op_sel_hi:[0,1]
	v_pk_mul_f32 v[84:85], v[100:101], v[84:85] op_sel_hi:[0,1]
	v_pk_mul_f32 v[92:93], v[12:13], v[92:93]
	v_pk_mul_f32 v[90:91], v[14:15], v[90:91]
	v_pk_mul_f32 v[88:89], v[8:9], v[88:89]
	v_pk_mul_f32 v[84:85], v[10:11], v[84:85]
	s_waitcnt vmcnt(0)
	v_pk_fma_f32 v[64:65], v[68:69], v[92:93], v[64:65]
	v_pk_fma_f32 v[66:67], v[90:91], v[70:71], v[66:67]
	v_pk_fma_f32 v[60:61], v[88:89], v[60:61], v[56:57]
	v_pk_fma_f32 v[62:63], v[84:85], v[62:63], v[58:59]
	v_cvt_pk_bf16_f32 v56, v64, v65
	v_cvt_pk_bf16_f32 v57, v66, v67
	v_cvt_pk_bf16_f32 v58, v60, v61
	v_cvt_pk_bf16_f32 v59, v62, v63
	global_store_dwordx4 v[94:95], v[56:59], off
	global_load_dwordx4 v[66:69], v[80:81], off offset:2048
	global_load_dwordx4 v[88:91], v[80:81], off offset:2064
	global_load_dwordx4 v[96:99], v[86:87], off offset:2048
	s_nop 0
	global_load_dwordx4 v[84:87], v[86:87], off offset:2064
	v_add_u32_e32 v64, s66, v104
	v_ashrrev_i32_e32 v56, 31, v64
	v_lshrrev_b32_e32 v56, 20, v56
	v_add_u32_e32 v56, v64, v56
	v_pk_mul_f32 v[58:59], v[100:101], v[72:73] op_sel_hi:[0,1]
	v_pk_mul_f32 v[62:63], v[100:101], v[74:75] op_sel_hi:[0,1]
	v_pk_mul_f32 v[70:71], v[100:101], v[76:77] op_sel_hi:[0,1]
	v_pk_mul_f32 v[72:73], v[100:101], v[78:79] op_sel_hi:[0,1]
	v_ashrrev_i32_e32 v56, 12, v56
	v_pk_mul_f32 v[58:59], v[28:29], v[58:59]
	v_pk_mul_f32 v[62:63], v[30:31], v[62:63]
	v_pk_mul_f32 v[70:71], v[24:25], v[70:71]
	v_pk_mul_f32 v[72:73], v[26:27], v[72:73]
	v_mul_hi_i32_i24_e32 v57, 0x1800, v56
	v_mul_i32_i24_e32 v56, 0x1800, v56
	v_lshlrev_b64 v[56:57], 2, v[56:57]
	v_lshl_add_u64 v[60:61], v[138:139], 0, v[56:57]
	v_cmp_gt_f32_e32 vcc, s67, v82
	v_add_u32_e32 v164, s66, v64
	s_waitcnt vmcnt(3)
	v_pk_add_f32 v[66:67], v[66:67], 1.0 op_sel_hi:[1,0]
	v_pk_add_f32 v[68:69], v[68:69], 1.0 op_sel_hi:[1,0]
	s_waitcnt vmcnt(2)
	v_pk_add_f32 v[74:75], v[88:89], 1.0 op_sel_hi:[1,0]
	v_pk_add_f32 v[76:77], v[90:91], 1.0 op_sel_hi:[1,0]
	s_waitcnt vmcnt(1)
	v_pk_fma_f32 v[58:59], v[58:59], v[66:67], v[96:97]
	v_pk_fma_f32 v[62:63], v[62:63], v[68:69], v[98:99]
	s_waitcnt vmcnt(0)
	v_pk_fma_f32 v[68:69], v[70:71], v[74:75], v[84:85]
	v_pk_fma_f32 v[70:71], v[72:73], v[76:77], v[86:87]
	v_cvt_pk_bf16_f32 v66, v58, v59
	v_cvt_pk_bf16_f32 v67, v62, v63
	v_cvt_pk_bf16_f32 v68, v68, v69
	v_cvt_pk_bf16_f32 v69, v70, v71
	global_store_dwordx4 v[94:95], v[66:69], off offset:1024
	global_load_dwordx4 v[66:69], v[60:61], off
	s_nop 0
	global_load_dwordx4 v[70:73], v[60:61], off offset:16
	v_lshlrev_b32_e32 v76, 16, v54
	v_and_b32_e32 v77, 0xffff0000, v54
	v_mul_f32_e32 v54, 0x4b800000, v82
	v_cndmask_b32_e32 v54, v82, v54, vcc
	v_rsq_f32_e32 v62, v54
	v_lshlrev_b32_e32 v74, 16, v52
	v_and_b32_e32 v75, 0xffff0000, v52
	v_lshlrev_b32_e32 v52, 16, v53
	v_mul_f32_e32 v63, 0x45800000, v62
	v_and_b32_e32 v53, 0xffff0000, v53
	v_lshlrev_b32_e32 v54, 16, v55
	v_and_b32_e32 v55, 0xffff0000, v55
	v_cndmask_b32_e32 v62, v62, v63, vcc
	v_pk_mul_f32 v[74:75], v[62:63], v[74:75] op_sel_hi:[0,1]
	v_pk_mul_f32 v[52:53], v[62:63], v[52:53] op_sel_hi:[0,1]
	v_pk_mul_f32 v[76:77], v[62:63], v[76:77] op_sel_hi:[0,1]
	v_pk_mul_f32 v[54:55], v[62:63], v[54:55] op_sel_hi:[0,1]
	v_pk_mul_f32 v[74:75], v[4:5], v[74:75]
	v_pk_mul_f32 v[52:53], v[6:7], v[52:53]
	v_pk_mul_f32 v[76:77], v[0:1], v[76:77]
	v_pk_mul_f32 v[54:55], v[2:3], v[54:55]
	v_lshl_add_u64 v[58:59], v[144:145], 0, v[154:155]
	s_waitcnt vmcnt(1)
	v_pk_fma_f32 v[48:49], v[66:67], v[74:75], v[48:49]
	v_pk_fma_f32 v[50:51], v[68:69], v[52:53], v[50:51]
	s_waitcnt vmcnt(0)
	v_pk_fma_f32 v[52:53], v[70:71], v[76:77], v[44:45]
	v_pk_fma_f32 v[54:55], v[72:73], v[54:55], v[46:47]
	v_cvt_pk_bf16_f32 v44, v48, v49
	v_cvt_pk_bf16_f32 v45, v50, v51
	v_cvt_pk_bf16_f32 v46, v52, v53
	v_cvt_pk_bf16_f32 v47, v54, v55
	global_store_dwordx4 v[58:59], v[44:47], off
	global_load_dwordx4 v[52:55], v[60:61], off offset:2048
	global_load_dwordx4 v[48:51], v[60:61], off offset:2064
	v_lshlrev_b32_e32 v60, 16, v40
	v_and_b32_e32 v61, 0xffff0000, v40
	v_lshlrev_b32_e32 v66, 16, v41
	v_and_b32_e32 v67, 0xffff0000, v41
	v_lshlrev_b32_e32 v68, 16, v42
	v_and_b32_e32 v69, 0xffff0000, v42
	v_lshlrev_b32_e32 v70, 16, v43
	v_and_b32_e32 v71, 0xffff0000, v43
	v_lshl_add_u64 v[40:41], v[140:141], 0, v[56:57]
	v_lshl_add_u64 v[42:43], v[142:143], 0, v[56:57]
	v_pk_mul_f32 v[56:57], v[62:63], v[60:61] op_sel_hi:[0,1]
	v_pk_mul_f32 v[60:61], v[62:63], v[66:67] op_sel_hi:[0,1]
	v_pk_mul_f32 v[66:67], v[62:63], v[68:69] op_sel_hi:[0,1]
	v_pk_mul_f32 v[62:63], v[62:63], v[70:71] op_sel_hi:[0,1]
	v_pk_mul_f32 v[68:69], v[20:21], v[56:57]
	v_pk_mul_f32 v[70:71], v[22:23], v[60:61]
	v_pk_mul_f32 v[66:67], v[16:17], v[66:67]
	v_pk_mul_f32 v[72:73], v[18:19], v[62:63]
	v_and_b32_e32 v63, 0xffff0000, v44
	v_lshlrev_b32_e32 v62, 16, v44
	v_lshlrev_b32_e32 v56, 16, v46
	v_and_b32_e32 v57, 0xffff0000, v46
	v_mul_f32_e32 v46, v63, v63
	v_lshlrev_b32_e32 v60, 16, v45
	v_and_b32_e32 v61, 0xffff0000, v45
	v_lshlrev_b32_e32 v44, 16, v47
	v_and_b32_e32 v45, 0xffff0000, v47
	v_pk_fma_f32 v[80:81], v[62:63], v[62:63], v[46:47] op_sel_hi:[1,1,0]
	v_mul_f32_e32 v74, v61, v61
	v_mul_f32_e32 v76, v57, v57
	v_mul_f32_e32 v78, v45, v45
	s_waitcnt vmcnt(1)
	v_pk_fma_f32 v[36:37], v[68:69], v[52:53], v[36:37]
	v_pk_fma_f32 v[38:39], v[70:71], v[54:55], v[38:39]
	s_waitcnt vmcnt(0)
	v_pk_fma_f32 v[32:33], v[66:67], v[48:49], v[32:33]
	v_pk_fma_f32 v[34:35], v[72:73], v[50:51], v[34:35]
	v_cvt_pk_bf16_f32 v46, v36, v37
	v_cvt_pk_bf16_f32 v47, v38, v39
	v_cvt_pk_bf16_f32 v48, v32, v33
	v_cvt_pk_bf16_f32 v49, v34, v35
	global_store_dwordx4 v[58:59], v[46:49], off offset:1024
	global_load_dwordx4 v[50:53], v[42:43], off offset:16
	global_load_dwordx4 v[66:69], v[42:43], off
	global_load_dwordx4 v[32:35], v[40:41], off offset:16
	global_load_dwordx4 v[70:73], v[40:41], off
	v_pk_fma_f32 v[36:37], v[60:61], v[60:61], v[80:81]
	v_lshlrev_b32_e32 v38, 16, v47
	v_pk_add_f32 v[36:37], v[74:75], v[36:37] op_sel_hi:[0,1]
	v_pk_fma_f32 v[36:37], v[56:57], v[56:57], v[36:37]
	v_and_b32_e32 v39, 0xffff0000, v47
	v_pk_add_f32 v[36:37], v[76:77], v[36:37] op_sel_hi:[0,1]
	v_pk_fma_f32 v[36:37], v[44:45], v[44:45], v[36:37]
	v_mul_f32_e32 v74, v39, v39
	v_pk_add_f32 v[54:55], v[78:79], v[36:37] op_sel_hi:[0,1]
	v_lshlrev_b32_e32 v36, 16, v46
	v_and_b32_e32 v37, 0xffff0000, v46
	v_pk_fma_f32 v[54:55], v[36:37], v[36:37], v[54:55]
	v_mul_f32_e32 v58, v37, v37
	v_pk_add_f32 v[54:55], v[58:59], v[54:55] op_sel_hi:[0,1]
	v_pk_fma_f32 v[54:55], v[38:39], v[38:39], v[54:55]
	v_lshlrev_b32_e32 v46, 16, v48
	v_and_b32_e32 v47, 0xffff0000, v48
	v_pk_add_f32 v[54:55], v[74:75], v[54:55] op_sel_hi:[0,1]
	v_mul_f32_e32 v76, v47, v47
	v_pk_fma_f32 v[54:55], v[46:47], v[46:47], v[54:55]
	v_lshlrev_b32_e32 v48, 16, v49
	v_and_b32_e32 v49, 0xffff0000, v49
	v_pk_add_f32 v[54:55], v[76:77], v[54:55] op_sel_hi:[0,1]
	v_mul_f32_e32 v78, v49, v49
	v_pk_fma_f32 v[54:55], v[48:49], v[48:49], v[54:55]
	v_lshl_add_u64 v[58:59], v[146:147], 0, v[154:155]
	v_pk_add_f32 v[54:55], v[78:79], v[54:55] op_sel_hi:[0,1]
	v_mov_b32_e32 v55, v54
	s_nop 1
	v_permlane32_swap_b32_e32 v54, v55
	v_add_f32_e32 v54, v54, v55
	v_mov_b32_e32 v55, v54
	s_nop 1
	v_permlane16_swap_b32_e32 v54, v55
	v_add_f32_e32 v54, v54, v55
	s_nop 1
	v_mov_b32_dpp v55, v54 row_ror:8 row_mask:0xf bank_mask:0xf
	s_waitcnt lgkmcnt(0)
	v_add_f32_e32 v54, v54, v55
	s_nop 1
	v_mov_b32_dpp v55, v54 row_ror:4 row_mask:0xf bank_mask:0xf
	s_waitcnt lgkmcnt(0)
	v_add_f32_e32 v54, v54, v55
	s_nop 1
	v_mov_b32_dpp v55, v54 row_ror:2 row_mask:0xf bank_mask:0xf
	s_waitcnt lgkmcnt(0)
	v_add_f32_e32 v54, v54, v55
	s_nop 1
	v_mov_b32_dpp v55, v54 row_ror:1 row_mask:0xf bank_mask:0xf
	s_waitcnt lgkmcnt(0)
	v_add_f32_e32 v54, v54, v55
	v_fmamk_f32 v54, v54, 0x3a800000, v188
	v_mul_f32_e32 v55, 0x4b800000, v54
	v_cmp_gt_f32_e32 vcc, s67, v54
	s_waitcnt vmcnt(3)
	v_pk_add_f32 v[50:51], v[50:51], 1.0 op_sel_hi:[1,0]
	v_cndmask_b32_e32 v54, v54, v55, vcc
	v_rsq_f32_e32 v54, v54
	s_waitcnt vmcnt(2)
	v_pk_add_f32 v[66:67], v[66:67], 1.0 op_sel_hi:[1,0]
	v_pk_add_f32 v[52:53], v[52:53], 1.0 op_sel_hi:[1,0]
	v_mul_f32_e32 v55, 0x45800000, v54
	v_cndmask_b32_e32 v74, v54, v55, vcc
	v_pk_mul_f32 v[54:55], v[74:75], v[62:63] op_sel_hi:[0,1]
	v_pk_mul_f32 v[60:61], v[74:75], v[60:61] op_sel_hi:[0,1]
	v_pk_mul_f32 v[56:57], v[74:75], v[56:57] op_sel_hi:[0,1]
	v_pk_mul_f32 v[44:45], v[74:75], v[44:45] op_sel_hi:[0,1]
	v_pk_mul_f32 v[54:55], v[12:13], v[54:55]
	v_pk_mul_f32 v[60:61], v[14:15], v[60:61]
	v_pk_mul_f32 v[56:57], v[8:9], v[56:57]
	v_pk_mul_f32 v[44:45], v[10:11], v[44:45]
	v_pk_add_f32 v[62:63], v[68:69], 1.0 op_sel_hi:[1,0]
	s_waitcnt vmcnt(0)
	v_pk_fma_f32 v[54:55], v[66:67], v[54:55], v[70:71]
	v_pk_fma_f32 v[60:61], v[60:61], v[62:63], v[72:73]
	v_pk_fma_f32 v[50:51], v[56:57], v[50:51], v[32:33]
	v_pk_fma_f32 v[44:45], v[44:45], v[52:53], v[34:35]
	v_cvt_pk_bf16_f32 v32, v54, v55
	v_cvt_pk_bf16_f32 v33, v60, v61
	v_cvt_pk_bf16_f32 v34, v50, v51
	v_cvt_pk_bf16_f32 v35, v44, v45
	global_store_dwordx4 v[58:59], v[32:35], off
	global_load_dwordx4 v[32:35], v[42:43], off offset:2048
	s_nop 0
	global_load_dwordx4 v[42:45], v[42:43], off offset:2064
	s_nop 0
	global_load_dwordx4 v[50:53], v[40:41], off offset:2048
	global_load_dwordx4 v[54:57], v[40:41], off offset:2064
	v_pk_mul_f32 v[36:37], v[74:75], v[36:37] op_sel_hi:[0,1]
	v_pk_mul_f32 v[38:39], v[74:75], v[38:39] op_sel_hi:[0,1]
	v_pk_mul_f32 v[40:41], v[74:75], v[46:47] op_sel_hi:[0,1]
	v_pk_mul_f32 v[46:47], v[74:75], v[48:49] op_sel_hi:[0,1]
	v_pk_mul_f32 v[36:37], v[28:29], v[36:37]
	v_pk_mul_f32 v[38:39], v[30:31], v[38:39]
	v_pk_mul_f32 v[40:41], v[24:25], v[40:41]
	v_pk_mul_f32 v[46:47], v[26:27], v[46:47]
	v_cmp_lt_i32_e32 vcc, s46, v164
	s_or_b64 s[12:13], vcc, s[12:13]
	s_waitcnt vmcnt(3)
	v_pk_add_f32 v[32:33], v[32:33], 1.0 op_sel_hi:[1,0]
	v_pk_add_f32 v[34:35], v[34:35], 1.0 op_sel_hi:[1,0]
	s_waitcnt vmcnt(2)
	v_pk_add_f32 v[42:43], v[42:43], 1.0 op_sel_hi:[1,0]
	v_pk_add_f32 v[44:45], v[44:45], 1.0 op_sel_hi:[1,0]
	s_waitcnt vmcnt(1)
	v_pk_fma_f32 v[32:33], v[36:37], v[32:33], v[50:51]
	v_pk_fma_f32 v[34:35], v[38:39], v[34:35], v[52:53]
	s_waitcnt vmcnt(0)
	v_pk_fma_f32 v[36:37], v[40:41], v[42:43], v[54:55]
	v_pk_fma_f32 v[38:39], v[46:47], v[44:45], v[56:57]
	v_cvt_pk_bf16_f32 v32, v32, v33
	v_cvt_pk_bf16_f32 v33, v34, v35
	v_cvt_pk_bf16_f32 v34, v36, v37
	v_cvt_pk_bf16_f32 v35, v38, v39
	global_store_dwordx4 v[58:59], v[32:35], off offset:1024
	s_andn2_b64 exec, exec, s[12:13]
	s_cbranch_execz .LBB0_2287

.LBB0_2305:
	s_waitcnt lgkmcnt(0)
	s_mov_b32 s99, 0x10000
	s_mov_b32 s100, 0x80
	s_mov_b32 s101, 0
	s_add_i32 m0, s93, 0x10000
	s_nop 0
	global_load_lds_dwordx4 v[128:129], off
	v_lshl_add_u64 v[128:129], v[128:129], 0, s[100:101]
	s_add_i32 m0, s93, 0x18000
	s_nop 0
	global_load_lds_dwordx4 v[140:141], off
	v_lshl_add_u64 v[140:141], v[140:141], 0, s[100:101]
	s_add_i32 m0, s94, 0x10000
	s_nop 0
	global_load_lds_dwordx4 v[130:131], off
	v_lshl_add_u64 v[130:131], v[130:131], 0, s[100:101]
	s_add_i32 m0, s94, 0x18000
	s_nop 0
	global_load_lds_dwordx4 v[142:143], off
	v_lshl_add_u64 v[142:143], v[142:143], 0, s[100:101]
	s_add_i32 m0, s95, 0x10000
	s_nop 0
	global_load_lds_dwordx4 v[136:137], off
	v_lshl_add_u64 v[136:137], v[136:137], 0, s[100:101]
	s_add_i32 m0, s95, 0x18000
	s_nop 0
	global_load_lds_dwordx4 v[144:145], off
	v_lshl_add_u64 v[144:145], v[144:145], 0, s[100:101]
	s_add_i32 m0, s96, 0x10000
	s_nop 0
	global_load_lds_dwordx4 v[138:139], off
	v_lshl_add_u64 v[138:139], v[138:139], 0, s[100:101]
	s_add_i32 m0, s96, 0x18000
	s_nop 0
	global_load_lds_dwordx4 v[146:147], off
	v_lshl_add_u64 v[146:147], v[146:147], 0, s[100:101]
	v_add_u32_e32 v164, v151, v150
	v_add_u32_e32 v134, v151, v148
	ds_read_b128 v[152:155], v164 offset:32768
	ds_read_b128 v[156:159], v164 offset:34816
	ds_read_b128 v[160:163], v164 offset:36864
	ds_read_b128 v[164:167], v164 offset:38912
	ds_read_b128 v[168:171], v134 offset:0
	ds_read_b128 v[172:175], v134 offset:2048
	ds_read_b128 v[176:179], v134 offset:4096
	ds_read_b128 v[180:183], v134 offset:6144
	s_mov_b32 s2, 0
.Lg_up_loop:
	ds_read_b128 v[198:201], v134 offset:8192
	ds_read_b128 v[202:205], v134 offset:10240
	ds_read_b128 v[206:209], v134 offset:12288
	ds_read_b128 v[210:213], v134 offset:14336
	s_waitcnt lgkmcnt(4)
	v_mfma_f32_16x16x32_bf16 v[124:127], v[168:171], v[152:155], v[124:127]
	v_mfma_f32_16x16x32_bf16 v[120:123], v[168:171], v[156:159], v[120:123]
	v_mfma_f32_16x16x32_bf16 v[116:119], v[168:171], v[160:163], v[116:119]
	v_mfma_f32_16x16x32_bf16 v[112:115], v[168:171], v[164:167], v[112:115]
	v_mfma_f32_16x16x32_bf16 v[108:111], v[172:175], v[152:155], v[108:111]
	v_mfma_f32_16x16x32_bf16 v[104:107], v[172:175], v[156:159], v[104:107]
	v_mfma_f32_16x16x32_bf16 v[100:103], v[172:175], v[160:163], v[100:103]
	v_mfma_f32_16x16x32_bf16 v[96:99], v[172:175], v[164:167], v[96:99]
	v_mfma_f32_16x16x32_bf16 v[92:95], v[176:179], v[152:155], v[92:95]
	v_mfma_f32_16x16x32_bf16 v[84:87], v[176:179], v[156:159], v[84:87]
	v_mfma_f32_16x16x32_bf16 v[80:83], v[176:179], v[160:163], v[80:83]
	v_mfma_f32_16x16x32_bf16 v[76:79], v[176:179], v[164:167], v[76:79]
	v_mfma_f32_16x16x32_bf16 v[72:75], v[180:183], v[152:155], v[72:75]
	v_mfma_f32_16x16x32_bf16 v[68:71], v[180:183], v[156:159], v[68:71]
	v_mfma_f32_16x16x32_bf16 v[64:67], v[180:183], v[160:163], v[64:67]
	v_mfma_f32_16x16x32_bf16 v[60:63], v[180:183], v[164:167], v[60:63]
	v_add_u32_e32 v180, v149, v150
	v_add_u32_e32 v134, v149, v148
	ds_read_b128 v[168:171], v180 offset:32768
	ds_read_b128 v[172:175], v180 offset:34816
	ds_read_b128 v[176:179], v180 offset:36864
	ds_read_b128 v[180:183], v180 offset:38912
	ds_read_b128 v[214:217], v134 offset:0
	ds_read_b128 v[218:221], v134 offset:2048
	ds_read_b128 v[222:225], v134 offset:4096
	ds_read_b128 v[226:229], v134 offset:6144
	s_waitcnt lgkmcnt(8)
	v_mfma_f32_16x16x32_bf16 v[56:59], v[198:201], v[152:155], v[56:59]
	v_mfma_f32_16x16x32_bf16 v[52:55], v[198:201], v[156:159], v[52:55]
	v_mfma_f32_16x16x32_bf16 v[48:51], v[198:201], v[160:163], v[48:51]
	v_mfma_f32_16x16x32_bf16 v[44:47], v[198:201], v[164:167], v[44:47]
	v_mfma_f32_16x16x32_bf16 v[40:43], v[202:205], v[152:155], v[40:43]
	v_mfma_f32_16x16x32_bf16 v[36:39], v[202:205], v[156:159], v[36:39]
	v_mfma_f32_16x16x32_bf16 v[32:35], v[202:205], v[160:163], v[32:35]
	v_mfma_f32_16x16x32_bf16 v[28:31], v[202:205], v[164:167], v[28:31]
	v_mfma_f32_16x16x32_bf16 v[24:27], v[206:209], v[152:155], v[24:27]
	v_mfma_f32_16x16x32_bf16 v[20:23], v[206:209], v[156:159], v[20:23]
	v_mfma_f32_16x16x32_bf16 v[16:19], v[206:209], v[160:163], v[16:19]
	v_mfma_f32_16x16x32_bf16 v[12:15], v[206:209], v[164:167], v[12:15]
	v_mfma_f32_16x16x32_bf16 v[8:11], v[210:213], v[152:155], v[8:11]
	v_mfma_f32_16x16x32_bf16 v[4:7], v[210:213], v[156:159], v[4:7]
	v_mfma_f32_16x16x32_bf16 v[0:3], v[210:213], v[160:163], v[0:3]
	v_mfma_f32_16x16x32_bf16 v[88:91], v[210:213], v[164:167], v[88:91]
	ds_read_b128 v[152:155], v134 offset:8192
	ds_read_b128 v[156:159], v134 offset:10240
	ds_read_b128 v[160:163], v134 offset:12288
	ds_read_b128 v[164:167], v134 offset:14336
	s_waitcnt lgkmcnt(4)
	v_mfma_f32_16x16x32_bf16 v[124:127], v[214:217], v[168:171], v[124:127]
	v_mfma_f32_16x16x32_bf16 v[120:123], v[214:217], v[172:175], v[120:123]
	v_mfma_f32_16x16x32_bf16 v[116:119], v[214:217], v[176:179], v[116:119]
	v_mfma_f32_16x16x32_bf16 v[112:115], v[214:217], v[180:183], v[112:115]
	v_mfma_f32_16x16x32_bf16 v[108:111], v[218:221], v[168:171], v[108:111]
	v_mfma_f32_16x16x32_bf16 v[104:107], v[218:221], v[172:175], v[104:107]
	v_mfma_f32_16x16x32_bf16 v[100:103], v[218:221], v[176:179], v[100:103]
	v_mfma_f32_16x16x32_bf16 v[96:99], v[218:221], v[180:183], v[96:99]
	v_mfma_f32_16x16x32_bf16 v[92:95], v[222:225], v[168:171], v[92:95]
	v_mfma_f32_16x16x32_bf16 v[84:87], v[222:225], v[172:175], v[84:87]
	v_mfma_f32_16x16x32_bf16 v[80:83], v[222:225], v[176:179], v[80:83]
	v_mfma_f32_16x16x32_bf16 v[76:79], v[222:225], v[180:183], v[76:79]
	v_mfma_f32_16x16x32_bf16 v[72:75], v[226:229], v[168:171], v[72:75]
	v_mfma_f32_16x16x32_bf16 v[68:71], v[226:229], v[172:175], v[68:71]
	v_mfma_f32_16x16x32_bf16 v[64:67], v[226:229], v[176:179], v[64:67]
	v_mfma_f32_16x16x32_bf16 v[60:63], v[226:229], v[180:183], v[60:63]
	s_waitcnt lgkmcnt(0)
	v_mfma_f32_16x16x32_bf16 v[56:59], v[152:155], v[168:171], v[56:59]
	s_waitcnt vmcnt(0)
	s_barrier
	v_add3_u32 v210, v151, v150, s99
	v_add3_u32 v134, v151, v148, s99
	v_mfma_f32_16x16x32_bf16 v[52:55], v[152:155], v[172:175], v[52:55]
	ds_read_b128 v[198:201], v210 offset:32768
	ds_read_b128 v[202:205], v210 offset:34816
	v_mfma_f32_16x16x32_bf16 v[48:51], v[152:155], v[176:179], v[48:51]
	ds_read_b128 v[206:209], v210 offset:36864
	ds_read_b128 v[210:213], v210 offset:38912
	v_mfma_f32_16x16x32_bf16 v[44:47], v[152:155], v[180:183], v[44:47]
	ds_read_b128 v[214:217], v134 offset:0
	ds_read_b128 v[218:221], v134 offset:2048
	v_mfma_f32_16x16x32_bf16 v[40:43], v[156:159], v[168:171], v[40:43]
	ds_read_b128 v[222:225], v134 offset:4096
	ds_read_b128 v[226:229], v134 offset:6144
	s_mov_b32 m0, s93
	v_mfma_f32_16x16x32_bf16 v[36:39], v[156:159], v[172:175], v[36:39]
	global_load_lds_dwordx4 v[128:129], off
	v_lshl_add_u64 v[128:129], v[128:129], 0, s[100:101]
	s_add_i32 m0, s93, 0x8000
	v_mfma_f32_16x16x32_bf16 v[32:35], v[156:159], v[176:179], v[32:35]
	global_load_lds_dwordx4 v[140:141], off
	v_lshl_add_u64 v[140:141], v[140:141], 0, s[100:101]
	s_mov_b32 m0, s94
	v_mfma_f32_16x16x32_bf16 v[28:31], v[156:159], v[180:183], v[28:31]
	global_load_lds_dwordx4 v[130:131], off
	v_lshl_add_u64 v[130:131], v[130:131], 0, s[100:101]
	s_add_i32 m0, s94, 0x8000
	v_mfma_f32_16x16x32_bf16 v[24:27], v[160:163], v[168:171], v[24:27]
	global_load_lds_dwordx4 v[142:143], off
	v_lshl_add_u64 v[142:143], v[142:143], 0, s[100:101]
	s_mov_b32 m0, s95
	v_mfma_f32_16x16x32_bf16 v[20:23], v[160:163], v[172:175], v[20:23]
	global_load_lds_dwordx4 v[136:137], off
	v_lshl_add_u64 v[136:137], v[136:137], 0, s[100:101]
	s_add_i32 m0, s95, 0x8000
	v_mfma_f32_16x16x32_bf16 v[16:19], v[160:163], v[176:179], v[16:19]
	global_load_lds_dwordx4 v[144:145], off
	v_lshl_add_u64 v[144:145], v[144:145], 0, s[100:101]
	s_mov_b32 m0, s96
	v_mfma_f32_16x16x32_bf16 v[12:15], v[160:163], v[180:183], v[12:15]
	global_load_lds_dwordx4 v[138:139], off
	v_lshl_add_u64 v[138:139], v[138:139], 0, s[100:101]
	s_add_i32 m0, s96, 0x8000
	v_mfma_f32_16x16x32_bf16 v[8:11], v[164:167], v[168:171], v[8:11]
	global_load_lds_dwordx4 v[146:147], off
	v_lshl_add_u64 v[146:147], v[146:147], 0, s[100:101]
	v_mfma_f32_16x16x32_bf16 v[4:7], v[164:167], v[172:175], v[4:7]
	v_mfma_f32_16x16x32_bf16 v[0:3], v[164:167], v[176:179], v[0:3]
	v_mfma_f32_16x16x32_bf16 v[88:91], v[164:167], v[180:183], v[88:91]
	ds_read_b128 v[152:155], v134 offset:8192
	ds_read_b128 v[156:159], v134 offset:10240
	ds_read_b128 v[160:163], v134 offset:12288
	ds_read_b128 v[164:167], v134 offset:14336
	s_waitcnt lgkmcnt(4)
	v_mfma_f32_16x16x32_bf16 v[124:127], v[214:217], v[198:201], v[124:127]
	v_mfma_f32_16x16x32_bf16 v[120:123], v[214:217], v[202:205], v[120:123]
	v_mfma_f32_16x16x32_bf16 v[116:119], v[214:217], v[206:209], v[116:119]
	v_mfma_f32_16x16x32_bf16 v[112:115], v[214:217], v[210:213], v[112:115]
	v_mfma_f32_16x16x32_bf16 v[108:111], v[218:221], v[198:201], v[108:111]
	v_mfma_f32_16x16x32_bf16 v[104:107], v[218:221], v[202:205], v[104:107]
	v_mfma_f32_16x16x32_bf16 v[100:103], v[218:221], v[206:209], v[100:103]
	v_mfma_f32_16x16x32_bf16 v[96:99], v[218:221], v[210:213], v[96:99]
	v_mfma_f32_16x16x32_bf16 v[92:95], v[222:225], v[198:201], v[92:95]
	v_mfma_f32_16x16x32_bf16 v[84:87], v[222:225], v[202:205], v[84:87]
	v_mfma_f32_16x16x32_bf16 v[80:83], v[222:225], v[206:209], v[80:83]
	v_mfma_f32_16x16x32_bf16 v[76:79], v[222:225], v[210:213], v[76:79]
	v_mfma_f32_16x16x32_bf16 v[72:75], v[226:229], v[198:201], v[72:75]
	v_mfma_f32_16x16x32_bf16 v[68:71], v[226:229], v[202:205], v[68:71]
	v_mfma_f32_16x16x32_bf16 v[64:67], v[226:229], v[206:209], v[64:67]
	v_mfma_f32_16x16x32_bf16 v[60:63], v[226:229], v[210:213], v[60:63]
	v_add3_u32 v226, v149, v150, s99
	v_add3_u32 v134, v149, v148, s99
	ds_read_b128 v[214:217], v226 offset:32768
	ds_read_b128 v[218:221], v226 offset:34816
	ds_read_b128 v[222:225], v226 offset:36864
	ds_read_b128 v[226:229], v226 offset:38912
	ds_read_b128 v[168:171], v134 offset:0
	ds_read_b128 v[172:175], v134 offset:2048
	ds_read_b128 v[176:179], v134 offset:4096
	ds_read_b128 v[180:183], v134 offset:6144
	s_waitcnt lgkmcnt(8)
	v_mfma_f32_16x16x32_bf16 v[56:59], v[152:155], v[198:201], v[56:59]
	v_mfma_f32_16x16x32_bf16 v[52:55], v[152:155], v[202:205], v[52:55]
	v_mfma_f32_16x16x32_bf16 v[48:51], v[152:155], v[206:209], v[48:51]
	v_mfma_f32_16x16x32_bf16 v[44:47], v[152:155], v[210:213], v[44:47]
	v_mfma_f32_16x16x32_bf16 v[40:43], v[156:159], v[198:201], v[40:43]
	v_mfma_f32_16x16x32_bf16 v[36:39], v[156:159], v[202:205], v[36:39]
	v_mfma_f32_16x16x32_bf16 v[32:35], v[156:159], v[206:209], v[32:35]
	v_mfma_f32_16x16x32_bf16 v[28:31], v[156:159], v[210:213], v[28:31]
	v_mfma_f32_16x16x32_bf16 v[24:27], v[160:163], v[198:201], v[24:27]
	v_mfma_f32_16x16x32_bf16 v[20:23], v[160:163], v[202:205], v[20:23]
	v_mfma_f32_16x16x32_bf16 v[16:19], v[160:163], v[206:209], v[16:19]
	v_mfma_f32_16x16x32_bf16 v[12:15], v[160:163], v[210:213], v[12:15]
	v_mfma_f32_16x16x32_bf16 v[8:11], v[164:167], v[198:201], v[8:11]
	v_mfma_f32_16x16x32_bf16 v[4:7], v[164:167], v[202:205], v[4:7]
	v_mfma_f32_16x16x32_bf16 v[0:3], v[164:167], v[206:209], v[0:3]
	v_mfma_f32_16x16x32_bf16 v[88:91], v[164:167], v[210:213], v[88:91]
	ds_read_b128 v[198:201], v134 offset:8192
	ds_read_b128 v[202:205], v134 offset:10240
	ds_read_b128 v[206:209], v134 offset:12288
	ds_read_b128 v[210:213], v134 offset:14336
	s_waitcnt lgkmcnt(4)
	v_mfma_f32_16x16x32_bf16 v[124:127], v[168:171], v[214:217], v[124:127]
	v_mfma_f32_16x16x32_bf16 v[120:123], v[168:171], v[218:221], v[120:123]
	v_mfma_f32_16x16x32_bf16 v[116:119], v[168:171], v[222:225], v[116:119]
	v_mfma_f32_16x16x32_bf16 v[112:115], v[168:171], v[226:229], v[112:115]
	v_mfma_f32_16x16x32_bf16 v[108:111], v[172:175], v[214:217], v[108:111]
	v_mfma_f32_16x16x32_bf16 v[104:107], v[172:175], v[218:221], v[104:107]
	v_mfma_f32_16x16x32_bf16 v[100:103], v[172:175], v[222:225], v[100:103]
	v_mfma_f32_16x16x32_bf16 v[96:99], v[172:175], v[226:229], v[96:99]
	v_mfma_f32_16x16x32_bf16 v[92:95], v[176:179], v[214:217], v[92:95]
	v_mfma_f32_16x16x32_bf16 v[84:87], v[176:179], v[218:221], v[84:87]
	v_mfma_f32_16x16x32_bf16 v[80:83], v[176:179], v[222:225], v[80:83]
	v_mfma_f32_16x16x32_bf16 v[76:79], v[176:179], v[226:229], v[76:79]
	v_mfma_f32_16x16x32_bf16 v[72:75], v[180:183], v[214:217], v[72:75]
	v_mfma_f32_16x16x32_bf16 v[68:71], v[180:183], v[218:221], v[68:71]
	v_mfma_f32_16x16x32_bf16 v[64:67], v[180:183], v[222:225], v[64:67]
	v_mfma_f32_16x16x32_bf16 v[60:63], v[180:183], v[226:229], v[60:63]
	s_waitcnt lgkmcnt(0)
	v_mfma_f32_16x16x32_bf16 v[56:59], v[198:201], v[214:217], v[56:59]
	s_waitcnt vmcnt(0)
	s_barrier
	v_add_u32_e32 v164, v151, v150
	v_add_u32_e32 v134, v151, v148
	v_mfma_f32_16x16x32_bf16 v[52:55], v[198:201], v[218:221], v[52:55]
	ds_read_b128 v[152:155], v164 offset:32768
	ds_read_b128 v[156:159], v164 offset:34816
	v_mfma_f32_16x16x32_bf16 v[48:51], v[198:201], v[222:225], v[48:51]
	ds_read_b128 v[160:163], v164 offset:36864
	ds_read_b128 v[164:167], v164 offset:38912
	v_mfma_f32_16x16x32_bf16 v[44:47], v[198:201], v[226:229], v[44:47]
	ds_read_b128 v[168:171], v134 offset:0
	ds_read_b128 v[172:175], v134 offset:2048
	v_mfma_f32_16x16x32_bf16 v[40:43], v[202:205], v[214:217], v[40:43]
	ds_read_b128 v[176:179], v134 offset:4096
	ds_read_b128 v[180:183], v134 offset:6144
	s_add_i32 m0, s93, 0x10000
	v_mfma_f32_16x16x32_bf16 v[36:39], v[202:205], v[218:221], v[36:39]
	global_load_lds_dwordx4 v[128:129], off
	v_lshl_add_u64 v[128:129], v[128:129], 0, s[100:101]
	s_add_i32 m0, s93, 0x18000
	v_mfma_f32_16x16x32_bf16 v[32:35], v[202:205], v[222:225], v[32:35]
	global_load_lds_dwordx4 v[140:141], off
	v_lshl_add_u64 v[140:141], v[140:141], 0, s[100:101]
	s_add_i32 m0, s94, 0x10000
	v_mfma_f32_16x16x32_bf16 v[28:31], v[202:205], v[226:229], v[28:31]
	global_load_lds_dwordx4 v[130:131], off
	v_lshl_add_u64 v[130:131], v[130:131], 0, s[100:101]
	s_add_i32 m0, s94, 0x18000
	v_mfma_f32_16x16x32_bf16 v[24:27], v[206:209], v[214:217], v[24:27]
	global_load_lds_dwordx4 v[142:143], off
	v_lshl_add_u64 v[142:143], v[142:143], 0, s[100:101]
	s_add_i32 m0, s95, 0x10000
	v_mfma_f32_16x16x32_bf16 v[20:23], v[206:209], v[218:221], v[20:23]
	global_load_lds_dwordx4 v[136:137], off
	v_lshl_add_u64 v[136:137], v[136:137], 0, s[100:101]
	s_add_i32 m0, s95, 0x18000
	v_mfma_f32_16x16x32_bf16 v[16:19], v[206:209], v[222:225], v[16:19]
	global_load_lds_dwordx4 v[144:145], off
	v_lshl_add_u64 v[144:145], v[144:145], 0, s[100:101]
	s_add_i32 m0, s96, 0x10000
	v_mfma_f32_16x16x32_bf16 v[12:15], v[206:209], v[226:229], v[12:15]
	global_load_lds_dwordx4 v[138:139], off
	v_lshl_add_u64 v[138:139], v[138:139], 0, s[100:101]
	s_add_i32 m0, s96, 0x18000
	v_mfma_f32_16x16x32_bf16 v[8:11], v[210:213], v[214:217], v[8:11]
	global_load_lds_dwordx4 v[146:147], off
	v_lshl_add_u64 v[146:147], v[146:147], 0, s[100:101]
	v_mfma_f32_16x16x32_bf16 v[4:7], v[210:213], v[218:221], v[4:7]
	v_mfma_f32_16x16x32_bf16 v[0:3], v[210:213], v[222:225], v[0:3]
	v_mfma_f32_16x16x32_bf16 v[88:91], v[210:213], v[226:229], v[88:91]
	s_add_u32 s2, s2, 0x100
	s_cmpk_lg_i32 s2, 0x700
	s_cbranch_scc1 .Lg_up_loop
	ds_read_b128 v[198:201], v134 offset:8192
	ds_read_b128 v[202:205], v134 offset:10240
	ds_read_b128 v[206:209], v134 offset:12288
	ds_read_b128 v[210:213], v134 offset:14336
	s_waitcnt lgkmcnt(4)
	v_mfma_f32_16x16x32_bf16 v[124:127], v[168:171], v[152:155], v[124:127]
	v_mfma_f32_16x16x32_bf16 v[120:123], v[168:171], v[156:159], v[120:123]
	v_mfma_f32_16x16x32_bf16 v[116:119], v[168:171], v[160:163], v[116:119]
	v_mfma_f32_16x16x32_bf16 v[112:115], v[168:171], v[164:167], v[112:115]
	v_mfma_f32_16x16x32_bf16 v[108:111], v[172:175], v[152:155], v[108:111]
	v_mfma_f32_16x16x32_bf16 v[104:107], v[172:175], v[156:159], v[104:107]
	v_mfma_f32_16x16x32_bf16 v[100:103], v[172:175], v[160:163], v[100:103]
	v_mfma_f32_16x16x32_bf16 v[96:99], v[172:175], v[164:167], v[96:99]
	v_mfma_f32_16x16x32_bf16 v[92:95], v[176:179], v[152:155], v[92:95]
	v_mfma_f32_16x16x32_bf16 v[84:87], v[176:179], v[156:159], v[84:87]
	v_mfma_f32_16x16x32_bf16 v[80:83], v[176:179], v[160:163], v[80:83]
	v_mfma_f32_16x16x32_bf16 v[76:79], v[176:179], v[164:167], v[76:79]
	v_mfma_f32_16x16x32_bf16 v[72:75], v[180:183], v[152:155], v[72:75]
	v_mfma_f32_16x16x32_bf16 v[68:71], v[180:183], v[156:159], v[68:71]
	v_mfma_f32_16x16x32_bf16 v[64:67], v[180:183], v[160:163], v[64:67]
	v_mfma_f32_16x16x32_bf16 v[60:63], v[180:183], v[164:167], v[60:63]
	v_add_u32_e32 v180, v149, v150
	v_add_u32_e32 v134, v149, v148
	ds_read_b128 v[168:171], v180 offset:32768
	ds_read_b128 v[172:175], v180 offset:34816
	ds_read_b128 v[176:179], v180 offset:36864
	ds_read_b128 v[180:183], v180 offset:38912
	ds_read_b128 v[214:217], v134 offset:0
	ds_read_b128 v[218:221], v134 offset:2048
	ds_read_b128 v[222:225], v134 offset:4096
	ds_read_b128 v[226:229], v134 offset:6144
	s_waitcnt lgkmcnt(8)
	v_mfma_f32_16x16x32_bf16 v[56:59], v[198:201], v[152:155], v[56:59]
	v_mfma_f32_16x16x32_bf16 v[52:55], v[198:201], v[156:159], v[52:55]
	v_mfma_f32_16x16x32_bf16 v[48:51], v[198:201], v[160:163], v[48:51]
	v_mfma_f32_16x16x32_bf16 v[44:47], v[198:201], v[164:167], v[44:47]
	v_mfma_f32_16x16x32_bf16 v[40:43], v[202:205], v[152:155], v[40:43]
	v_mfma_f32_16x16x32_bf16 v[36:39], v[202:205], v[156:159], v[36:39]
	v_mfma_f32_16x16x32_bf16 v[32:35], v[202:205], v[160:163], v[32:35]
	v_mfma_f32_16x16x32_bf16 v[28:31], v[202:205], v[164:167], v[28:31]
	v_mfma_f32_16x16x32_bf16 v[24:27], v[206:209], v[152:155], v[24:27]
	v_mfma_f32_16x16x32_bf16 v[20:23], v[206:209], v[156:159], v[20:23]
	v_mfma_f32_16x16x32_bf16 v[16:19], v[206:209], v[160:163], v[16:19]
	v_mfma_f32_16x16x32_bf16 v[12:15], v[206:209], v[164:167], v[12:15]
	v_mfma_f32_16x16x32_bf16 v[8:11], v[210:213], v[152:155], v[8:11]
	v_mfma_f32_16x16x32_bf16 v[4:7], v[210:213], v[156:159], v[4:7]
	v_mfma_f32_16x16x32_bf16 v[0:3], v[210:213], v[160:163], v[0:3]
	v_mfma_f32_16x16x32_bf16 v[88:91], v[210:213], v[164:167], v[88:91]
	ds_read_b128 v[152:155], v134 offset:8192
	ds_read_b128 v[156:159], v134 offset:10240
	ds_read_b128 v[160:163], v134 offset:12288
	ds_read_b128 v[164:167], v134 offset:14336
	s_waitcnt lgkmcnt(4)
	v_mfma_f32_16x16x32_bf16 v[124:127], v[214:217], v[168:171], v[124:127]
	v_mfma_f32_16x16x32_bf16 v[120:123], v[214:217], v[172:175], v[120:123]
	v_mfma_f32_16x16x32_bf16 v[116:119], v[214:217], v[176:179], v[116:119]
	v_mfma_f32_16x16x32_bf16 v[112:115], v[214:217], v[180:183], v[112:115]
	v_mfma_f32_16x16x32_bf16 v[108:111], v[218:221], v[168:171], v[108:111]
	v_mfma_f32_16x16x32_bf16 v[104:107], v[218:221], v[172:175], v[104:107]
	v_mfma_f32_16x16x32_bf16 v[100:103], v[218:221], v[176:179], v[100:103]
	v_mfma_f32_16x16x32_bf16 v[96:99], v[218:221], v[180:183], v[96:99]
	v_mfma_f32_16x16x32_bf16 v[92:95], v[222:225], v[168:171], v[92:95]
	v_mfma_f32_16x16x32_bf16 v[84:87], v[222:225], v[172:175], v[84:87]
	v_mfma_f32_16x16x32_bf16 v[80:83], v[222:225], v[176:179], v[80:83]
	v_mfma_f32_16x16x32_bf16 v[76:79], v[222:225], v[180:183], v[76:79]
	v_mfma_f32_16x16x32_bf16 v[72:75], v[226:229], v[168:171], v[72:75]
	v_mfma_f32_16x16x32_bf16 v[68:71], v[226:229], v[172:175], v[68:71]
	v_mfma_f32_16x16x32_bf16 v[64:67], v[226:229], v[176:179], v[64:67]
	v_mfma_f32_16x16x32_bf16 v[60:63], v[226:229], v[180:183], v[60:63]
	s_waitcnt lgkmcnt(0)
	v_mfma_f32_16x16x32_bf16 v[56:59], v[152:155], v[168:171], v[56:59]
	s_waitcnt vmcnt(0)
	s_barrier
	v_mfma_f32_16x16x32_bf16 v[52:55], v[152:155], v[172:175], v[52:55]
	v_mfma_f32_16x16x32_bf16 v[48:51], v[152:155], v[176:179], v[48:51]
	v_mfma_f32_16x16x32_bf16 v[44:47], v[152:155], v[180:183], v[44:47]
	v_mfma_f32_16x16x32_bf16 v[40:43], v[156:159], v[168:171], v[40:43]
	v_mfma_f32_16x16x32_bf16 v[36:39], v[156:159], v[172:175], v[36:39]
	v_mfma_f32_16x16x32_bf16 v[32:35], v[156:159], v[176:179], v[32:35]
	v_mfma_f32_16x16x32_bf16 v[28:31], v[156:159], v[180:183], v[28:31]
	v_mfma_f32_16x16x32_bf16 v[24:27], v[160:163], v[168:171], v[24:27]
	v_mfma_f32_16x16x32_bf16 v[20:23], v[160:163], v[172:175], v[20:23]
	v_mfma_f32_16x16x32_bf16 v[16:19], v[160:163], v[176:179], v[16:19]
	v_mfma_f32_16x16x32_bf16 v[12:15], v[160:163], v[180:183], v[12:15]
	v_mfma_f32_16x16x32_bf16 v[8:11], v[164:167], v[168:171], v[8:11]
	v_mfma_f32_16x16x32_bf16 v[4:7], v[164:167], v[172:175], v[4:7]
	v_mfma_f32_16x16x32_bf16 v[0:3], v[164:167], v[176:179], v[0:3]
	v_mfma_f32_16x16x32_bf16 v[88:91], v[164:167], v[180:183], v[88:91]
	s_movk_i32 s2, 0x780
	s_mov_b32 s97, 0xf0000
	v_add3_u32 v134, v148, v151, s75
	ds_read_b128 v[128:131], v134 offset:14336
	ds_read_b128 v[136:139], v134 offset:12288
	ds_read_b128 v[140:143], v134 offset:10240
	ds_read_b128 v[144:147], v134 offset:8192
	ds_read_b128 v[152:155], v134 offset:6144
	ds_read_b128 v[156:159], v134 offset:4096
	ds_read_b128 v[160:163], v134 offset:2048
	ds_read_b128 v[164:167], v134
	v_add3_u32 v134, v150, v151, s63
	ds_read_b128 v[168:171], v134 offset:6144
	ds_read_b128 v[172:175], v134 offset:4096
	ds_read_b128 v[176:179], v134 offset:2048
	ds_read_b128 v[180:183], v134
	s_waitcnt lgkmcnt(0)
	v_mfma_f32_16x16x32_bf16 v[124:127], v[164:167], v[180:183], v[124:127]
	v_mfma_f32_16x16x32_bf16 v[120:123], v[164:167], v[176:179], v[120:123]
	v_mfma_f32_16x16x32_bf16 v[116:119], v[164:167], v[172:175], v[116:119]
	v_mfma_f32_16x16x32_bf16 v[112:115], v[164:167], v[168:171], v[112:115]
	v_mfma_f32_16x16x32_bf16 v[108:111], v[160:163], v[180:183], v[108:111]
	v_mfma_f32_16x16x32_bf16 v[104:107], v[160:163], v[176:179], v[104:107]
	v_mfma_f32_16x16x32_bf16 v[100:103], v[160:163], v[172:175], v[100:103]
	v_mfma_f32_16x16x32_bf16 v[96:99], v[160:163], v[168:171], v[96:99]
	v_mfma_f32_16x16x32_bf16 v[92:95], v[156:159], v[180:183], v[92:95]
	v_mfma_f32_16x16x32_bf16 v[84:87], v[156:159], v[176:179], v[84:87]
	v_mfma_f32_16x16x32_bf16 v[80:83], v[156:159], v[172:175], v[80:83]
	v_mfma_f32_16x16x32_bf16 v[76:79], v[156:159], v[168:171], v[76:79]
	v_mfma_f32_16x16x32_bf16 v[72:75], v[152:155], v[180:183], v[72:75]
	v_mfma_f32_16x16x32_bf16 v[68:71], v[152:155], v[176:179], v[68:71]
	v_mfma_f32_16x16x32_bf16 v[64:67], v[152:155], v[172:175], v[64:67]
	v_mfma_f32_16x16x32_bf16 v[60:63], v[152:155], v[168:171], v[60:63]
	v_add3_u32 v134, v150, v149, s63
	ds_read_b128 v[150:153], v134
	ds_read_b128 v[154:157], v134 offset:2048
	ds_read_b128 v[158:161], v134 offset:4096
	ds_read_b128 v[162:165], v134 offset:6144
	v_add3_u32 v134, v148, v149, s75
	ds_read_b128 v[198:201], v134
	ds_read_b128 v[202:205], v134 offset:2048
	ds_read_b128 v[206:209], v134 offset:4096
	ds_read_b128 v[210:213], v134 offset:6144
	v_mfma_f32_16x16x32_bf16 v[44:47], v[144:147], v[168:171], v[44:47]
	v_mfma_f32_16x16x32_bf16 v[40:43], v[140:143], v[180:183], v[40:43]
	v_mfma_f32_16x16x32_bf16 v[28:31], v[140:143], v[168:171], v[28:31]
	v_mfma_f32_16x16x32_bf16 v[24:27], v[136:139], v[180:183], v[24:27]
	v_mfma_f32_16x16x32_bf16 v[20:23], v[136:139], v[176:179], v[20:23]
	v_mfma_f32_16x16x32_bf16 v[16:19], v[136:139], v[172:175], v[16:19]
	v_mfma_f32_16x16x32_bf16 v[12:15], v[136:139], v[168:171], v[12:15]
	v_mfma_f32_16x16x32_bf16 v[8:11], v[128:131], v[180:183], v[8:11]
	v_mfma_f32_16x16x32_bf16 v[4:7], v[128:131], v[176:179], v[4:7]
	v_mfma_f32_16x16x32_bf16 v[0:3], v[128:131], v[172:175], v[0:3]
	v_mfma_f32_16x16x32_bf16 v[56:59], v[144:147], v[180:183], v[56:59]
	v_mfma_f32_16x16x32_bf16 v[52:55], v[144:147], v[176:179], v[52:55]
	v_mfma_f32_16x16x32_bf16 v[48:51], v[144:147], v[172:175], v[48:51]
	v_mfma_f32_16x16x32_bf16 v[36:39], v[140:143], v[176:179], v[36:39]
	v_mfma_f32_16x16x32_bf16 v[32:35], v[140:143], v[172:175], v[32:35]
	v_mfma_f32_16x16x32_bf16 v[88:91], v[128:131], v[168:171], v[88:91]
	ds_read_b128 v[128:131], v134 offset:8192
	ds_read_b128 v[136:139], v134 offset:10240
	ds_read_b128 v[140:143], v134 offset:12288
	ds_read_b128 v[144:147], v134 offset:14336
	s_waitcnt lgkmcnt(0)
	v_mfma_f32_16x16x32_bf16 v[124:127], v[198:201], v[150:153], v[124:127]
	v_mfma_f32_16x16x32_bf16 v[120:123], v[198:201], v[154:157], v[120:123]
	v_mfma_f32_16x16x32_bf16 v[116:119], v[198:201], v[158:161], v[116:119]
	v_mfma_f32_16x16x32_bf16 v[112:115], v[198:201], v[162:165], v[112:115]
	v_mfma_f32_16x16x32_bf16 v[108:111], v[202:205], v[150:153], v[108:111]
	v_mfma_f32_16x16x32_bf16 v[104:107], v[202:205], v[154:157], v[104:107]
	v_mfma_f32_16x16x32_bf16 v[100:103], v[202:205], v[158:161], v[100:103]
	v_mfma_f32_16x16x32_bf16 v[96:99], v[202:205], v[162:165], v[96:99]
	v_mfma_f32_16x16x32_bf16 v[92:95], v[206:209], v[150:153], v[92:95]
	v_mfma_f32_16x16x32_bf16 v[84:87], v[206:209], v[154:157], v[84:87]
	v_mfma_f32_16x16x32_bf16 v[80:83], v[206:209], v[158:161], v[80:83]
	v_mfma_f32_16x16x32_bf16 v[76:79], v[206:209], v[162:165], v[76:79]
	v_mfma_f32_16x16x32_bf16 v[72:75], v[210:213], v[150:153], v[72:75]
	v_mfma_f32_16x16x32_bf16 v[68:71], v[210:213], v[154:157], v[68:71]
	v_mfma_f32_16x16x32_bf16 v[64:67], v[210:213], v[158:161], v[64:67]
	v_mfma_f32_16x16x32_bf16 v[60:63], v[210:213], v[162:165], v[60:63]
	s_waitcnt vmcnt(0)
	v_mov_b32_e32 v148, v184
	v_mfma_f32_16x16x32_bf16 v[24:27], v[140:143], v[150:153], v[24:27]
	s_waitcnt lgkmcnt(0)
	s_barrier
	v_mfma_f32_16x16x32_bf16 v[8:11], v[144:147], v[150:153], v[8:11]
	s_nop 5
	v_cvt_pk_bf16_f32 v24, v24, v25
	v_lshrrev_b32_e32 v134, 8, v148
	v_mul_i32_i24_e32 v134, 0x11000, v134
	v_lshrrev_b32_e32 v166, 1, v148
	v_and_b32_e32 v149, 0xcf, v148
	v_and_or_b32 v134, v166, 24, v134
	v_mfma_f32_16x16x32_bf16 v[56:59], v[128:131], v[150:153], v[56:59]
	v_cvt_pk_bf16_f32 v25, v26, v27
	v_cvt_pk_bf16_f32 v8, v8, v9
	v_cvt_pk_bf16_f32 v9, v10, v11
	v_mfma_f32_16x16x32_bf16 v[52:55], v[128:131], v[154:157], v[52:55]
	s_mov_b64 s[2:3], 0x2c00
	s_nop 2
	v_cvt_pk_bf16_f32 v56, v56, v57
	v_cvt_pk_bf16_f32 v57, v58, v59
	v_mfma_f32_16x16x32_bf16 v[48:51], v[128:131], v[158:161], v[48:51]
	v_cvt_pk_bf16_f32 v124, v124, v125
	v_cvt_pk_bf16_f32 v125, v126, v127
	v_cvt_pk_bf16_f32 v108, v108, v109
	v_mfma_f32_16x16x32_bf16 v[44:47], v[128:131], v[162:165], v[44:47]
	v_mad_u32_u24 v128, v149, s51, v134
	s_waitcnt vmcnt(0)
	ds_write2_b64 v128, v[24:25], v[8:9] offset0:24 offset1:28
	v_cvt_pk_bf16_f32 v24, v52, v53
	v_mfma_f32_16x16x32_bf16 v[40:43], v[136:139], v[150:153], v[40:43]
	v_cvt_pk_bf16_f32 v25, v54, v55
	v_cvt_pk_bf16_f32 v109, v110, v111
	v_cvt_pk_bf16_f32 v92, v92, v93
	v_mfma_f32_16x16x32_bf16 v[8:11], v[140:143], v[154:157], v[20:23]
	v_cvt_pk_bf16_f32 v93, v94, v95
	s_nop 2
	v_cvt_pk_bf16_f32 v40, v40, v41
	v_cvt_pk_bf16_f32 v41, v42, v43
	v_mfma_f32_16x16x32_bf16 v[4:7], v[144:147], v[154:157], v[4:7]
	ds_write2_b64 v128, v[56:57], v[40:41] offset0:16 offset1:20
	v_add_u32_e32 v40, 0x1000, v128
	v_cvt_pk_bf16_f32 v8, v8, v9
	v_mfma_f32_16x16x32_bf16 v[32:35], v[136:139], v[158:161], v[32:35]
	v_cvt_pk_bf16_f32 v9, v10, v11
	s_nop 2
	v_cvt_pk_bf16_f32 v4, v4, v5
	v_cvt_pk_bf16_f32 v5, v6, v7
	v_mfma_f32_16x16x32_bf16 v[16:19], v[140:143], v[158:161], v[16:19]
	ds_write2_b64 v40, v[8:9], v[4:5] offset0:56 offset1:60
	v_cvt_pk_bf16_f32 v4, v116, v117
	v_cvt_pk_bf16_f32 v5, v118, v119
	v_mfma_f32_16x16x32_bf16 v[0:3], v[144:147], v[158:161], v[0:3]
	v_cvt_pk_bf16_f32 v6, v100, v101
	v_cvt_pk_bf16_f32 v7, v102, v103
	v_add_u32_e32 v8, 0x2000, v128
	v_cvt_pk_bf16_f32 v20, v120, v121
	v_cvt_pk_bf16_f32 v21, v122, v123
	v_cvt_pk_bf16_f32 v22, v104, v105
	v_cvt_pk_bf16_f32 v23, v106, v107
	ds_write2_b64 v8, v[4:5], v[6:7] offset0:64 offset1:68
	v_cvt_pk_bf16_f32 v4, v80, v81
	v_cvt_pk_bf16_f32 v5, v82, v83
	v_cvt_pk_bf16_f32 v6, v64, v65
	v_cvt_pk_bf16_f32 v7, v66, v67
	v_mfma_f32_16x16x32_bf16 v[28:31], v[136:139], v[162:165], v[28:31]
	ds_write2_b64 v40, v[20:21], v[22:23] offset0:32 offset1:36
	v_cvt_pk_bf16_f32 v20, v84, v85
	v_cvt_pk_bf16_f32 v21, v86, v87
	v_cvt_pk_bf16_f32 v22, v68, v69
	v_cvt_pk_bf16_f32 v23, v70, v71
	ds_write2_b64 v8, v[4:5], v[6:7] offset0:72 offset1:76
	v_cvt_pk_bf16_f32 v4, v48, v49
	v_cvt_pk_bf16_f32 v5, v50, v51
	v_cvt_pk_bf16_f32 v6, v32, v33
	v_cvt_pk_bf16_f32 v7, v34, v35
	v_mfma_f32_16x16x32_bf16 v[12:15], v[140:143], v[162:165], v[12:15]
	ds_write2_b64 v40, v[20:21], v[22:23] offset0:40 offset1:44
	ds_write2_b64 v8, v[4:5], v[6:7] offset0:80 offset1:84
	v_cvt_pk_bf16_f32 v4, v16, v17
	v_mfma_f32_16x16x32_bf16 v[20:23], v[144:147], v[162:165], v[88:91]
	v_cvt_pk_bf16_f32 v5, v18, v19
	v_cvt_pk_bf16_f32 v0, v0, v1
	v_cvt_pk_bf16_f32 v1, v2, v3
	ds_write2_b64 v8, v[4:5], v[0:1] offset0:88 offset1:92
	v_cvt_pk_bf16_f32 v0, v112, v113
	v_cvt_pk_bf16_f32 v1, v114, v115
	v_cvt_pk_bf16_f32 v2, v96, v97
	v_cvt_pk_bf16_f32 v3, v98, v99
	v_add_u32_e32 v4, 0x3000, v128
	ds_write2_b64 v4, v[0:1], v[2:3] offset0:96 offset1:100
	v_cvt_pk_bf16_f32 v0, v76, v77
	v_cvt_pk_bf16_f32 v1, v78, v79
	v_cvt_pk_bf16_f32 v2, v60, v61
	v_cvt_pk_bf16_f32 v3, v62, v63
	v_mfma_f32_16x16x32_bf16 v[36:39], v[136:139], v[154:157], v[36:39]
	ds_write2_b64 v4, v[0:1], v[2:3] offset0:104 offset1:108
	v_cvt_pk_bf16_f32 v0, v44, v45
	v_cvt_pk_bf16_f32 v1, v46, v47
	v_cvt_pk_bf16_f32 v2, v28, v29
	v_cvt_pk_bf16_f32 v3, v30, v31
	ds_write2_b64 v4, v[0:1], v[2:3] offset0:112 offset1:116
	v_cvt_pk_bf16_f32 v0, v12, v13
	v_cvt_pk_bf16_f32 v1, v14, v15
	v_cvt_pk_bf16_f32 v2, v20, v21
	v_cvt_pk_bf16_f32 v3, v22, v23
	ds_write2_b64 v4, v[0:1], v[2:3] offset0:120 offset1:124
	v_lshlrev_b32_e32 v0, 3, v148
	v_and_b32_e32 v32, 0x78, v0
	v_cvt_pk_bf16_f32 v26, v36, v37
	v_cvt_pk_bf16_f32 v27, v38, v39
	v_lshl_or_b32 v134, s44, 7, v32
	ds_write2_b64 v40, v[24:25], v[26:27] offset0:48 offset1:52
	v_lshlrev_b64 v[24:25], 2, v[134:135]
	v_lshl_add_u64 v[16:17], s[10:11], 0, v[24:25]
	v_cvt_pk_bf16_f32 v72, v72, v73
	v_cvt_pk_bf16_f32 v73, v74, v75
	v_lshl_add_u64 v[12:13], v[16:17], 0, s[2:3]
	s_movk_i32 s2, 0x2000
	ds_write2_b64 v128, v[124:125], v[108:109] offset1:4
	ds_write2_b64 v128, v[92:93], v[72:73] offset0:8 offset1:12
	v_add_co_u32_e32 v8, vcc, s2, v16
	s_mov_b64 s[2:3], 0x5800
	s_waitcnt lgkmcnt(0)
	s_barrier
	v_addc_co_u32_e32 v9, vcc, 0, v17, vcc
	v_lshl_add_u64 v[20:21], v[16:17], 0, s[2:3]
	s_movk_i32 s2, 0x5000
	global_load_dwordx4 v[0:3], v[16:17], off offset:16
	global_load_dwordx4 v[4:7], v[16:17], off
	v_add_co_u32_e32 v16, vcc, s2, v16
	v_lshl_add_u64 v[28:29], s[12:13], 0, v[24:25]
	s_nop 0
	v_addc_co_u32_e32 v17, vcc, 0, v17, vcc
	global_load_dwordx4 v[8:11], v[8:9], off offset:3072
	s_nop 0
	global_load_dwordx4 v[12:15], v[12:13], off offset:16
	s_nop 0
	global_load_dwordx4 v[16:19], v[16:17], off offset:2048
	s_nop 0
	global_load_dwordx4 v[20:23], v[20:21], off offset:16
	s_nop 0
	global_load_dwordx4 v[24:27], v[28:29], off offset:16
	s_nop 0
	global_load_dwordx4 v[28:31], v[28:29], off
	v_ashrrev_i32_e32 v33, 4, v148
	v_mul_lo_u32 v34, v33, s51
	s_mov_b32 s44, 0
	v_lshl_add_u64 v[40:41], v[134:135], 1, s[22:23]
	v_lshl_add_u32 v44, v32, 1, v34
	v_add_u32_e32 v45, 31, v33
	s_waitcnt vmcnt(0)
	s_branch .LBB0_2308

.LBB0_2355:
	s_waitcnt lgkmcnt(0)
	s_mov_b32 s99, 0x10000
	s_mov_b32 s100, 0x80
	s_mov_b32 s101, 0
	s_add_i32 m0, s12, 0x10000
	s_nop 0
	global_load_lds_dwordx4 v[128:129], off
	v_lshl_add_u64 v[128:129], v[128:129], 0, s[100:101]
	s_add_i32 m0, s12, 0x18000
	s_nop 0
	global_load_lds_dwordx4 v[140:141], off
	v_lshl_add_u64 v[140:141], v[140:141], 0, s[100:101]
	s_add_i32 m0, s13, 0x10000
	s_nop 0
	global_load_lds_dwordx4 v[130:131], off
	v_lshl_add_u64 v[130:131], v[130:131], 0, s[100:101]
	s_add_i32 m0, s13, 0x18000
	s_nop 0
	global_load_lds_dwordx4 v[142:143], off
	v_lshl_add_u64 v[142:143], v[142:143], 0, s[100:101]
	s_add_i32 m0, s29, 0x10000
	s_nop 0
	global_load_lds_dwordx4 v[136:137], off
	v_lshl_add_u64 v[136:137], v[136:137], 0, s[100:101]
	s_add_i32 m0, s29, 0x18000
	s_nop 0
	global_load_lds_dwordx4 v[144:145], off
	v_lshl_add_u64 v[144:145], v[144:145], 0, s[100:101]
	s_add_i32 m0, s31, 0x10000
	s_nop 0
	global_load_lds_dwordx4 v[138:139], off
	v_lshl_add_u64 v[138:139], v[138:139], 0, s[100:101]
	s_add_i32 m0, s31, 0x18000
	s_nop 0
	global_load_lds_dwordx4 v[146:147], off
	v_lshl_add_u64 v[146:147], v[146:147], 0, s[100:101]
	v_add_u32_e32 v164, v151, v149
	v_add_u32_e32 v134, v151, v148
	ds_read_b128 v[152:155], v164 offset:32768
	ds_read_b128 v[156:159], v164 offset:34816
	ds_read_b128 v[160:163], v164 offset:36864
	ds_read_b128 v[164:167], v164 offset:38912
	ds_read_b128 v[168:171], v134 offset:0
	ds_read_b128 v[172:175], v134 offset:2048
	ds_read_b128 v[176:179], v134 offset:4096
	ds_read_b128 v[180:183], v134 offset:6144
	s_mov_b32 s4, 0
.Lg_down_loop:
	ds_read_b128 v[198:201], v134 offset:8192
	ds_read_b128 v[202:205], v134 offset:10240
	ds_read_b128 v[206:209], v134 offset:12288
	ds_read_b128 v[210:213], v134 offset:14336
	s_waitcnt lgkmcnt(4)
	v_mfma_f32_16x16x32_bf16 v[124:127], v[168:171], v[152:155], v[124:127]
	v_mfma_f32_16x16x32_bf16 v[120:123], v[168:171], v[156:159], v[120:123]
	v_mfma_f32_16x16x32_bf16 v[116:119], v[168:171], v[160:163], v[116:119]
	v_mfma_f32_16x16x32_bf16 v[112:115], v[168:171], v[164:167], v[112:115]
	v_mfma_f32_16x16x32_bf16 v[108:111], v[172:175], v[152:155], v[108:111]
	v_mfma_f32_16x16x32_bf16 v[104:107], v[172:175], v[156:159], v[104:107]
	v_mfma_f32_16x16x32_bf16 v[100:103], v[172:175], v[160:163], v[100:103]
	v_mfma_f32_16x16x32_bf16 v[96:99], v[172:175], v[164:167], v[96:99]
	v_mfma_f32_16x16x32_bf16 v[92:95], v[176:179], v[152:155], v[92:95]
	v_mfma_f32_16x16x32_bf16 v[84:87], v[176:179], v[156:159], v[84:87]
	v_mfma_f32_16x16x32_bf16 v[80:83], v[176:179], v[160:163], v[80:83]
	v_mfma_f32_16x16x32_bf16 v[76:79], v[176:179], v[164:167], v[76:79]
	v_mfma_f32_16x16x32_bf16 v[72:75], v[180:183], v[152:155], v[72:75]
	v_mfma_f32_16x16x32_bf16 v[68:71], v[180:183], v[156:159], v[68:71]
	v_mfma_f32_16x16x32_bf16 v[64:67], v[180:183], v[160:163], v[64:67]
	v_mfma_f32_16x16x32_bf16 v[60:63], v[180:183], v[164:167], v[60:63]
	v_add_u32_e32 v180, v150, v149
	v_add_u32_e32 v134, v150, v148
	ds_read_b128 v[168:171], v180 offset:32768
	ds_read_b128 v[172:175], v180 offset:34816
	ds_read_b128 v[176:179], v180 offset:36864
	ds_read_b128 v[180:183], v180 offset:38912
	ds_read_b128 v[214:217], v134 offset:0
	ds_read_b128 v[218:221], v134 offset:2048
	ds_read_b128 v[222:225], v134 offset:4096
	ds_read_b128 v[226:229], v134 offset:6144
	s_waitcnt lgkmcnt(8)
	v_mfma_f32_16x16x32_bf16 v[56:59], v[198:201], v[152:155], v[56:59]
	v_mfma_f32_16x16x32_bf16 v[52:55], v[198:201], v[156:159], v[52:55]
	v_mfma_f32_16x16x32_bf16 v[48:51], v[198:201], v[160:163], v[48:51]
	v_mfma_f32_16x16x32_bf16 v[44:47], v[198:201], v[164:167], v[44:47]
	v_mfma_f32_16x16x32_bf16 v[40:43], v[202:205], v[152:155], v[40:43]
	v_mfma_f32_16x16x32_bf16 v[36:39], v[202:205], v[156:159], v[36:39]
	v_mfma_f32_16x16x32_bf16 v[32:35], v[202:205], v[160:163], v[32:35]
	v_mfma_f32_16x16x32_bf16 v[28:31], v[202:205], v[164:167], v[28:31]
	v_mfma_f32_16x16x32_bf16 v[24:27], v[206:209], v[152:155], v[24:27]
	v_mfma_f32_16x16x32_bf16 v[20:23], v[206:209], v[156:159], v[20:23]
	v_mfma_f32_16x16x32_bf16 v[16:19], v[206:209], v[160:163], v[16:19]
	v_mfma_f32_16x16x32_bf16 v[12:15], v[206:209], v[164:167], v[12:15]
	v_mfma_f32_16x16x32_bf16 v[8:11], v[210:213], v[152:155], v[8:11]
	v_mfma_f32_16x16x32_bf16 v[4:7], v[210:213], v[156:159], v[4:7]
	v_mfma_f32_16x16x32_bf16 v[0:3], v[210:213], v[160:163], v[0:3]
	v_mfma_f32_16x16x32_bf16 v[88:91], v[210:213], v[164:167], v[88:91]
	ds_read_b128 v[152:155], v134 offset:8192
	ds_read_b128 v[156:159], v134 offset:10240
	ds_read_b128 v[160:163], v134 offset:12288
	ds_read_b128 v[164:167], v134 offset:14336
	s_waitcnt lgkmcnt(4)
	v_mfma_f32_16x16x32_bf16 v[124:127], v[214:217], v[168:171], v[124:127]
	v_mfma_f32_16x16x32_bf16 v[120:123], v[214:217], v[172:175], v[120:123]
	v_mfma_f32_16x16x32_bf16 v[116:119], v[214:217], v[176:179], v[116:119]
	v_mfma_f32_16x16x32_bf16 v[112:115], v[214:217], v[180:183], v[112:115]
	v_mfma_f32_16x16x32_bf16 v[108:111], v[218:221], v[168:171], v[108:111]
	v_mfma_f32_16x16x32_bf16 v[104:107], v[218:221], v[172:175], v[104:107]
	v_mfma_f32_16x16x32_bf16 v[100:103], v[218:221], v[176:179], v[100:103]
	v_mfma_f32_16x16x32_bf16 v[96:99], v[218:221], v[180:183], v[96:99]
	v_mfma_f32_16x16x32_bf16 v[92:95], v[222:225], v[168:171], v[92:95]
	v_mfma_f32_16x16x32_bf16 v[84:87], v[222:225], v[172:175], v[84:87]
	v_mfma_f32_16x16x32_bf16 v[80:83], v[222:225], v[176:179], v[80:83]
	v_mfma_f32_16x16x32_bf16 v[76:79], v[222:225], v[180:183], v[76:79]
	v_mfma_f32_16x16x32_bf16 v[72:75], v[226:229], v[168:171], v[72:75]
	v_mfma_f32_16x16x32_bf16 v[68:71], v[226:229], v[172:175], v[68:71]
	v_mfma_f32_16x16x32_bf16 v[64:67], v[226:229], v[176:179], v[64:67]
	v_mfma_f32_16x16x32_bf16 v[60:63], v[226:229], v[180:183], v[60:63]
	s_waitcnt lgkmcnt(0)
	v_mfma_f32_16x16x32_bf16 v[56:59], v[152:155], v[168:171], v[56:59]
	s_waitcnt vmcnt(0)
	s_barrier
	v_add3_u32 v210, v151, v149, s99
	v_add3_u32 v134, v151, v148, s99
	v_mfma_f32_16x16x32_bf16 v[52:55], v[152:155], v[172:175], v[52:55]
	ds_read_b128 v[198:201], v210 offset:32768
	ds_read_b128 v[202:205], v210 offset:34816
	v_mfma_f32_16x16x32_bf16 v[48:51], v[152:155], v[176:179], v[48:51]
	ds_read_b128 v[206:209], v210 offset:36864
	ds_read_b128 v[210:213], v210 offset:38912
	v_mfma_f32_16x16x32_bf16 v[44:47], v[152:155], v[180:183], v[44:47]
	ds_read_b128 v[214:217], v134 offset:0
	ds_read_b128 v[218:221], v134 offset:2048
	v_mfma_f32_16x16x32_bf16 v[40:43], v[156:159], v[168:171], v[40:43]
	ds_read_b128 v[222:225], v134 offset:4096
	ds_read_b128 v[226:229], v134 offset:6144
	s_mov_b32 m0, s12
	v_mfma_f32_16x16x32_bf16 v[36:39], v[156:159], v[172:175], v[36:39]
	global_load_lds_dwordx4 v[128:129], off
	v_lshl_add_u64 v[128:129], v[128:129], 0, s[100:101]
	s_add_i32 m0, s12, 0x8000
	v_mfma_f32_16x16x32_bf16 v[32:35], v[156:159], v[176:179], v[32:35]
	global_load_lds_dwordx4 v[140:141], off
	v_lshl_add_u64 v[140:141], v[140:141], 0, s[100:101]
	s_mov_b32 m0, s13
	v_mfma_f32_16x16x32_bf16 v[28:31], v[156:159], v[180:183], v[28:31]
	global_load_lds_dwordx4 v[130:131], off
	v_lshl_add_u64 v[130:131], v[130:131], 0, s[100:101]
	s_add_i32 m0, s13, 0x8000
	v_mfma_f32_16x16x32_bf16 v[24:27], v[160:163], v[168:171], v[24:27]
	global_load_lds_dwordx4 v[142:143], off
	v_lshl_add_u64 v[142:143], v[142:143], 0, s[100:101]
	s_mov_b32 m0, s29
	v_mfma_f32_16x16x32_bf16 v[20:23], v[160:163], v[172:175], v[20:23]
	global_load_lds_dwordx4 v[136:137], off
	v_lshl_add_u64 v[136:137], v[136:137], 0, s[100:101]
	s_add_i32 m0, s29, 0x8000
	v_mfma_f32_16x16x32_bf16 v[16:19], v[160:163], v[176:179], v[16:19]
	global_load_lds_dwordx4 v[144:145], off
	v_lshl_add_u64 v[144:145], v[144:145], 0, s[100:101]
	s_mov_b32 m0, s31
	v_mfma_f32_16x16x32_bf16 v[12:15], v[160:163], v[180:183], v[12:15]
	global_load_lds_dwordx4 v[138:139], off
	v_lshl_add_u64 v[138:139], v[138:139], 0, s[100:101]
	s_add_i32 m0, s31, 0x8000
	v_mfma_f32_16x16x32_bf16 v[8:11], v[164:167], v[168:171], v[8:11]
	global_load_lds_dwordx4 v[146:147], off
	v_lshl_add_u64 v[146:147], v[146:147], 0, s[100:101]
	v_mfma_f32_16x16x32_bf16 v[4:7], v[164:167], v[172:175], v[4:7]
	v_mfma_f32_16x16x32_bf16 v[0:3], v[164:167], v[176:179], v[0:3]
	v_mfma_f32_16x16x32_bf16 v[88:91], v[164:167], v[180:183], v[88:91]
	ds_read_b128 v[152:155], v134 offset:8192
	ds_read_b128 v[156:159], v134 offset:10240
	ds_read_b128 v[160:163], v134 offset:12288
	ds_read_b128 v[164:167], v134 offset:14336
	s_waitcnt lgkmcnt(4)
	v_mfma_f32_16x16x32_bf16 v[124:127], v[214:217], v[198:201], v[124:127]
	v_mfma_f32_16x16x32_bf16 v[120:123], v[214:217], v[202:205], v[120:123]
	v_mfma_f32_16x16x32_bf16 v[116:119], v[214:217], v[206:209], v[116:119]
	v_mfma_f32_16x16x32_bf16 v[112:115], v[214:217], v[210:213], v[112:115]
	v_mfma_f32_16x16x32_bf16 v[108:111], v[218:221], v[198:201], v[108:111]
	v_mfma_f32_16x16x32_bf16 v[104:107], v[218:221], v[202:205], v[104:107]
	v_mfma_f32_16x16x32_bf16 v[100:103], v[218:221], v[206:209], v[100:103]
	v_mfma_f32_16x16x32_bf16 v[96:99], v[218:221], v[210:213], v[96:99]
	v_mfma_f32_16x16x32_bf16 v[92:95], v[222:225], v[198:201], v[92:95]
	v_mfma_f32_16x16x32_bf16 v[84:87], v[222:225], v[202:205], v[84:87]
	v_mfma_f32_16x16x32_bf16 v[80:83], v[222:225], v[206:209], v[80:83]
	v_mfma_f32_16x16x32_bf16 v[76:79], v[222:225], v[210:213], v[76:79]
	v_mfma_f32_16x16x32_bf16 v[72:75], v[226:229], v[198:201], v[72:75]
	v_mfma_f32_16x16x32_bf16 v[68:71], v[226:229], v[202:205], v[68:71]
	v_mfma_f32_16x16x32_bf16 v[64:67], v[226:229], v[206:209], v[64:67]
	v_mfma_f32_16x16x32_bf16 v[60:63], v[226:229], v[210:213], v[60:63]
	v_add3_u32 v226, v150, v149, s99
	v_add3_u32 v134, v150, v148, s99
	ds_read_b128 v[214:217], v226 offset:32768
	ds_read_b128 v[218:221], v226 offset:34816
	ds_read_b128 v[222:225], v226 offset:36864
	ds_read_b128 v[226:229], v226 offset:38912
	ds_read_b128 v[168:171], v134 offset:0
	ds_read_b128 v[172:175], v134 offset:2048
	ds_read_b128 v[176:179], v134 offset:4096
	ds_read_b128 v[180:183], v134 offset:6144
	s_waitcnt lgkmcnt(8)
	v_mfma_f32_16x16x32_bf16 v[56:59], v[152:155], v[198:201], v[56:59]
	v_mfma_f32_16x16x32_bf16 v[52:55], v[152:155], v[202:205], v[52:55]
	v_mfma_f32_16x16x32_bf16 v[48:51], v[152:155], v[206:209], v[48:51]
	v_mfma_f32_16x16x32_bf16 v[44:47], v[152:155], v[210:213], v[44:47]
	v_mfma_f32_16x16x32_bf16 v[40:43], v[156:159], v[198:201], v[40:43]
	v_mfma_f32_16x16x32_bf16 v[36:39], v[156:159], v[202:205], v[36:39]
	v_mfma_f32_16x16x32_bf16 v[32:35], v[156:159], v[206:209], v[32:35]
	v_mfma_f32_16x16x32_bf16 v[28:31], v[156:159], v[210:213], v[28:31]
	v_mfma_f32_16x16x32_bf16 v[24:27], v[160:163], v[198:201], v[24:27]
	v_mfma_f32_16x16x32_bf16 v[20:23], v[160:163], v[202:205], v[20:23]
	v_mfma_f32_16x16x32_bf16 v[16:19], v[160:163], v[206:209], v[16:19]
	v_mfma_f32_16x16x32_bf16 v[12:15], v[160:163], v[210:213], v[12:15]
	v_mfma_f32_16x16x32_bf16 v[8:11], v[164:167], v[198:201], v[8:11]
	v_mfma_f32_16x16x32_bf16 v[4:7], v[164:167], v[202:205], v[4:7]
	v_mfma_f32_16x16x32_bf16 v[0:3], v[164:167], v[206:209], v[0:3]
	v_mfma_f32_16x16x32_bf16 v[88:91], v[164:167], v[210:213], v[88:91]
	ds_read_b128 v[198:201], v134 offset:8192
	ds_read_b128 v[202:205], v134 offset:10240
	ds_read_b128 v[206:209], v134 offset:12288
	ds_read_b128 v[210:213], v134 offset:14336
	s_waitcnt lgkmcnt(4)
	v_mfma_f32_16x16x32_bf16 v[124:127], v[168:171], v[214:217], v[124:127]
	v_mfma_f32_16x16x32_bf16 v[120:123], v[168:171], v[218:221], v[120:123]
	v_mfma_f32_16x16x32_bf16 v[116:119], v[168:171], v[222:225], v[116:119]
	v_mfma_f32_16x16x32_bf16 v[112:115], v[168:171], v[226:229], v[112:115]
	v_mfma_f32_16x16x32_bf16 v[108:111], v[172:175], v[214:217], v[108:111]
	v_mfma_f32_16x16x32_bf16 v[104:107], v[172:175], v[218:221], v[104:107]
	v_mfma_f32_16x16x32_bf16 v[100:103], v[172:175], v[222:225], v[100:103]
	v_mfma_f32_16x16x32_bf16 v[96:99], v[172:175], v[226:229], v[96:99]
	v_mfma_f32_16x16x32_bf16 v[92:95], v[176:179], v[214:217], v[92:95]
	v_mfma_f32_16x16x32_bf16 v[84:87], v[176:179], v[218:221], v[84:87]
	v_mfma_f32_16x16x32_bf16 v[80:83], v[176:179], v[222:225], v[80:83]
	v_mfma_f32_16x16x32_bf16 v[76:79], v[176:179], v[226:229], v[76:79]
	v_mfma_f32_16x16x32_bf16 v[72:75], v[180:183], v[214:217], v[72:75]
	v_mfma_f32_16x16x32_bf16 v[68:71], v[180:183], v[218:221], v[68:71]
	v_mfma_f32_16x16x32_bf16 v[64:67], v[180:183], v[222:225], v[64:67]
	v_mfma_f32_16x16x32_bf16 v[60:63], v[180:183], v[226:229], v[60:63]
	s_waitcnt lgkmcnt(0)
	v_mfma_f32_16x16x32_bf16 v[56:59], v[198:201], v[214:217], v[56:59]
	s_waitcnt vmcnt(0)
	s_barrier
	v_add_u32_e32 v164, v151, v149
	v_add_u32_e32 v134, v151, v148
	v_mfma_f32_16x16x32_bf16 v[52:55], v[198:201], v[218:221], v[52:55]
	ds_read_b128 v[152:155], v164 offset:32768
	ds_read_b128 v[156:159], v164 offset:34816
	v_mfma_f32_16x16x32_bf16 v[48:51], v[198:201], v[222:225], v[48:51]
	ds_read_b128 v[160:163], v164 offset:36864
	ds_read_b128 v[164:167], v164 offset:38912
	v_mfma_f32_16x16x32_bf16 v[44:47], v[198:201], v[226:229], v[44:47]
	ds_read_b128 v[168:171], v134 offset:0
	ds_read_b128 v[172:175], v134 offset:2048
	v_mfma_f32_16x16x32_bf16 v[40:43], v[202:205], v[214:217], v[40:43]
	ds_read_b128 v[176:179], v134 offset:4096
	ds_read_b128 v[180:183], v134 offset:6144
	s_add_i32 m0, s12, 0x10000
	v_mfma_f32_16x16x32_bf16 v[36:39], v[202:205], v[218:221], v[36:39]
	global_load_lds_dwordx4 v[128:129], off
	v_lshl_add_u64 v[128:129], v[128:129], 0, s[100:101]
	s_add_i32 m0, s12, 0x18000
	v_mfma_f32_16x16x32_bf16 v[32:35], v[202:205], v[222:225], v[32:35]
	global_load_lds_dwordx4 v[140:141], off
	v_lshl_add_u64 v[140:141], v[140:141], 0, s[100:101]
	s_add_i32 m0, s13, 0x10000
	v_mfma_f32_16x16x32_bf16 v[28:31], v[202:205], v[226:229], v[28:31]
	global_load_lds_dwordx4 v[130:131], off
	v_lshl_add_u64 v[130:131], v[130:131], 0, s[100:101]
	s_add_i32 m0, s13, 0x18000
	v_mfma_f32_16x16x32_bf16 v[24:27], v[206:209], v[214:217], v[24:27]
	global_load_lds_dwordx4 v[142:143], off
	v_lshl_add_u64 v[142:143], v[142:143], 0, s[100:101]
	s_add_i32 m0, s29, 0x10000
	v_mfma_f32_16x16x32_bf16 v[20:23], v[206:209], v[218:221], v[20:23]
	global_load_lds_dwordx4 v[136:137], off
	v_lshl_add_u64 v[136:137], v[136:137], 0, s[100:101]
	s_add_i32 m0, s29, 0x18000
	v_mfma_f32_16x16x32_bf16 v[16:19], v[206:209], v[222:225], v[16:19]
	global_load_lds_dwordx4 v[144:145], off
	v_lshl_add_u64 v[144:145], v[144:145], 0, s[100:101]
	s_add_i32 m0, s31, 0x10000
	v_mfma_f32_16x16x32_bf16 v[12:15], v[206:209], v[226:229], v[12:15]
	global_load_lds_dwordx4 v[138:139], off
	v_lshl_add_u64 v[138:139], v[138:139], 0, s[100:101]
	s_add_i32 m0, s31, 0x18000
	v_mfma_f32_16x16x32_bf16 v[8:11], v[210:213], v[214:217], v[8:11]
	global_load_lds_dwordx4 v[146:147], off
	v_lshl_add_u64 v[146:147], v[146:147], 0, s[100:101]
	v_mfma_f32_16x16x32_bf16 v[4:7], v[210:213], v[218:221], v[4:7]
	v_mfma_f32_16x16x32_bf16 v[0:3], v[210:213], v[222:225], v[0:3]
	v_mfma_f32_16x16x32_bf16 v[88:91], v[210:213], v[226:229], v[88:91]
	s_add_u32 s4, s4, 0x100
	s_cmpk_lg_i32 s4, 0x1500
	s_cbranch_scc1 .Lg_down_loop
	ds_read_b128 v[198:201], v134 offset:8192
	ds_read_b128 v[202:205], v134 offset:10240
	ds_read_b128 v[206:209], v134 offset:12288
	ds_read_b128 v[210:213], v134 offset:14336
	s_waitcnt lgkmcnt(4)
	v_mfma_f32_16x16x32_bf16 v[124:127], v[168:171], v[152:155], v[124:127]
	v_mfma_f32_16x16x32_bf16 v[120:123], v[168:171], v[156:159], v[120:123]
	v_mfma_f32_16x16x32_bf16 v[116:119], v[168:171], v[160:163], v[116:119]
	v_mfma_f32_16x16x32_bf16 v[112:115], v[168:171], v[164:167], v[112:115]
	v_mfma_f32_16x16x32_bf16 v[108:111], v[172:175], v[152:155], v[108:111]
	v_mfma_f32_16x16x32_bf16 v[104:107], v[172:175], v[156:159], v[104:107]
	v_mfma_f32_16x16x32_bf16 v[100:103], v[172:175], v[160:163], v[100:103]
	v_mfma_f32_16x16x32_bf16 v[96:99], v[172:175], v[164:167], v[96:99]
	v_mfma_f32_16x16x32_bf16 v[92:95], v[176:179], v[152:155], v[92:95]
	v_mfma_f32_16x16x32_bf16 v[84:87], v[176:179], v[156:159], v[84:87]
	v_mfma_f32_16x16x32_bf16 v[80:83], v[176:179], v[160:163], v[80:83]
	v_mfma_f32_16x16x32_bf16 v[76:79], v[176:179], v[164:167], v[76:79]
	v_mfma_f32_16x16x32_bf16 v[72:75], v[180:183], v[152:155], v[72:75]
	v_mfma_f32_16x16x32_bf16 v[68:71], v[180:183], v[156:159], v[68:71]
	v_mfma_f32_16x16x32_bf16 v[64:67], v[180:183], v[160:163], v[64:67]
	v_mfma_f32_16x16x32_bf16 v[60:63], v[180:183], v[164:167], v[60:63]
	v_add_u32_e32 v180, v150, v149
	v_add_u32_e32 v134, v150, v148
	ds_read_b128 v[168:171], v180 offset:32768
	ds_read_b128 v[172:175], v180 offset:34816
	ds_read_b128 v[176:179], v180 offset:36864
	ds_read_b128 v[180:183], v180 offset:38912
	ds_read_b128 v[214:217], v134 offset:0
	ds_read_b128 v[218:221], v134 offset:2048
	ds_read_b128 v[222:225], v134 offset:4096
	ds_read_b128 v[226:229], v134 offset:6144
	s_waitcnt lgkmcnt(8)
	v_mfma_f32_16x16x32_bf16 v[56:59], v[198:201], v[152:155], v[56:59]
	v_mfma_f32_16x16x32_bf16 v[52:55], v[198:201], v[156:159], v[52:55]
	v_mfma_f32_16x16x32_bf16 v[48:51], v[198:201], v[160:163], v[48:51]
	v_mfma_f32_16x16x32_bf16 v[44:47], v[198:201], v[164:167], v[44:47]
	v_mfma_f32_16x16x32_bf16 v[40:43], v[202:205], v[152:155], v[40:43]
	v_mfma_f32_16x16x32_bf16 v[36:39], v[202:205], v[156:159], v[36:39]
	v_mfma_f32_16x16x32_bf16 v[32:35], v[202:205], v[160:163], v[32:35]
	v_mfma_f32_16x16x32_bf16 v[28:31], v[202:205], v[164:167], v[28:31]
	v_mfma_f32_16x16x32_bf16 v[24:27], v[206:209], v[152:155], v[24:27]
	v_mfma_f32_16x16x32_bf16 v[20:23], v[206:209], v[156:159], v[20:23]
	v_mfma_f32_16x16x32_bf16 v[16:19], v[206:209], v[160:163], v[16:19]
	v_mfma_f32_16x16x32_bf16 v[12:15], v[206:209], v[164:167], v[12:15]
	v_mfma_f32_16x16x32_bf16 v[8:11], v[210:213], v[152:155], v[8:11]
	v_mfma_f32_16x16x32_bf16 v[4:7], v[210:213], v[156:159], v[4:7]
	v_mfma_f32_16x16x32_bf16 v[0:3], v[210:213], v[160:163], v[0:3]
	v_mfma_f32_16x16x32_bf16 v[88:91], v[210:213], v[164:167], v[88:91]
	ds_read_b128 v[152:155], v134 offset:8192
	ds_read_b128 v[156:159], v134 offset:10240
	ds_read_b128 v[160:163], v134 offset:12288
	ds_read_b128 v[164:167], v134 offset:14336
	s_waitcnt lgkmcnt(4)
	v_mfma_f32_16x16x32_bf16 v[124:127], v[214:217], v[168:171], v[124:127]
	v_mfma_f32_16x16x32_bf16 v[120:123], v[214:217], v[172:175], v[120:123]
	v_mfma_f32_16x16x32_bf16 v[116:119], v[214:217], v[176:179], v[116:119]
	v_mfma_f32_16x16x32_bf16 v[112:115], v[214:217], v[180:183], v[112:115]
	v_mfma_f32_16x16x32_bf16 v[108:111], v[218:221], v[168:171], v[108:111]
	v_mfma_f32_16x16x32_bf16 v[104:107], v[218:221], v[172:175], v[104:107]
	v_mfma_f32_16x16x32_bf16 v[100:103], v[218:221], v[176:179], v[100:103]
	v_mfma_f32_16x16x32_bf16 v[96:99], v[218:221], v[180:183], v[96:99]
	v_mfma_f32_16x16x32_bf16 v[92:95], v[222:225], v[168:171], v[92:95]
	v_mfma_f32_16x16x32_bf16 v[84:87], v[222:225], v[172:175], v[84:87]
	v_mfma_f32_16x16x32_bf16 v[80:83], v[222:225], v[176:179], v[80:83]
	v_mfma_f32_16x16x32_bf16 v[76:79], v[222:225], v[180:183], v[76:79]
	v_mfma_f32_16x16x32_bf16 v[72:75], v[226:229], v[168:171], v[72:75]
	v_mfma_f32_16x16x32_bf16 v[68:71], v[226:229], v[172:175], v[68:71]
	v_mfma_f32_16x16x32_bf16 v[64:67], v[226:229], v[176:179], v[64:67]
	v_mfma_f32_16x16x32_bf16 v[60:63], v[226:229], v[180:183], v[60:63]
	s_waitcnt lgkmcnt(0)
	v_mfma_f32_16x16x32_bf16 v[56:59], v[152:155], v[168:171], v[56:59]
	s_waitcnt vmcnt(0)
	s_barrier
	v_mfma_f32_16x16x32_bf16 v[52:55], v[152:155], v[172:175], v[52:55]
	v_mfma_f32_16x16x32_bf16 v[48:51], v[152:155], v[176:179], v[48:51]
	v_mfma_f32_16x16x32_bf16 v[44:47], v[152:155], v[180:183], v[44:47]
	v_mfma_f32_16x16x32_bf16 v[40:43], v[156:159], v[168:171], v[40:43]
	v_mfma_f32_16x16x32_bf16 v[36:39], v[156:159], v[172:175], v[36:39]
	v_mfma_f32_16x16x32_bf16 v[32:35], v[156:159], v[176:179], v[32:35]
	v_mfma_f32_16x16x32_bf16 v[28:31], v[156:159], v[180:183], v[28:31]
	v_mfma_f32_16x16x32_bf16 v[24:27], v[160:163], v[168:171], v[24:27]
	v_mfma_f32_16x16x32_bf16 v[20:23], v[160:163], v[172:175], v[20:23]
	v_mfma_f32_16x16x32_bf16 v[16:19], v[160:163], v[176:179], v[16:19]
	v_mfma_f32_16x16x32_bf16 v[12:15], v[160:163], v[180:183], v[12:15]
	v_mfma_f32_16x16x32_bf16 v[8:11], v[164:167], v[168:171], v[8:11]
	v_mfma_f32_16x16x32_bf16 v[4:7], v[164:167], v[172:175], v[4:7]
	v_mfma_f32_16x16x32_bf16 v[0:3], v[164:167], v[176:179], v[0:3]
	v_mfma_f32_16x16x32_bf16 v[88:91], v[164:167], v[180:183], v[88:91]
	s_movk_i32 s4, 0x1580
	s_mov_b32 s86, 0x10000
	s_mov_b32 s87, 0x2b0000
	s_mov_b32 s44, 0x2b0000
	v_add_u32_e32 v134, s86, v151
	v_add_u32_e32 v144, v134, v149
	v_add_u32_e32 v134, v134, v148
	ds_read_b128 v[128:131], v144 offset:32768
	ds_read_b128 v[136:139], v144 offset:34816
	ds_read_b128 v[140:143], v144 offset:36864
	ds_read_b128 v[144:147], v144 offset:38912
	ds_read_b128 v[152:155], v134
	ds_read_b128 v[156:159], v134 offset:2048
	ds_read_b128 v[160:163], v134 offset:4096
	ds_read_b128 v[164:167], v134 offset:6144
	ds_read_b128 v[168:171], v134 offset:8192
	ds_read_b128 v[172:175], v134 offset:10240
	ds_read_b128 v[176:179], v134 offset:12288
	ds_read_b128 v[180:183], v134 offset:14336
	s_waitcnt lgkmcnt(0)
	v_mfma_f32_16x16x32_bf16 v[124:127], v[152:155], v[128:131], v[124:127]
	v_mfma_f32_16x16x32_bf16 v[120:123], v[152:155], v[136:139], v[120:123]
	v_mfma_f32_16x16x32_bf16 v[116:119], v[152:155], v[140:143], v[116:119]
	v_mfma_f32_16x16x32_bf16 v[112:115], v[152:155], v[144:147], v[112:115]
	v_mfma_f32_16x16x32_bf16 v[108:111], v[156:159], v[128:131], v[108:111]
	v_mfma_f32_16x16x32_bf16 v[104:107], v[156:159], v[136:139], v[104:107]
	v_mfma_f32_16x16x32_bf16 v[100:103], v[156:159], v[140:143], v[100:103]
	v_mfma_f32_16x16x32_bf16 v[96:99], v[156:159], v[144:147], v[96:99]
	v_mfma_f32_16x16x32_bf16 v[84:87], v[160:163], v[136:139], v[84:87]
	v_mfma_f32_16x16x32_bf16 v[76:79], v[160:163], v[144:147], v[76:79]
	v_mfma_f32_16x16x32_bf16 v[72:75], v[164:167], v[128:131], v[72:75]
	v_mfma_f32_16x16x32_bf16 v[68:71], v[164:167], v[136:139], v[68:71]
	v_mfma_f32_16x16x32_bf16 v[64:67], v[164:167], v[140:143], v[64:67]
	v_mfma_f32_16x16x32_bf16 v[152:155], v[160:163], v[128:131], v[92:95]
	v_mfma_f32_16x16x32_bf16 v[156:159], v[160:163], v[140:143], v[80:83]
	v_mfma_f32_16x16x32_bf16 v[160:163], v[164:167], v[144:147], v[60:63]
	s_nop 2
	v_add_u32_e32 v60, s86, v150
	v_add_u32_e32 v61, v60, v149
	v_add_u32_e32 v60, v60, v148
	ds_read_b128 v[164:167], v61 offset:32768
	ds_read_b128 v[198:201], v61 offset:34816
	ds_read_b128 v[202:205], v61 offset:36864
	ds_read_b128 v[206:209], v61 offset:38912
	ds_read_b128 v[80:83], v60
	ds_read_b128 v[148:151], v60 offset:2048
	ds_read_b128 v[210:213], v60 offset:4096
	ds_read_b128 v[214:217], v60 offset:6144
	v_mfma_f32_16x16x32_bf16 v[56:59], v[168:171], v[128:131], v[56:59]
	v_mfma_f32_16x16x32_bf16 v[218:221], v[168:171], v[136:139], v[52:55]
	v_mfma_f32_16x16x32_bf16 v[222:225], v[168:171], v[140:143], v[48:51]
	v_mfma_f32_16x16x32_bf16 v[44:47], v[168:171], v[144:147], v[44:47]
	v_mfma_f32_16x16x32_bf16 v[168:171], v[172:175], v[128:131], v[40:43]
	v_mfma_f32_16x16x32_bf16 v[226:229], v[172:175], v[136:139], v[36:39]
	v_mfma_f32_16x16x32_bf16 v[32:35], v[172:175], v[140:143], v[32:35]
	v_mfma_f32_16x16x32_bf16 v[28:31], v[172:175], v[144:147], v[28:31]
	v_mfma_f32_16x16x32_bf16 v[172:175], v[176:179], v[128:131], v[24:27]
	v_mfma_f32_16x16x32_bf16 v[16:19], v[176:179], v[140:143], v[16:19]
	v_mfma_f32_16x16x32_bf16 v[128:131], v[180:183], v[128:131], v[8:11]
	v_mfma_f32_16x16x32_bf16 v[230:233], v[176:179], v[136:139], v[20:23]
	v_mfma_f32_16x16x32_bf16 v[176:179], v[176:179], v[144:147], v[12:15]
	v_mfma_f32_16x16x32_bf16 v[234:237], v[180:183], v[136:139], v[4:7]
	v_mfma_f32_16x16x32_bf16 v[140:143], v[180:183], v[140:143], v[0:3]
	v_mfma_f32_16x16x32_bf16 v[144:147], v[180:183], v[144:147], v[88:91]
	s_nop 1
	ds_read_b128 v[0:3], v60 offset:8192
	ds_read_b128 v[136:139], v60 offset:10240
	ds_read_b128 v[180:183], v60 offset:12288
	ds_read_b128 v[238:241], v60 offset:14336
	s_waitcnt lgkmcnt(0)
	v_mfma_f32_16x16x32_bf16 v[124:127], v[80:83], v[164:167], v[124:127]
	v_mfma_f32_16x16x32_bf16 v[92:95], v[80:83], v[198:201], v[120:123]
	v_mfma_f32_16x16x32_bf16 v[60:63], v[80:83], v[202:205], v[116:119]
	v_mfma_f32_16x16x32_bf16 v[24:27], v[80:83], v[206:209], v[112:115]
	v_mfma_f32_16x16x32_bf16 v[120:123], v[148:151], v[164:167], v[108:111]
	v_mfma_f32_16x16x32_bf16 v[88:91], v[148:151], v[198:201], v[104:107]
	v_mfma_f32_16x16x32_bf16 v[52:55], v[148:151], v[202:205], v[100:103]
	v_mfma_f32_16x16x32_bf16 v[20:23], v[148:151], v[206:209], v[96:99]
	v_mfma_f32_16x16x32_bf16 v[116:119], v[210:213], v[164:167], v[152:155]
	v_mfma_f32_16x16x32_bf16 v[80:83], v[210:213], v[198:201], v[84:87]
	v_mfma_f32_16x16x32_bf16 v[48:51], v[210:213], v[202:205], v[156:159]
	v_mfma_f32_16x16x32_bf16 v[12:15], v[210:213], v[206:209], v[76:79]
	v_mfma_f32_16x16x32_bf16 v[108:111], v[214:217], v[164:167], v[72:75]
	v_mfma_f32_16x16x32_bf16 v[76:79], v[214:217], v[198:201], v[68:71]
	v_mfma_f32_16x16x32_bf16 v[40:43], v[214:217], v[202:205], v[64:67]
	v_mfma_f32_16x16x32_bf16 v[8:11], v[214:217], v[206:209], v[160:163]
	v_mfma_f32_16x16x32_bf16 v[104:107], v[0:3], v[164:167], v[56:59]
	s_waitcnt vmcnt(0)
	s_waitcnt lgkmcnt(0)
	s_barrier
	v_mfma_f32_16x16x32_bf16 v[68:71], v[0:3], v[198:201], v[218:221]
	v_cvt_pk_bf16_f32 v134, v124, v125
	v_mfma_f32_16x16x32_bf16 v[36:39], v[0:3], v[202:205], v[222:225]
	v_mfma_f32_16x16x32_bf16 v[4:7], v[0:3], v[206:209], v[44:47]
	v_mfma_f32_16x16x32_bf16 v[100:103], v[136:139], v[164:167], v[168:171]
	v_mfma_f32_16x16x32_bf16 v[64:67], v[136:139], v[198:201], v[226:229]
	v_mfma_f32_16x16x32_bf16 v[32:35], v[136:139], v[202:205], v[32:35]
	v_mfma_f32_16x16x32_bf16 v[0:3], v[136:139], v[206:209], v[28:31]
	v_mov_b32_e32 v137, v184
	v_cvt_pk_bf16_f32 v136, v126, v127
	v_mfma_f32_16x16x32_bf16 v[96:99], v[180:183], v[164:167], v[172:175]
	v_and_b32_e32 v28, 16, v137
	v_cmp_eq_u32_e64 s[4:5], 0, v28
	v_cmp_ne_u32_e32 vcc, 0, v28
	v_mfma_f32_16x16x32_bf16 v[72:75], v[180:183], v[198:201], v[230:233]
	v_cvt_pk_bf16_f32 v138, v120, v121
	v_cvt_pk_bf16_f32 v139, v122, v123
	v_mfma_f32_16x16x32_bf16 v[44:47], v[180:183], v[202:205], v[16:19]
	v_mfma_f32_16x16x32_bf16 v[16:19], v[180:183], v[206:209], v[176:179]
	v_mfma_f32_16x16x32_bf16 v[112:115], v[238:241], v[164:167], v[128:131]
	v_mfma_f32_16x16x32_bf16 v[84:87], v[238:241], v[198:201], v[234:237]
	s_nop 1
	v_mov_b32_e32 v128, v134
	v_mov_b32_e32 v130, v138
	v_mov_b32_e32 v131, v139
	v_mfma_f32_16x16x32_bf16 v[56:59], v[238:241], v[202:205], v[140:143]
	v_mov_b32_e32 v129, v136
	v_permlane16_swap_b32_e32 v128, v130
	v_mfma_f32_16x16x32_bf16 v[28:31], v[238:241], v[206:209], v[144:147]
	v_permlane16_swap_b32_e32 v129, v131
	s_and_saveexec_b64 s[12:13], vcc
	s_xor_b64 s[12:13], exec, s[12:13]
	v_mov_b32_e32 v131, v139
	v_mov_b32_e32 v130, v138
	s_andn2_saveexec_b64 s[12:13], s[12:13]
	v_mov_b32_e32 v128, v134
	v_mov_b32_e32 v129, v136
	s_or_b64 exec, exec, s[12:13]
	v_ashrrev_i32_e32 v136, 8, v137
	v_bfe_u32 v134, v137, 4, 2
	v_and_b32_e32 v137, 0xcf, v137
	v_lshlrev_b32_e32 v138, 2, v134
	v_lshl_or_b32 v140, s22, 8, v137
	v_add_u32_e32 v139, 12, v138
	v_ashrrev_i32_e32 v141, 31, v140
	v_cndmask_b32_e64 v138, v139, v138, s[4:5]
	v_lshlrev_b64 v[142:143], 11, v[140:141]
	s_lshl_b32 s44, s24, 8
	v_lshl_or_b32 v138, v136, 7, v138
	v_lshl_add_u64 v[142:143], s[8:9], 0, v[142:143]
	v_lshl_add_u64 v[142:143], s[44:45], 1, v[142:143]
	v_ashrrev_i32_e32 v139, 31, v138
	v_lshl_add_u64 v[142:143], v[138:139], 1, v[142:143]
	v_cvt_pk_bf16_f32 v137, v116, v117
	v_cvt_pk_bf16_f32 v144, v118, v119
	v_cvt_pk_bf16_f32 v145, v108, v109
	v_cvt_pk_bf16_f32 v146, v110, v111
	global_store_dwordx4 v[142:143], v[128:131], off nt
	s_nop 1
	v_mov_b32_e32 v128, v137
	v_mov_b32_e32 v130, v145
	v_mov_b32_e32 v129, v144
	v_mov_b32_e32 v131, v146
	v_permlane16_swap_b32_e32 v128, v130
	s_nop 0
	v_permlane16_swap_b32_e32 v129, v131
	s_and_saveexec_b64 s[4:5], vcc
	s_xor_b64 s[4:5], exec, s[4:5]
	v_mov_b32_e32 v131, v146
	v_mov_b32_e32 v130, v145
	s_andn2_saveexec_b64 s[4:5], s[4:5]
	v_mov_b32_e32 v128, v137
	v_mov_b32_e32 v129, v144
	s_or_b64 exec, exec, s[4:5]
	v_cvt_pk_bf16_f32 v137, v104, v105
	v_cvt_pk_bf16_f32 v144, v106, v107
	v_cvt_pk_bf16_f32 v145, v100, v101
	v_cvt_pk_bf16_f32 v146, v102, v103
	global_store_dwordx4 v[142:143], v[128:131], off offset:64 nt
	s_nop 1
	v_mov_b32_e32 v128, v137
	v_mov_b32_e32 v130, v145
	v_mov_b32_e32 v129, v144
	v_mov_b32_e32 v131, v146
	v_permlane16_swap_b32_e32 v128, v130
	s_nop 0
	v_permlane16_swap_b32_e32 v129, v131
	s_and_saveexec_b64 s[4:5], vcc
	s_xor_b64 s[4:5], exec, s[4:5]
	v_mov_b32_e32 v131, v146
	v_mov_b32_e32 v130, v145
	s_andn2_saveexec_b64 s[4:5], s[4:5]
	v_mov_b32_e32 v128, v137
	v_mov_b32_e32 v129, v144
	s_or_b64 exec, exec, s[4:5]
	v_cvt_pk_bf16_f32 v137, v96, v97
	v_cvt_pk_bf16_f32 v144, v98, v99
	v_cvt_pk_bf16_f32 v145, v112, v113
	v_cvt_pk_bf16_f32 v146, v114, v115
	global_store_dwordx4 v[142:143], v[128:131], off offset:128 nt
	s_nop 1
	v_mov_b32_e32 v128, v137
	v_mov_b32_e32 v130, v145
	v_mov_b32_e32 v129, v144
	v_mov_b32_e32 v131, v146
	v_permlane16_swap_b32_e32 v128, v130
	s_nop 0
	v_permlane16_swap_b32_e32 v129, v131
	s_and_saveexec_b64 s[4:5], vcc
	s_xor_b64 s[4:5], exec, s[4:5]
	v_mov_b32_e32 v131, v146
	v_mov_b32_e32 v130, v145
	s_andn2_saveexec_b64 s[4:5], s[4:5]
	v_mov_b32_e32 v128, v137
	v_mov_b32_e32 v129, v144
	s_or_b64 exec, exec, s[4:5]
	v_mul_f32_e32 v125, v125, v125
	v_mul_f32_e32 v117, v117, v117
	v_fmac_f32_e32 v125, v124, v124
	v_fmac_f32_e32 v117, v116, v116
	v_mul_f32_e32 v105, v105, v105
	v_fmac_f32_e32 v125, v126, v126
	v_fmac_f32_e32 v117, v118, v118
	v_fmac_f32_e32 v105, v104, v104
	v_mul_f32_e32 v97, v97, v97
	v_fmac_f32_e32 v125, v127, v127
	v_fmac_f32_e32 v117, v119, v119
	v_fmac_f32_e32 v105, v106, v106
	v_fmac_f32_e32 v97, v96, v96
	v_fmac_f32_e32 v125, v120, v120
	v_fmac_f32_e32 v117, v108, v108
	v_fmac_f32_e32 v105, v107, v107
	v_fmac_f32_e32 v97, v98, v98
	v_fmac_f32_e32 v125, v121, v121
	v_fmac_f32_e32 v117, v109, v109
	v_fmac_f32_e32 v105, v100, v100
	v_fmac_f32_e32 v97, v99, v99
	v_fmac_f32_e32 v125, v122, v122
	v_fmac_f32_e32 v117, v110, v110
	v_fmac_f32_e32 v105, v101, v101
	v_fmac_f32_e32 v97, v112, v112
	v_fmac_f32_e32 v125, v123, v123
	v_fmac_f32_e32 v117, v111, v111
	v_fmac_f32_e32 v105, v102, v102
	v_fmac_f32_e32 v97, v113, v113
	v_add_f32_e32 v108, v125, v117
	v_fmac_f32_e32 v105, v103, v103
	v_fmac_f32_e32 v97, v114, v114
	v_add_f32_e32 v100, v108, v105
	v_fmac_f32_e32 v97, v115, v115
	v_add_f32_e32 v96, v100, v97
	v_mov_b32_e32 v97, v96
	s_nop 1
	v_permlane16_swap_b32_e32 v96, v97
	v_add_f32_e32 v96, v96, v97
	v_mov_b32_e32 v97, v96
	v_cmp_eq_u32_e64 s[4:5], 0, v134
	v_ashrrev_i32_e32 v137, 31, v136
	v_permlane32_swap_b32_e32 v96, v97
	global_store_dwordx4 v[142:143], v[128:131], off offset:192 nt
	s_and_saveexec_b64 s[12:13], s[4:5]
	s_cbranch_execz .LBB0_2374
	v_add_f32_e32 v98, v96, v97
	v_lshlrev_b64 v[96:97], 5, v[140:141]
	s_lshl_b32 s86, s24, 1
	s_mov_b32 s87, s45
	v_lshl_add_u64 v[96:97], s[10:11], 0, v[96:97]
	v_lshl_add_u64 v[96:97], s[86:87], 2, v[96:97]
	v_lshl_add_u64 v[96:97], v[136:137], 2, v[96:97]
	global_store_dword v[96:97], v98, off

.LBB0_2440:
	s_or_b64 exec, exec, s[22:23]
	v_ashrrev_i32_e32 v111, 31, v108
	v_lshrrev_b32_e32 v111, 20, v111
	v_add_u32_e32 v108, v108, v111
	v_ashrrev_i32_e32 v108, 12, v108
	v_mul_hi_i32_i24_e32 v113, 0x6000, v108
	v_mul_i32_i24_e32 v112, 0x6000, v108
	v_lshl_add_u64 v[120:121], v[86:87], 0, v[112:113]
	global_load_dwordx4 v[112:115], v[120:121], off
	global_load_dwordx4 v[116:119], v[120:121], off offset:16
	s_waitcnt vmcnt(14)
	v_mov_b32_e32 v108, v110
	s_waitcnt vmcnt(10)
	v_mov_b32_e32 v122, v109
	v_permlane32_swap_b32_e32 v110, v108
	s_nop 0
	v_permlane32_swap_b32_e32 v109, v122
	v_add_f32_e32 v111, v110, v108
	v_add_f32_e32 v110, v109, v122
	v_mov_b32_e32 v109, v111
	v_mov_b32_e32 v108, v110
	s_nop 0
	v_permlane16_swap_b32_e32 v111, v109
	v_permlane16_swap_b32_e32 v110, v108
	v_pk_add_f32 v[108:109], v[110:111], v[108:109]
	s_nop 1
	v_mov_b32_dpp v111, v109 row_ror:8 row_mask:0xf bank_mask:0xf
	s_nop 1
	v_mov_b32_dpp v110, v108 row_ror:8 row_mask:0xf bank_mask:0xf
	v_lshlrev_b32_e32 v126, 16, v72
	v_and_b32_e32 v127, 0xffff0000, v72
	v_lshlrev_b32_e32 v128, 16, v73
	v_and_b32_e32 v129, 0xffff0000, v73
	s_waitcnt lgkmcnt(0)
	v_pk_add_f32 v[108:109], v[108:109], v[110:111]
	s_nop 1
	v_mov_b32_dpp v111, v109 row_ror:4 row_mask:0xf bank_mask:0xf
	s_nop 1
	v_mov_b32_dpp v110, v108 row_ror:4 row_mask:0xf bank_mask:0xf
	v_mov_b64_e32 v[72:73], s[68:69]
	v_lshlrev_b32_e32 v130, 16, v74
	v_and_b32_e32 v131, 0xffff0000, v74
	v_lshlrev_b32_e32 v74, 16, v75
	s_waitcnt lgkmcnt(0)
	v_pk_add_f32 v[108:109], v[108:109], v[110:111]
	s_nop 1
	v_mov_b32_dpp v111, v109 row_ror:2 row_mask:0xf bank_mask:0xf
	s_nop 1
	v_mov_b32_dpp v110, v108 row_ror:2 row_mask:0xf bank_mask:0xf
	v_and_b32_e32 v75, 0xffff0000, v75
	v_lshlrev_b32_e32 v122, 16, v76
	v_and_b32_e32 v123, 0xffff0000, v76
	v_lshlrev_b32_e32 v76, 16, v77
	s_waitcnt lgkmcnt(0)
	v_pk_add_f32 v[108:109], v[108:109], v[110:111]
	s_nop 1
	v_mov_b32_dpp v111, v109 row_ror:1 row_mask:0xf bank_mask:0xf
	s_nop 1
	v_mov_b32_dpp v110, v108 row_ror:1 row_mask:0xf bank_mask:0xf
	v_and_b32_e32 v77, 0xffff0000, v77
	v_lshlrev_b32_e32 v124, 16, v78
	v_and_b32_e32 v125, 0xffff0000, v78
	v_lshlrev_b32_e32 v78, 16, v79
	s_waitcnt lgkmcnt(0)
	v_pk_add_f32 v[108:109], v[108:109], v[110:111]
	v_and_b32_e32 v79, 0xffff0000, v79
	v_pk_fma_f32 v[136:137], v[108:109], s[62:63], v[72:73] op_sel_hi:[1,0,0]
	v_lshl_add_u64 v[90:91], v[90:91], 0, s[38:39]
	v_mul_f32_e32 v108, 0x4b800000, v137
	v_cmp_gt_f32_e32 vcc, s67, v137
	v_lshl_add_u64 v[92:93], v[92:93], 0, s[40:41]
	s_nop 0
	v_cndmask_b32_e32 v108, v137, v108, vcc
	v_rsq_f32_e32 v108, v108
	s_nop 0
	v_mul_f32_e32 v109, 0x45800000, v108
	v_cndmask_b32_e32 v134, v108, v109, vcc
	v_pk_mul_f32 v[108:109], v[134:135], v[126:127] op_sel_hi:[0,1]
	v_pk_mul_f32 v[110:111], v[134:135], v[128:129] op_sel_hi:[0,1]
	v_pk_mul_f32 v[126:127], v[134:135], v[130:131] op_sel_hi:[0,1]
	v_pk_mul_f32 v[74:75], v[134:135], v[74:75] op_sel_hi:[0,1]
	v_pk_mul_f32 v[108:109], v[4:5], v[108:109]
	v_pk_mul_f32 v[110:111], v[6:7], v[110:111]
	v_pk_mul_f32 v[126:127], v[0:1], v[126:127]
	v_pk_mul_f32 v[128:129], v[2:3], v[74:75]
	v_cmp_gt_f32_e32 vcc, s67, v136
	s_waitcnt vmcnt(1)
	v_pk_fma_f32 v[74:75], v[112:113], v[108:109], v[122:123]
	v_pk_fma_f32 v[76:77], v[114:115], v[110:111], v[76:77]
	s_waitcnt vmcnt(0)
	v_pk_fma_f32 v[108:109], v[116:117], v[126:127], v[124:125]
	v_pk_fma_f32 v[110:111], v[118:119], v[128:129], v[78:79]
	global_store_dwordx4 v[94:95], v[74:77], off
	global_store_dwordx4 v[94:95], v[108:111], off offset:16
	global_load_dwordx4 v[74:77], v[120:121], off offset:2048
	s_nop 0
	global_load_dwordx4 v[108:111], v[120:121], off offset:2064
	v_ashrrev_i32_e32 v118, 31, v100
	v_lshlrev_b32_e32 v114, 16, v64
	v_and_b32_e32 v115, 0xffff0000, v64
	v_lshlrev_b32_e32 v64, 16, v65
	v_and_b32_e32 v65, 0xffff0000, v65
	v_lshrrev_b32_e32 v118, 20, v118
	v_lshlrev_b32_e32 v116, 16, v66
	v_and_b32_e32 v117, 0xffff0000, v66
	v_lshlrev_b32_e32 v66, 16, v67
	v_and_b32_e32 v67, 0xffff0000, v67
	v_add_u32_e32 v118, v100, v118
	v_pk_mul_f32 v[114:115], v[134:135], v[114:115] op_sel_hi:[0,1]
	v_pk_mul_f32 v[64:65], v[134:135], v[64:65] op_sel_hi:[0,1]
	v_lshlrev_b32_e32 v78, 16, v68
	v_and_b32_e32 v79, 0xffff0000, v68
	v_lshlrev_b32_e32 v68, 16, v69
	v_and_b32_e32 v69, 0xffff0000, v69
	v_ashrrev_i32_e32 v118, 12, v118
	v_pk_mul_f32 v[116:117], v[134:135], v[116:117] op_sel_hi:[0,1]
	v_pk_mul_f32 v[66:67], v[134:135], v[66:67] op_sel_hi:[0,1]
	v_pk_mul_f32 v[114:115], v[12:13], v[114:115]
	v_pk_mul_f32 v[120:121], v[14:15], v[64:65]
	v_lshlrev_b32_e32 v112, 16, v70
	v_and_b32_e32 v113, 0xffff0000, v70
	v_lshlrev_b32_e32 v70, 16, v71
	v_and_b32_e32 v71, 0xffff0000, v71
	v_mul_hi_i32_i24_e32 v119, 0x6000, v118
	v_mul_i32_i24_e32 v118, 0x6000, v118
	v_pk_mul_f32 v[116:117], v[8:9], v[116:117]
	v_pk_mul_f32 v[122:123], v[10:11], v[66:67]
	v_lshl_add_u64 v[118:119], v[86:87], 0, v[118:119]
	s_waitcnt vmcnt(1)
	v_pk_fma_f32 v[64:65], v[114:115], v[74:75], v[78:79]
	v_pk_fma_f32 v[66:67], v[120:121], v[76:77], v[68:69]
	s_waitcnt vmcnt(0)
	v_pk_fma_f32 v[68:69], v[116:117], v[108:109], v[112:113]
	v_pk_fma_f32 v[70:71], v[122:123], v[110:111], v[70:71]
	global_store_dwordx4 v[94:95], v[64:67], off offset:2048
	global_store_dwordx4 v[94:95], v[68:71], off offset:2064
	global_load_dwordx4 v[64:67], v[118:119], off
	s_nop 0
	global_load_dwordx4 v[68:71], v[118:119], off offset:16
	v_lshlrev_b32_e32 v110, 16, v58
	v_and_b32_e32 v111, 0xffff0000, v58
	v_mul_f32_e32 v58, 0x4b800000, v136
	v_cndmask_b32_e32 v58, v136, v58, vcc
	v_lshlrev_b64 v[78:79], 12, v[100:101]
	v_rsq_f32_e32 v101, v58
	v_lshlrev_b32_e32 v108, 16, v56
	v_and_b32_e32 v109, 0xffff0000, v56
	v_lshlrev_b32_e32 v56, 16, v57
	v_mul_f32_e32 v112, 0x45800000, v101
	v_and_b32_e32 v57, 0xffff0000, v57
	v_cndmask_b32_e32 v112, v101, v112, vcc
	v_lshlrev_b32_e32 v58, 16, v59
	v_and_b32_e32 v59, 0xffff0000, v59
	v_pk_mul_f32 v[108:109], v[112:113], v[108:109] op_sel_hi:[0,1]
	v_pk_mul_f32 v[56:57], v[112:113], v[56:57] op_sel_hi:[0,1]
	v_lshlrev_b32_e32 v74, 16, v60
	v_and_b32_e32 v75, 0xffff0000, v60
	v_lshlrev_b32_e32 v60, 16, v61
	v_and_b32_e32 v61, 0xffff0000, v61
	v_pk_mul_f32 v[110:111], v[112:113], v[110:111] op_sel_hi:[0,1]
	v_pk_mul_f32 v[58:59], v[112:113], v[58:59] op_sel_hi:[0,1]
	v_pk_mul_f32 v[108:109], v[4:5], v[108:109]
	v_pk_mul_f32 v[114:115], v[6:7], v[56:57]
	v_lshlrev_b32_e32 v76, 16, v62
	v_and_b32_e32 v77, 0xffff0000, v62
	v_lshlrev_b32_e32 v62, 16, v63
	v_and_b32_e32 v63, 0xffff0000, v63
	v_lshl_add_u64 v[78:79], v[88:89], 0, v[78:79]
	v_pk_mul_f32 v[110:111], v[0:1], v[110:111]
	v_pk_mul_f32 v[116:117], v[2:3], v[58:59]
	v_lshl_add_u64 v[94:95], v[94:95], 0, s[42:43]
	s_waitcnt vmcnt(1)
	v_pk_fma_f32 v[56:57], v[64:65], v[108:109], v[74:75]
	v_pk_fma_f32 v[58:59], v[66:67], v[114:115], v[60:61]
	s_waitcnt vmcnt(0)
	v_pk_fma_f32 v[60:61], v[68:69], v[110:111], v[76:77]
	v_pk_fma_f32 v[62:63], v[70:71], v[116:117], v[62:63]
	global_store_dwordx4 v[78:79], v[56:59], off
	global_store_dwordx4 v[78:79], v[60:63], off offset:16
	global_load_dwordx4 v[56:59], v[118:119], off offset:2048
	s_nop 0
	global_load_dwordx4 v[60:63], v[118:119], off offset:2064
	v_add_u32_e32 v108, s66, v100
	v_ashrrev_i32_e32 v74, 31, v108
	v_lshlrev_b32_e32 v68, 16, v48
	v_and_b32_e32 v69, 0xffff0000, v48
	v_lshlrev_b32_e32 v48, 16, v49
	v_and_b32_e32 v49, 0xffff0000, v49
	v_lshrrev_b32_e32 v74, 20, v74
	v_lshlrev_b32_e32 v70, 16, v50
	v_and_b32_e32 v71, 0xffff0000, v50
	v_lshlrev_b32_e32 v50, 16, v51
	v_and_b32_e32 v51, 0xffff0000, v51
	v_add_u32_e32 v74, v108, v74
	v_pk_mul_f32 v[68:69], v[112:113], v[68:69] op_sel_hi:[0,1]
	v_pk_mul_f32 v[48:49], v[112:113], v[48:49] op_sel_hi:[0,1]
	v_lshlrev_b32_e32 v64, 16, v52
	v_and_b32_e32 v65, 0xffff0000, v52
	v_lshlrev_b32_e32 v52, 16, v53
	v_and_b32_e32 v53, 0xffff0000, v53
	v_ashrrev_i32_e32 v74, 12, v74
	v_pk_mul_f32 v[70:71], v[112:113], v[70:71] op_sel_hi:[0,1]
	v_pk_mul_f32 v[50:51], v[112:113], v[50:51] op_sel_hi:[0,1]
	v_pk_mul_f32 v[68:69], v[12:13], v[68:69]
	v_pk_mul_f32 v[76:77], v[14:15], v[48:49]
	v_lshlrev_b32_e32 v66, 16, v54
	v_and_b32_e32 v67, 0xffff0000, v54
	v_lshlrev_b32_e32 v54, 16, v55
	v_and_b32_e32 v55, 0xffff0000, v55
	v_mul_hi_i32_i24_e32 v75, 0x6000, v74
	v_mul_i32_i24_e32 v74, 0x6000, v74
	v_pk_mul_f32 v[70:71], v[8:9], v[70:71]
	v_pk_mul_f32 v[100:101], v[10:11], v[50:51]
	v_lshl_add_u64 v[74:75], v[86:87], 0, v[74:75]
	s_waitcnt vmcnt(1)
	v_pk_fma_f32 v[48:49], v[68:69], v[56:57], v[64:65]
	v_pk_fma_f32 v[50:51], v[76:77], v[58:59], v[52:53]
	s_waitcnt vmcnt(0)
	v_pk_fma_f32 v[52:53], v[70:71], v[60:61], v[66:67]
	v_pk_fma_f32 v[54:55], v[100:101], v[62:63], v[54:55]
	global_store_dwordx4 v[78:79], v[48:51], off offset:2048
	global_store_dwordx4 v[78:79], v[52:55], off offset:2064
	global_load_dwordx4 v[48:51], v[74:75], off
	s_nop 0
	global_load_dwordx4 v[52:55], v[74:75], off offset:16
	v_mov_b32_e32 v56, v107
	v_mov_b32_e32 v58, v106
	s_nop 0
	v_permlane32_swap_b32_e32 v107, v56
	v_permlane32_swap_b32_e32 v106, v58
	v_add_f32_e32 v57, v107, v56
	v_add_f32_e32 v56, v106, v58
	v_mov_b32_e32 v59, v57
	v_mov_b32_e32 v58, v56
	s_nop 0
	v_permlane16_swap_b32_e32 v57, v59
	v_permlane16_swap_b32_e32 v56, v58
	v_pk_add_f32 v[56:57], v[56:57], v[58:59]
	s_nop 1
	v_mov_b32_dpp v59, v57 row_ror:8 row_mask:0xf bank_mask:0xf
	s_nop 1
	v_mov_b32_dpp v58, v56 row_ror:8 row_mask:0xf bank_mask:0xf
	v_lshlrev_b32_e32 v68, 16, v42
	v_and_b32_e32 v69, 0xffff0000, v42
	v_lshlrev_b64 v[64:65], 12, v[98:99]
	v_lshlrev_b32_e32 v66, 16, v40
	s_waitcnt lgkmcnt(0)
	v_pk_add_f32 v[56:57], v[56:57], v[58:59]
	s_nop 1
	v_mov_b32_dpp v59, v57 row_ror:4 row_mask:0xf bank_mask:0xf
	s_nop 1
	v_mov_b32_dpp v58, v56 row_ror:4 row_mask:0xf bank_mask:0xf
	v_and_b32_e32 v67, 0xffff0000, v40
	v_lshlrev_b32_e32 v40, 16, v41
	v_and_b32_e32 v41, 0xffff0000, v41
	v_lshlrev_b32_e32 v60, 16, v44
	s_waitcnt lgkmcnt(0)
	v_pk_add_f32 v[56:57], v[56:57], v[58:59]
	s_nop 1
	v_mov_b32_dpp v59, v57 row_ror:2 row_mask:0xf bank_mask:0xf
	s_nop 1
	v_mov_b32_dpp v58, v56 row_ror:2 row_mask:0xf bank_mask:0xf
	v_and_b32_e32 v61, 0xffff0000, v44
	v_lshlrev_b32_e32 v44, 16, v45
	v_and_b32_e32 v45, 0xffff0000, v45
	v_lshlrev_b32_e32 v62, 16, v46
	s_waitcnt lgkmcnt(0)
	v_pk_add_f32 v[56:57], v[56:57], v[58:59]
	s_nop 1
	v_mov_b32_dpp v59, v57 row_ror:1 row_mask:0xf bank_mask:0xf
	s_nop 1
	v_mov_b32_dpp v58, v56 row_ror:1 row_mask:0xf bank_mask:0xf
	v_and_b32_e32 v63, 0xffff0000, v46
	v_lshlrev_b32_e32 v46, 16, v47
	v_and_b32_e32 v47, 0xffff0000, v47
	s_waitcnt lgkmcnt(0)
	v_pk_add_f32 v[56:57], v[56:57], v[58:59]
	s_nop 0
	v_pk_fma_f32 v[56:57], v[56:57], s[62:63], v[72:73] op_sel_hi:[1,0,0]
	v_lshl_add_u64 v[58:59], v[88:89], 0, v[64:65]
	v_mul_f32_e32 v42, 0x4b800000, v57
	v_cmp_gt_f32_e32 vcc, s67, v57
	s_nop 1
	v_cndmask_b32_e32 v42, v57, v42, vcc
	v_rsq_f32_e32 v57, v42
	v_lshlrev_b32_e32 v42, 16, v43
	v_and_b32_e32 v43, 0xffff0000, v43
	v_mul_f32_e32 v64, 0x45800000, v57
	v_cndmask_b32_e32 v64, v57, v64, vcc
	v_pk_mul_f32 v[66:67], v[64:65], v[66:67] op_sel_hi:[0,1]
	v_pk_mul_f32 v[40:41], v[64:65], v[40:41] op_sel_hi:[0,1]
	v_pk_mul_f32 v[68:69], v[64:65], v[68:69] op_sel_hi:[0,1]
	v_pk_mul_f32 v[42:43], v[64:65], v[42:43] op_sel_hi:[0,1]
	v_pk_mul_f32 v[66:67], v[4:5], v[66:67]
	v_pk_mul_f32 v[70:71], v[6:7], v[40:41]
	v_pk_mul_f32 v[68:69], v[0:1], v[68:69]
	v_pk_mul_f32 v[72:73], v[2:3], v[42:43]
	v_add_u32_e32 v57, s66, v108
	v_cmp_gt_f32_e32 vcc, s67, v56
	v_add_u32_e32 v108, s66, v57
	s_waitcnt vmcnt(1)
	v_pk_fma_f32 v[40:41], v[48:49], v[66:67], v[60:61]
	v_pk_fma_f32 v[42:43], v[50:51], v[70:71], v[44:45]
	s_waitcnt vmcnt(0)
	v_pk_fma_f32 v[44:45], v[52:53], v[68:69], v[62:63]
	v_pk_fma_f32 v[46:47], v[54:55], v[72:73], v[46:47]
	global_store_dwordx4 v[58:59], v[40:43], off
	global_store_dwordx4 v[58:59], v[44:47], off offset:16
	global_load_dwordx4 v[40:43], v[74:75], off offset:2048
	s_nop 0
	global_load_dwordx4 v[44:47], v[74:75], off offset:2064
	v_ashrrev_i32_e32 v60, 31, v57
	v_lshlrev_b32_e32 v52, 16, v32
	v_and_b32_e32 v53, 0xffff0000, v32
	v_lshlrev_b32_e32 v32, 16, v33
	v_and_b32_e32 v33, 0xffff0000, v33
	v_lshrrev_b32_e32 v60, 20, v60
	v_lshlrev_b32_e32 v54, 16, v34
	v_and_b32_e32 v55, 0xffff0000, v34
	v_lshlrev_b32_e32 v34, 16, v35
	v_and_b32_e32 v35, 0xffff0000, v35
	v_add_u32_e32 v60, v57, v60
	v_pk_mul_f32 v[52:53], v[64:65], v[52:53] op_sel_hi:[0,1]
	v_pk_mul_f32 v[32:33], v[64:65], v[32:33] op_sel_hi:[0,1]
	v_lshlrev_b32_e32 v48, 16, v36
	v_and_b32_e32 v49, 0xffff0000, v36
	v_lshlrev_b32_e32 v36, 16, v37
	v_and_b32_e32 v37, 0xffff0000, v37
	v_ashrrev_i32_e32 v60, 12, v60
	v_pk_mul_f32 v[54:55], v[64:65], v[54:55] op_sel_hi:[0,1]
	v_pk_mul_f32 v[34:35], v[64:65], v[34:35] op_sel_hi:[0,1]
	v_pk_mul_f32 v[52:53], v[12:13], v[52:53]
	v_pk_mul_f32 v[62:63], v[14:15], v[32:33]
	v_lshlrev_b32_e32 v50, 16, v38
	v_and_b32_e32 v51, 0xffff0000, v38
	v_lshlrev_b32_e32 v38, 16, v39
	v_and_b32_e32 v39, 0xffff0000, v39
	v_mul_hi_i32_i24_e32 v61, 0x6000, v60
	v_mul_i32_i24_e32 v60, 0x6000, v60
	v_pk_mul_f32 v[54:55], v[8:9], v[54:55]
	v_pk_mul_f32 v[64:65], v[10:11], v[34:35]
	v_lshl_add_u64 v[60:61], v[86:87], 0, v[60:61]
	s_waitcnt vmcnt(1)
	v_pk_fma_f32 v[32:33], v[52:53], v[40:41], v[48:49]
	v_pk_fma_f32 v[34:35], v[62:63], v[42:43], v[36:37]
	s_waitcnt vmcnt(0)
	v_pk_fma_f32 v[36:37], v[54:55], v[44:45], v[50:51]
	v_pk_fma_f32 v[38:39], v[64:65], v[46:47], v[38:39]
	global_store_dwordx4 v[58:59], v[32:35], off offset:2048
	global_store_dwordx4 v[58:59], v[36:39], off offset:2064
	global_load_dwordx4 v[32:35], v[60:61], off
	s_nop 0
	global_load_dwordx4 v[36:39], v[60:61], off offset:16
	v_lshlrev_b32_e32 v48, 16, v26
	v_and_b32_e32 v49, 0xffff0000, v26
	v_mul_f32_e32 v26, 0x4b800000, v56
	v_cndmask_b32_e32 v26, v56, v26, vcc
	v_rsq_f32_e32 v50, v26
	v_lshlrev_b32_e32 v46, 16, v24
	v_and_b32_e32 v47, 0xffff0000, v24
	v_lshlrev_b32_e32 v24, 16, v25
	v_mul_f32_e32 v51, 0x45800000, v50
	v_and_b32_e32 v25, 0xffff0000, v25
	v_cndmask_b32_e32 v50, v50, v51, vcc
	v_lshlrev_b32_e32 v26, 16, v27
	v_and_b32_e32 v27, 0xffff0000, v27
	v_pk_mul_f32 v[46:47], v[50:51], v[46:47] op_sel_hi:[0,1]
	v_pk_mul_f32 v[24:25], v[50:51], v[24:25] op_sel_hi:[0,1]
	v_lshlrev_b32_e32 v40, 16, v28
	v_and_b32_e32 v41, 0xffff0000, v28
	v_lshlrev_b32_e32 v28, 16, v29
	v_and_b32_e32 v29, 0xffff0000, v29
	v_lshlrev_b64 v[44:45], 12, v[96:97]
	v_pk_mul_f32 v[48:49], v[50:51], v[48:49] op_sel_hi:[0,1]
	v_pk_mul_f32 v[26:27], v[50:51], v[26:27] op_sel_hi:[0,1]
	v_pk_mul_f32 v[46:47], v[4:5], v[46:47]
	v_pk_mul_f32 v[52:53], v[6:7], v[24:25]
	v_lshlrev_b32_e32 v42, 16, v30
	v_and_b32_e32 v43, 0xffff0000, v30
	v_lshlrev_b32_e32 v30, 16, v31
	v_and_b32_e32 v31, 0xffff0000, v31
	v_lshl_add_u64 v[44:45], v[88:89], 0, v[44:45]
	v_pk_mul_f32 v[48:49], v[0:1], v[48:49]
	v_pk_mul_f32 v[54:55], v[2:3], v[26:27]
	v_cmp_lt_i32_e32 vcc, s46, v108
	s_or_b64 s[8:9], vcc, s[8:9]
	s_waitcnt vmcnt(1)
	v_pk_fma_f32 v[24:25], v[32:33], v[46:47], v[40:41]
	v_pk_fma_f32 v[26:27], v[34:35], v[52:53], v[28:29]
	s_waitcnt vmcnt(0)
	v_pk_fma_f32 v[28:29], v[36:37], v[48:49], v[42:43]
	v_pk_fma_f32 v[30:31], v[38:39], v[54:55], v[30:31]
	global_store_dwordx4 v[44:45], v[24:27], off
	global_store_dwordx4 v[44:45], v[28:31], off offset:16
	global_load_dwordx4 v[24:27], v[60:61], off offset:2048
	s_nop 0
	global_load_dwordx4 v[28:31], v[60:61], off offset:2064
	v_lshlrev_b32_e32 v36, 16, v16
	v_and_b32_e32 v37, 0xffff0000, v16
	v_lshlrev_b32_e32 v16, 16, v17
	v_and_b32_e32 v17, 0xffff0000, v17
	v_lshlrev_b32_e32 v38, 16, v18
	v_and_b32_e32 v39, 0xffff0000, v18
	v_lshlrev_b32_e32 v18, 16, v19
	v_and_b32_e32 v19, 0xffff0000, v19
	v_pk_mul_f32 v[36:37], v[50:51], v[36:37] op_sel_hi:[0,1]
	v_pk_mul_f32 v[16:17], v[50:51], v[16:17] op_sel_hi:[0,1]
	v_lshlrev_b32_e32 v32, 16, v20
	v_and_b32_e32 v33, 0xffff0000, v20
	v_lshlrev_b32_e32 v20, 16, v21
	v_and_b32_e32 v21, 0xffff0000, v21
	v_pk_mul_f32 v[38:39], v[50:51], v[38:39] op_sel_hi:[0,1]
	v_pk_mul_f32 v[18:19], v[50:51], v[18:19] op_sel_hi:[0,1]
	v_pk_mul_f32 v[36:37], v[12:13], v[36:37]
	v_pk_mul_f32 v[40:41], v[14:15], v[16:17]
	v_lshlrev_b32_e32 v34, 16, v22
	v_and_b32_e32 v35, 0xffff0000, v22
	v_lshlrev_b32_e32 v22, 16, v23
	v_and_b32_e32 v23, 0xffff0000, v23
	v_pk_mul_f32 v[38:39], v[8:9], v[38:39]
	v_pk_mul_f32 v[42:43], v[10:11], v[18:19]
	s_waitcnt vmcnt(1)
	v_pk_fma_f32 v[16:17], v[36:37], v[24:25], v[32:33]
	v_pk_fma_f32 v[18:19], v[40:41], v[26:27], v[20:21]
	s_waitcnt vmcnt(0)
	v_pk_fma_f32 v[20:21], v[38:39], v[28:29], v[34:35]
	v_pk_fma_f32 v[22:23], v[42:43], v[30:31], v[22:23]
	global_store_dwordx4 v[44:45], v[16:19], off offset:2048
	global_store_dwordx4 v[44:45], v[20:23], off offset:2064
	s_andn2_b64 exec, exec, s[8:9]
	s_cbranch_execz .LBB0_2449

.LBB0_2452:
	s_or_b64 exec, exec, s[6:7]
	v_ashrrev_i32_e32 v136, 31, v130
	v_lshrrev_b32_e32 v136, 20, v136
	v_add_u32_e32 v130, v130, v136
	v_ashrrev_i32_e32 v130, 12, v130
	v_mul_hi_i32_i24_e32 v137, 0x1800, v130
	v_mul_i32_i24_e32 v136, 0x1800, v130
	v_lshlrev_b64 v[136:137], 2, v[136:137]
	v_lshl_add_u64 v[152:153], v[102:103], 0, v[136:137]
	global_load_dwordx4 v[144:147], v[152:153], off
	global_load_dwordx4 v[148:151], v[152:153], off offset:16
	s_waitcnt vmcnt(14)
	v_mov_b32_e32 v130, v142
	s_nop 1
	v_permlane32_swap_b32_e32 v142, v130
	v_add_f32_e32 v130, v142, v130
	v_mov_b32_e32 v142, v130
	s_nop 1
	v_permlane16_swap_b32_e32 v130, v142
	v_add_f32_e32 v130, v130, v142
	s_nop 1
	v_mov_b32_dpp v155, v130 row_ror:8 row_mask:0xf bank_mask:0xf
	v_lshlrev_b32_e32 v158, 16, v88
	v_lshlrev_b32_e32 v160, 16, v90
	v_lshlrev_b32_e32 v154, 16, v92
	v_lshlrev_b32_e32 v156, 16, v94
	s_waitcnt lgkmcnt(0)
	v_add_f32_e32 v130, v130, v155
	s_nop 1
	v_mov_b32_dpp v157, v130 row_ror:4 row_mask:0xf bank_mask:0xf
	v_and_b32_e32 v155, 0xffff0000, v92
	v_lshlrev_b32_e32 v92, 16, v93
	v_and_b32_e32 v93, 0xffff0000, v93
	v_lshl_add_u64 v[142:143], v[128:129], 0, s[58:59]
	s_waitcnt lgkmcnt(0)
	v_add_f32_e32 v130, v130, v157
	s_nop 1
	v_mov_b32_dpp v159, v130 row_ror:2 row_mask:0xf bank_mask:0xf
	v_and_b32_e32 v157, 0xffff0000, v94
	v_lshlrev_b32_e32 v94, 16, v95
	v_and_b32_e32 v95, 0xffff0000, v95
	v_lshl_add_u64 v[124:125], v[108:109], 0, v[124:125]
	s_waitcnt lgkmcnt(0)
	v_add_f32_e32 v130, v130, v159
	s_nop 1
	v_mov_b32_dpp v161, v130 row_ror:1 row_mask:0xf bank_mask:0xf
	v_and_b32_e32 v159, 0xffff0000, v88
	v_lshlrev_b32_e32 v88, 16, v89
	v_and_b32_e32 v89, 0xffff0000, v89
	v_lshl_add_u64 v[110:111], v[110:111], 0, s[38:39]
	s_waitcnt lgkmcnt(0)
	v_add_f32_e32 v130, v130, v161
	v_fmamk_f32 v130, v130, 0x3a800000, v188
	v_mul_f32_e32 v161, 0x4b800000, v130
	v_cmp_gt_f32_e32 vcc, s67, v130
	v_lshl_add_u64 v[112:113], v[112:113], 0, s[40:41]
	s_nop 0
	v_cndmask_b32_e32 v130, v130, v161, vcc
	v_rsq_f32_e32 v130, v130
	v_and_b32_e32 v161, 0xffff0000, v90
	v_lshlrev_b32_e32 v90, 16, v91
	v_and_b32_e32 v91, 0xffff0000, v91
	v_mul_f32_e32 v162, 0x45800000, v130
	v_cndmask_b32_e32 v130, v130, v162, vcc
	s_waitcnt vmcnt(6)
	v_pk_mul_f32 v[158:159], v[130:131], v[158:159] op_sel_hi:[0,1]
	v_pk_mul_f32 v[88:89], v[130:131], v[88:89] op_sel_hi:[0,1]
	v_pk_mul_f32 v[160:161], v[130:131], v[160:161] op_sel_hi:[0,1]
	v_pk_mul_f32 v[90:91], v[130:131], v[90:91] op_sel_hi:[0,1]
	v_pk_mul_f32 v[158:159], v[4:5], v[158:159]
	v_pk_mul_f32 v[88:89], v[6:7], v[88:89]
	v_pk_mul_f32 v[160:161], v[0:1], v[160:161]
	v_pk_mul_f32 v[90:91], v[2:3], v[90:91]
	s_waitcnt vmcnt(1)
	v_pk_fma_f32 v[144:145], v[144:145], v[158:159], v[154:155]
	v_pk_fma_f32 v[92:93], v[146:147], v[88:89], v[92:93]
	s_waitcnt vmcnt(0)
	v_pk_fma_f32 v[146:147], v[148:149], v[160:161], v[156:157]
	v_pk_fma_f32 v[94:95], v[150:151], v[90:91], v[94:95]
	v_cvt_pk_bf16_f32 v88, v144, v145
	v_cvt_pk_bf16_f32 v89, v92, v93
	v_cvt_pk_bf16_f32 v90, v146, v147
	v_cvt_pk_bf16_f32 v91, v94, v95
	global_store_dwordx4 v[142:143], v[88:91], off
	global_load_dwordx4 v[92:95], v[152:153], off offset:2048
	s_nop 0
	global_load_dwordx4 v[142:145], v[152:153], off offset:2064
	v_and_b32_e32 v163, 0xffff0000, v88
	v_lshlrev_b32_e32 v162, 16, v88
	v_mul_f32_e32 v88, v163, v163
	v_lshlrev_b32_e32 v164, 16, v89
	v_and_b32_e32 v165, 0xffff0000, v89
	v_pk_fma_f32 v[88:89], v[162:163], v[162:163], v[88:89] op_sel_hi:[1,1,0]
	v_lshlrev_b32_e32 v166, 16, v90
	v_and_b32_e32 v167, 0xffff0000, v90
	v_mul_f32_e32 v90, v165, v165
	v_pk_fma_f32 v[88:89], v[164:165], v[164:165], v[88:89]
	v_lshlrev_b32_e32 v152, 16, v80
	v_and_b32_e32 v153, 0xffff0000, v80
	v_lshlrev_b32_e32 v80, 16, v81
	v_and_b32_e32 v81, 0xffff0000, v81
	v_lshlrev_b32_e32 v154, 16, v82
	v_and_b32_e32 v155, 0xffff0000, v82
	v_lshlrev_b32_e32 v82, 16, v83
	v_and_b32_e32 v83, 0xffff0000, v83
	v_pk_add_f32 v[88:89], v[90:91], v[88:89] op_sel_hi:[0,1]
	v_pk_mul_f32 v[152:153], v[130:131], v[152:153] op_sel_hi:[0,1]
	v_pk_mul_f32 v[80:81], v[130:131], v[80:81] op_sel_hi:[0,1]
	v_pk_mul_f32 v[154:155], v[130:131], v[154:155] op_sel_hi:[0,1]
	v_pk_mul_f32 v[82:83], v[130:131], v[82:83] op_sel_hi:[0,1]
	v_mul_f32_e32 v130, v167, v167
	v_pk_fma_f32 v[88:89], v[166:167], v[166:167], v[88:89]
	v_lshlrev_b32_e32 v148, 16, v84
	v_and_b32_e32 v149, 0xffff0000, v84
	v_lshlrev_b32_e32 v84, 16, v85
	v_and_b32_e32 v85, 0xffff0000, v85
	v_lshlrev_b32_e32 v150, 16, v86
	v_and_b32_e32 v151, 0xffff0000, v86
	v_lshlrev_b32_e32 v86, 16, v87
	v_and_b32_e32 v87, 0xffff0000, v87
	v_pk_mul_f32 v[152:153], v[12:13], v[152:153]
	v_pk_mul_f32 v[80:81], v[14:15], v[80:81]
	v_pk_mul_f32 v[154:155], v[8:9], v[154:155]
	v_pk_mul_f32 v[82:83], v[10:11], v[82:83]
	v_lshlrev_b32_e32 v168, 16, v91
	v_and_b32_e32 v169, 0xffff0000, v91
	v_pk_add_f32 v[88:89], v[130:131], v[88:89] op_sel_hi:[0,1]
	v_pk_fma_f32 v[170:171], v[168:169], v[168:169], v[88:89]
	v_lshl_add_u64 v[146:147], v[128:129], 0, s[60:61]
	v_lshl_add_u64 v[160:161], v[104:105], 0, v[136:137]
	v_lshl_add_u64 v[136:137], v[106:107], 0, v[136:137]
	v_mov_b32_e32 v156, v134
	s_nop 1
	v_permlane32_swap_b32_e32 v134, v156
	v_add_f32_e32 v156, v134, v156
	v_mul_f32_e32 v134, v169, v169
	v_mov_b32_e32 v158, v156
	s_nop 1
	v_permlane16_swap_b32_e32 v156, v158
	v_add_co_u32_e64 v128, s[6:7], s69, v128
	s_waitcnt vmcnt(1)
	v_pk_fma_f32 v[88:89], v[152:153], v[92:93], v[148:149]
	v_pk_fma_f32 v[84:85], v[80:81], v[94:95], v[84:85]
	s_waitcnt vmcnt(0)
	v_pk_fma_f32 v[90:91], v[154:155], v[142:143], v[150:151]
	v_pk_fma_f32 v[86:87], v[82:83], v[144:145], v[86:87]
	v_cvt_pk_bf16_f32 v80, v88, v89
	v_cvt_pk_bf16_f32 v81, v84, v85
	v_cvt_pk_bf16_f32 v82, v90, v91
	v_cvt_pk_bf16_f32 v83, v86, v87
	global_store_dwordx4 v[146:147], v[80:83], off
	global_load_dwordx4 v[84:87], v[136:137], off offset:16
	global_load_dwordx4 v[88:91], v[136:137], off
	global_load_dwordx4 v[92:95], v[160:161], off offset:16
	global_load_dwordx4 v[142:145], v[160:161], off
	v_pk_add_f32 v[146:147], v[134:135], v[170:171] op_sel_hi:[0,1]
	v_lshlrev_b32_e32 v148, 16, v80
	v_and_b32_e32 v149, 0xffff0000, v80
	v_lshlrev_b32_e32 v150, 16, v81
	v_and_b32_e32 v151, 0xffff0000, v81
	v_lshlrev_b32_e32 v152, 16, v82
	v_and_b32_e32 v153, 0xffff0000, v82
	v_pk_fma_f32 v[80:81], v[148:149], v[148:149], v[146:147]
	v_mul_f32_e32 v82, v149, v149
	v_pk_add_f32 v[80:81], v[82:83], v[80:81] op_sel_hi:[0,1]
	v_mul_f32_e32 v130, v151, v151
	v_pk_fma_f32 v[80:81], v[150:151], v[150:151], v[80:81]
	v_mul_f32_e32 v134, v153, v153
	v_pk_add_f32 v[80:81], v[130:131], v[80:81] op_sel_hi:[0,1]
	v_pk_fma_f32 v[80:81], v[152:153], v[152:153], v[80:81]
	v_lshlrev_b32_e32 v154, 16, v83
	v_and_b32_e32 v155, 0xffff0000, v83
	v_pk_add_f32 v[80:81], v[134:135], v[80:81] op_sel_hi:[0,1]
	v_mul_f32_e32 v146, v155, v155
	v_pk_fma_f32 v[80:81], v[154:155], v[154:155], v[80:81]
	v_addc_co_u32_e64 v129, s[6:7], 0, v129, s[6:7]
	v_pk_add_f32 v[80:81], v[146:147], v[80:81] op_sel_hi:[0,1]
	v_mov_b32_e32 v81, v80
	s_nop 1
	v_permlane32_swap_b32_e32 v80, v81
	v_add_f32_e32 v157, v80, v81
	v_mov_b32_e32 v159, v157
	s_nop 1
	v_permlane16_swap_b32_e32 v157, v159
	v_pk_add_f32 v[80:81], v[156:157], v[158:159]
	s_nop 1
	v_mov_b32_dpp v83, v81 row_ror:8 row_mask:0xf bank_mask:0xf
	s_nop 1
	v_mov_b32_dpp v82, v80 row_ror:8 row_mask:0xf bank_mask:0xf
	s_waitcnt lgkmcnt(0)
	v_pk_add_f32 v[80:81], v[80:81], v[82:83]
	s_nop 1
	v_mov_b32_dpp v83, v81 row_ror:4 row_mask:0xf bank_mask:0xf
	s_nop 1
	v_mov_b32_dpp v82, v80 row_ror:4 row_mask:0xf bank_mask:0xf
	s_waitcnt lgkmcnt(0)
	v_pk_add_f32 v[80:81], v[80:81], v[82:83]
	s_nop 1
	v_mov_b32_dpp v83, v81 row_ror:2 row_mask:0xf bank_mask:0xf
	s_nop 1
	v_mov_b32_dpp v82, v80 row_ror:2 row_mask:0xf bank_mask:0xf
	s_waitcnt lgkmcnt(0)
	v_pk_add_f32 v[82:83], v[80:81], v[82:83]
	s_nop 1
	v_mov_b32_dpp v147, v83 row_ror:1 row_mask:0xf bank_mask:0xf
	s_nop 1
	v_mov_b32_dpp v146, v82 row_ror:1 row_mask:0xf bank_mask:0xf
	v_mov_b64_e32 v[80:81], s[68:69]
	s_waitcnt lgkmcnt(0)
	v_pk_add_f32 v[82:83], v[82:83], v[146:147]
	s_nop 0
	v_pk_fma_f32 v[146:147], v[82:83], s[62:63], v[80:81] op_sel_hi:[1,0,0]
	s_waitcnt vmcnt(3)
	v_pk_add_f32 v[84:85], v[84:85], 1.0 op_sel_hi:[1,0]
	v_mul_f32_e32 v82, 0x4b800000, v147
	v_cmp_gt_f32_e32 vcc, s67, v147
	s_waitcnt vmcnt(2)
	v_pk_add_f32 v[90:91], v[90:91], 1.0 op_sel_hi:[1,0]
	v_pk_add_f32 v[88:89], v[88:89], 1.0 op_sel_hi:[1,0]
	v_cndmask_b32_e32 v82, v147, v82, vcc
	v_rsq_f32_e32 v82, v82
	v_pk_add_f32 v[86:87], v[86:87], 1.0 op_sel_hi:[1,0]
	v_mul_f32_e32 v83, 0x45800000, v82
	v_cndmask_b32_e32 v130, v82, v83, vcc
	v_pk_mul_f32 v[82:83], v[130:131], v[162:163] op_sel_hi:[0,1]
	v_pk_mul_f32 v[156:157], v[130:131], v[164:165] op_sel_hi:[0,1]
	v_pk_mul_f32 v[158:159], v[130:131], v[166:167] op_sel_hi:[0,1]
	v_pk_mul_f32 v[162:163], v[130:131], v[168:169] op_sel_hi:[0,1]
	v_pk_mul_f32 v[82:83], v[16:17], v[82:83]
	v_pk_mul_f32 v[156:157], v[18:19], v[156:157]
	v_pk_mul_f32 v[158:159], v[24:25], v[158:159]
	v_pk_mul_f32 v[162:163], v[26:27], v[162:163]
	s_waitcnt vmcnt(0)
	v_pk_fma_f32 v[82:83], v[88:89], v[82:83], v[142:143]
	v_pk_fma_f32 v[88:89], v[156:157], v[90:91], v[144:145]
	v_pk_fma_f32 v[84:85], v[158:159], v[84:85], v[92:93]
	v_pk_fma_f32 v[86:87], v[162:163], v[86:87], v[94:95]
	v_cvt_pk_bf16_f32 v82, v82, v83
	v_cvt_pk_bf16_f32 v83, v88, v89
	v_cvt_pk_bf16_f32 v84, v84, v85
	v_cvt_pk_bf16_f32 v85, v86, v87
	global_store_dwordx4 v[128:129], v[82:85], off
	global_load_dwordx4 v[84:87], v[136:137], off offset:2048
	s_nop 0
	global_load_dwordx4 v[88:91], v[136:137], off offset:2064
	global_load_dwordx4 v[92:95], v[160:161], off offset:2048
	global_load_dwordx4 v[142:145], v[160:161], off offset:2064
	v_ashrrev_i32_e32 v82, 31, v122
	v_lshrrev_b32_e32 v82, 20, v82
	v_add_u32_e32 v82, v122, v82
	v_pk_mul_f32 v[148:149], v[130:131], v[148:149] op_sel_hi:[0,1]
	v_pk_mul_f32 v[150:151], v[130:131], v[150:151] op_sel_hi:[0,1]
	v_pk_mul_f32 v[152:153], v[130:131], v[152:153] op_sel_hi:[0,1]
	v_pk_mul_f32 v[154:155], v[130:131], v[154:155] op_sel_hi:[0,1]
	v_ashrrev_i32_e32 v82, 12, v82
	v_pk_mul_f32 v[148:149], v[28:29], v[148:149]
	v_pk_mul_f32 v[150:151], v[30:31], v[150:151]
	v_pk_mul_f32 v[152:153], v[20:21], v[152:153]
	v_pk_mul_f32 v[154:155], v[22:23], v[154:155]
	v_mul_hi_i32_i24_e32 v83, 0x1800, v82
	v_mul_i32_i24_e32 v82, 0x1800, v82
	v_lshlrev_b64 v[82:83], 2, v[82:83]
	v_lshl_add_u64 v[136:137], v[102:103], 0, v[82:83]
	v_mul_f32_e32 v130, 0x4b800000, v146
	v_cmp_gt_f32_e32 vcc, s67, v146
	s_waitcnt vmcnt(3)
	v_pk_add_f32 v[84:85], v[84:85], 1.0 op_sel_hi:[1,0]
	v_pk_add_f32 v[86:87], v[86:87], 1.0 op_sel_hi:[1,0]
	s_waitcnt vmcnt(2)
	v_pk_add_f32 v[88:89], v[88:89], 1.0 op_sel_hi:[1,0]
	v_pk_add_f32 v[90:91], v[90:91], 1.0 op_sel_hi:[1,0]
	s_waitcnt vmcnt(1)
	v_pk_fma_f32 v[84:85], v[148:149], v[84:85], v[92:93]
	v_pk_fma_f32 v[86:87], v[150:151], v[86:87], v[94:95]
	s_waitcnt vmcnt(0)
	v_pk_fma_f32 v[88:89], v[152:153], v[88:89], v[142:143]
	v_pk_fma_f32 v[90:91], v[154:155], v[90:91], v[144:145]
	v_cvt_pk_bf16_f32 v84, v84, v85
	v_cvt_pk_bf16_f32 v85, v86, v87
	v_cvt_pk_bf16_f32 v86, v88, v89
	v_cvt_pk_bf16_f32 v87, v90, v91
	global_store_dwordx4 v[128:129], v[84:87], off offset:1024
	global_load_dwordx4 v[84:87], v[136:137], off
	s_nop 0
	global_load_dwordx4 v[88:91], v[136:137], off offset:16
	v_cndmask_b32_e32 v130, v146, v130, vcc
	v_rsq_f32_e32 v130, v130
	v_lshlrev_b32_e32 v128, 16, v72
	v_and_b32_e32 v129, 0xffff0000, v72
	v_lshlrev_b32_e32 v72, 16, v73
	v_mul_f32_e32 v134, 0x45800000, v130
	v_and_b32_e32 v73, 0xffff0000, v73
	v_lshlrev_b32_e32 v142, 16, v74
	v_and_b32_e32 v143, 0xffff0000, v74
	v_lshlrev_b32_e32 v74, 16, v75
	v_and_b32_e32 v75, 0xffff0000, v75
	v_cndmask_b32_e32 v130, v130, v134, vcc
	v_pk_mul_f32 v[128:129], v[130:131], v[128:129] op_sel_hi:[0,1]
	v_pk_mul_f32 v[72:73], v[130:131], v[72:73] op_sel_hi:[0,1]
	v_pk_mul_f32 v[142:143], v[130:131], v[142:143] op_sel_hi:[0,1]
	v_pk_mul_f32 v[74:75], v[130:131], v[74:75] op_sel_hi:[0,1]
	v_lshlrev_b32_e32 v92, 16, v76
	v_and_b32_e32 v93, 0xffff0000, v76
	v_lshlrev_b32_e32 v76, 16, v77
	v_and_b32_e32 v77, 0xffff0000, v77
	v_lshlrev_b32_e32 v94, 16, v78
	v_and_b32_e32 v95, 0xffff0000, v78
	v_lshlrev_b32_e32 v78, 16, v79
	v_and_b32_e32 v79, 0xffff0000, v79
	v_pk_mul_f32 v[128:129], v[4:5], v[128:129]
	v_pk_mul_f32 v[72:73], v[6:7], v[72:73]
	v_pk_mul_f32 v[142:143], v[0:1], v[142:143]
	v_pk_mul_f32 v[74:75], v[2:3], v[74:75]
	v_lshl_add_u64 v[144:145], v[106:107], 0, v[82:83]
	s_waitcnt vmcnt(1)
	v_pk_fma_f32 v[84:85], v[84:85], v[128:129], v[92:93]
	v_pk_fma_f32 v[76:77], v[86:87], v[72:73], v[76:77]
	s_waitcnt vmcnt(0)
	v_pk_fma_f32 v[86:87], v[88:89], v[142:143], v[94:95]
	v_pk_fma_f32 v[78:79], v[90:91], v[74:75], v[78:79]
	v_cvt_pk_bf16_f32 v72, v84, v85
	v_cvt_pk_bf16_f32 v73, v76, v77
	v_cvt_pk_bf16_f32 v74, v86, v87
	v_cvt_pk_bf16_f32 v75, v78, v79
	global_store_dwordx4 v[126:127], v[72:75], off
	global_load_dwordx4 v[76:79], v[136:137], off offset:2048
	global_load_dwordx4 v[84:87], v[136:137], off offset:2064
	v_mov_b32_e32 v128, v131
	v_lshlrev_b32_e32 v92, 16, v64
	v_and_b32_e32 v93, 0xffff0000, v64
	v_lshlrev_b32_e32 v94, 16, v66
	v_and_b32_e32 v95, 0xffff0000, v66
	v_permlane32_swap_b32_e32 v131, v128
	v_lshl_add_u64 v[142:143], v[104:105], 0, v[82:83]
	v_pk_mul_f32 v[82:83], v[130:131], v[92:93] op_sel_hi:[0,1]
	v_pk_mul_f32 v[92:93], v[130:131], v[94:95] op_sel_hi:[0,1]
	v_and_b32_e32 v95, 0xffff0000, v72
	v_lshlrev_b32_e32 v64, 16, v65
	v_and_b32_e32 v65, 0xffff0000, v65
	v_lshlrev_b32_e32 v66, 16, v67
	v_and_b32_e32 v67, 0xffff0000, v67
	v_lshlrev_b32_e32 v94, 16, v72
	v_mul_f32_e32 v72, v95, v95
	v_add_f32_e32 v128, v131, v128
	v_pk_mul_f32 v[64:65], v[130:131], v[64:65] op_sel_hi:[0,1]
	v_pk_mul_f32 v[66:67], v[130:131], v[66:67] op_sel_hi:[0,1]
	v_lshlrev_b32_e32 v130, 16, v73
	v_and_b32_e32 v131, 0xffff0000, v73
	v_pk_fma_f32 v[72:73], v[94:95], v[94:95], v[72:73] op_sel_hi:[1,1,0]
	v_lshlrev_b32_e32 v146, 16, v74
	v_and_b32_e32 v147, 0xffff0000, v74
	v_mul_f32_e32 v74, v131, v131
	v_pk_fma_f32 v[72:73], v[130:131], v[130:131], v[72:73]
	v_lshlrev_b32_e32 v88, 16, v68
	v_pk_add_f32 v[72:73], v[74:75], v[72:73] op_sel_hi:[0,1]
	v_and_b32_e32 v89, 0xffff0000, v68
	v_lshlrev_b32_e32 v68, 16, v69
	v_and_b32_e32 v69, 0xffff0000, v69
	v_lshlrev_b32_e32 v90, 16, v70
	v_and_b32_e32 v91, 0xffff0000, v70
	v_lshlrev_b32_e32 v70, 16, v71
	v_and_b32_e32 v71, 0xffff0000, v71
	v_pk_mul_f32 v[82:83], v[12:13], v[82:83]
	v_pk_mul_f32 v[64:65], v[14:15], v[64:65]
	v_pk_mul_f32 v[92:93], v[8:9], v[92:93]
	v_pk_mul_f32 v[66:67], v[10:11], v[66:67]
	v_mul_f32_e32 v134, v147, v147
	v_pk_fma_f32 v[72:73], v[146:147], v[146:147], v[72:73]
	v_lshlrev_b32_e32 v148, 16, v75
	v_and_b32_e32 v149, 0xffff0000, v75
	v_pk_add_f32 v[152:153], v[134:135], v[72:73] op_sel_hi:[0,1]
	v_mul_f32_e32 v150, v149, v149
	v_mov_b32_e32 v136, v128
	s_nop 1
	v_permlane16_swap_b32_e32 v128, v136
	s_waitcnt vmcnt(1)
	v_pk_fma_f32 v[72:73], v[82:83], v[76:77], v[88:89]
	v_pk_fma_f32 v[68:69], v[64:65], v[78:79], v[68:69]
	s_waitcnt vmcnt(0)
	v_pk_fma_f32 v[74:75], v[92:93], v[84:85], v[90:91]
	v_pk_fma_f32 v[70:71], v[66:67], v[86:87], v[70:71]
	v_cvt_pk_bf16_f32 v64, v72, v73
	v_cvt_pk_bf16_f32 v65, v68, v69
	v_cvt_pk_bf16_f32 v66, v74, v75
	v_cvt_pk_bf16_f32 v67, v70, v71
	global_store_dwordx4 v[126:127], v[64:67], off offset:1024
	global_load_dwordx4 v[68:71], v[144:145], off offset:16
	global_load_dwordx4 v[72:75], v[144:145], off
	global_load_dwordx4 v[76:79], v[142:143], off offset:16
	global_load_dwordx4 v[82:85], v[142:143], off
	v_pk_fma_f32 v[86:87], v[148:149], v[148:149], v[152:153]
	v_lshlrev_b32_e32 v88, 16, v64
	v_pk_add_f32 v[86:87], v[150:151], v[86:87] op_sel_hi:[0,1]
	v_and_b32_e32 v89, 0xffff0000, v64
	v_lshlrev_b32_e32 v90, 16, v65
	v_and_b32_e32 v91, 0xffff0000, v65
	v_lshlrev_b32_e32 v92, 16, v66
	v_and_b32_e32 v93, 0xffff0000, v66
	v_pk_fma_f32 v[64:65], v[88:89], v[88:89], v[86:87]
	v_mul_f32_e32 v66, v89, v89
	v_pk_add_f32 v[64:65], v[66:67], v[64:65] op_sel_hi:[0,1]
	v_mul_f32_e32 v86, v91, v91
	v_pk_fma_f32 v[64:65], v[90:91], v[90:91], v[64:65]
	v_mul_f32_e32 v134, v93, v93
	v_pk_add_f32 v[64:65], v[86:87], v[64:65] op_sel_hi:[0,1]
	v_pk_fma_f32 v[64:65], v[92:93], v[92:93], v[64:65]
	v_lshlrev_b32_e32 v126, 16, v67
	v_and_b32_e32 v127, 0xffff0000, v67
	v_pk_add_f32 v[64:65], v[134:135], v[64:65] op_sel_hi:[0,1]
	v_mul_f32_e32 v150, v127, v127
	v_pk_fma_f32 v[64:65], v[126:127], v[126:127], v[64:65]
	s_waitcnt vmcnt(3)
	v_pk_add_f32 v[68:69], v[68:69], 1.0 op_sel_hi:[1,0]
	v_pk_add_f32 v[64:65], v[150:151], v[64:65] op_sel_hi:[0,1]
	v_mov_b32_e32 v65, v64
	s_nop 1
	v_permlane32_swap_b32_e32 v64, v65
	v_add_f32_e32 v129, v64, v65
	v_mov_b32_e32 v137, v129
	s_nop 1
	v_permlane16_swap_b32_e32 v129, v137
	v_pk_add_f32 v[64:65], v[128:129], v[136:137]
	s_nop 1
	v_mov_b32_dpp v67, v65 row_ror:8 row_mask:0xf bank_mask:0xf
	s_nop 1
	v_mov_b32_dpp v66, v64 row_ror:8 row_mask:0xf bank_mask:0xf
	s_waitcnt vmcnt(2)
	v_pk_add_f32 v[74:75], v[74:75], 1.0 op_sel_hi:[1,0]
	v_pk_add_f32 v[72:73], v[72:73], 1.0 op_sel_hi:[1,0]
	v_pk_add_f32 v[70:71], v[70:71], 1.0 op_sel_hi:[1,0]
	s_waitcnt lgkmcnt(0)
	v_pk_add_f32 v[64:65], v[64:65], v[66:67]
	s_nop 1
	v_mov_b32_dpp v67, v65 row_ror:4 row_mask:0xf bank_mask:0xf
	s_nop 1
	v_mov_b32_dpp v66, v64 row_ror:4 row_mask:0xf bank_mask:0xf
	s_waitcnt lgkmcnt(0)
	v_pk_add_f32 v[64:65], v[64:65], v[66:67]
	s_nop 1
	v_mov_b32_dpp v67, v65 row_ror:2 row_mask:0xf bank_mask:0xf
	s_nop 1
	v_mov_b32_dpp v66, v64 row_ror:2 row_mask:0xf bank_mask:0xf
	s_waitcnt lgkmcnt(0)
	v_pk_add_f32 v[64:65], v[64:65], v[66:67]
	s_nop 1
	v_mov_b32_dpp v67, v65 row_ror:1 row_mask:0xf bank_mask:0xf
	s_nop 1
	v_mov_b32_dpp v66, v64 row_ror:1 row_mask:0xf bank_mask:0xf
	s_waitcnt lgkmcnt(0)
	v_pk_add_f32 v[64:65], v[64:65], v[66:67]
	s_nop 0
	v_pk_fma_f32 v[86:87], v[64:65], s[62:63], v[80:81] op_sel_hi:[1,0,0]
	s_nop 0
	v_mul_f32_e32 v64, 0x4b800000, v87
	v_cmp_gt_f32_e32 vcc, s67, v87
	s_nop 1
	v_cndmask_b32_e32 v64, v87, v64, vcc
	v_rsq_f32_e32 v64, v64
	s_nop 0
	v_mul_f32_e32 v65, 0x45800000, v64
	v_cndmask_b32_e32 v128, v64, v65, vcc
	v_pk_mul_f32 v[64:65], v[128:129], v[94:95] op_sel_hi:[0,1]
	v_pk_mul_f32 v[66:67], v[128:129], v[130:131] op_sel_hi:[0,1]
	v_pk_mul_f32 v[94:95], v[128:129], v[146:147] op_sel_hi:[0,1]
	v_pk_mul_f32 v[130:131], v[128:129], v[148:149] op_sel_hi:[0,1]
	v_pk_mul_f32 v[64:65], v[16:17], v[64:65]
	v_pk_mul_f32 v[66:67], v[18:19], v[66:67]
	v_pk_mul_f32 v[94:95], v[24:25], v[94:95]
	v_pk_mul_f32 v[130:131], v[26:27], v[130:131]
	s_waitcnt vmcnt(0)
	v_pk_fma_f32 v[64:65], v[72:73], v[64:65], v[82:83]
	v_pk_fma_f32 v[66:67], v[66:67], v[74:75], v[84:85]
	v_pk_fma_f32 v[68:69], v[94:95], v[68:69], v[76:77]
	v_pk_fma_f32 v[70:71], v[130:131], v[70:71], v[78:79]
	v_cvt_pk_bf16_f32 v64, v64, v65
	v_cvt_pk_bf16_f32 v65, v66, v67
	v_cvt_pk_bf16_f32 v66, v68, v69
	v_cvt_pk_bf16_f32 v67, v70, v71
	global_store_dwordx4 v[124:125], v[64:67], off
	global_load_dwordx4 v[66:69], v[144:145], off offset:2048
	s_nop 0
	global_load_dwordx4 v[70:73], v[144:145], off offset:2064
	global_load_dwordx4 v[74:77], v[142:143], off offset:2048
	global_load_dwordx4 v[82:85], v[142:143], off offset:2064
	v_add_u32_e32 v129, s66, v122
	v_ashrrev_i32_e32 v64, 31, v129
	v_lshrrev_b32_e32 v64, 20, v64
	v_add_u32_e32 v64, v129, v64
	v_pk_mul_f32 v[88:89], v[128:129], v[88:89] op_sel_hi:[0,1]
	v_pk_mul_f32 v[90:91], v[128:129], v[90:91] op_sel_hi:[0,1]
	v_pk_mul_f32 v[92:93], v[128:129], v[92:93] op_sel_hi:[0,1]
	v_pk_mul_f32 v[94:95], v[128:129], v[126:127] op_sel_hi:[0,1]
	v_ashrrev_i32_e32 v64, 12, v64
	v_pk_mul_f32 v[88:89], v[28:29], v[88:89]
	v_pk_mul_f32 v[90:91], v[30:31], v[90:91]
	v_pk_mul_f32 v[92:93], v[20:21], v[92:93]
	v_pk_mul_f32 v[94:95], v[22:23], v[94:95]
	v_mul_hi_i32_i24_e32 v65, 0x1800, v64
	v_mul_i32_i24_e32 v64, 0x1800, v64
	v_lshlrev_b64 v[64:65], 2, v[64:65]
	v_lshl_add_u64 v[78:79], v[102:103], 0, v[64:65]
	v_cmp_gt_f32_e32 vcc, s67, v86
	s_waitcnt vmcnt(3)
	v_pk_add_f32 v[66:67], v[66:67], 1.0 op_sel_hi:[1,0]
	v_pk_add_f32 v[68:69], v[68:69], 1.0 op_sel_hi:[1,0]
	s_waitcnt vmcnt(2)
	v_pk_add_f32 v[70:71], v[70:71], 1.0 op_sel_hi:[1,0]
	v_pk_add_f32 v[72:73], v[72:73], 1.0 op_sel_hi:[1,0]
	s_waitcnt vmcnt(1)
	v_pk_fma_f32 v[66:67], v[88:89], v[66:67], v[74:75]
	v_pk_fma_f32 v[68:69], v[90:91], v[68:69], v[76:77]
	s_waitcnt vmcnt(0)
	v_pk_fma_f32 v[70:71], v[92:93], v[70:71], v[82:83]
	v_pk_fma_f32 v[72:73], v[94:95], v[72:73], v[84:85]
	v_cvt_pk_bf16_f32 v66, v66, v67
	v_cvt_pk_bf16_f32 v67, v68, v69
	v_cvt_pk_bf16_f32 v68, v70, v71
	v_cvt_pk_bf16_f32 v69, v72, v73
	global_store_dwordx4 v[124:125], v[66:69], off offset:1024
	global_load_dwordx4 v[66:69], v[78:79], off
	s_nop 0
	global_load_dwordx4 v[70:73], v[78:79], off offset:16
	v_mul_f32_e32 v85, 0x4b800000, v86
	v_cndmask_b32_e32 v85, v86, v85, vcc
	v_rsq_f32_e32 v86, v85
	v_lshlrev_b32_e32 v82, 16, v56
	v_and_b32_e32 v83, 0xffff0000, v56
	v_lshlrev_b32_e32 v56, 16, v57
	v_mul_f32_e32 v87, 0x45800000, v86
	v_and_b32_e32 v57, 0xffff0000, v57
	v_lshlrev_b32_e32 v84, 16, v58
	v_and_b32_e32 v85, 0xffff0000, v58
	v_lshlrev_b32_e32 v58, 16, v59
	v_and_b32_e32 v59, 0xffff0000, v59
	v_cndmask_b32_e32 v86, v86, v87, vcc
	v_pk_mul_f32 v[82:83], v[86:87], v[82:83] op_sel_hi:[0,1]
	v_pk_mul_f32 v[56:57], v[86:87], v[56:57] op_sel_hi:[0,1]
	v_pk_mul_f32 v[84:85], v[86:87], v[84:85] op_sel_hi:[0,1]
	v_pk_mul_f32 v[58:59], v[86:87], v[58:59] op_sel_hi:[0,1]
	v_lshlrev_b32_e32 v74, 16, v60
	v_and_b32_e32 v75, 0xffff0000, v60
	v_lshlrev_b32_e32 v60, 16, v61
	v_and_b32_e32 v61, 0xffff0000, v61
	v_lshlrev_b32_e32 v76, 16, v62
	v_and_b32_e32 v77, 0xffff0000, v62
	v_lshlrev_b32_e32 v62, 16, v63
	v_and_b32_e32 v63, 0xffff0000, v63
	v_pk_mul_f32 v[82:83], v[4:5], v[82:83]
	v_pk_mul_f32 v[56:57], v[6:7], v[56:57]
	v_pk_mul_f32 v[84:85], v[0:1], v[84:85]
	v_pk_mul_f32 v[58:59], v[2:3], v[58:59]
	v_lshl_add_u64 v[88:89], v[106:107], 0, v[64:65]
	s_waitcnt vmcnt(1)
	v_pk_fma_f32 v[66:67], v[66:67], v[82:83], v[74:75]
	v_pk_fma_f32 v[60:61], v[68:69], v[56:57], v[60:61]
	s_waitcnt vmcnt(0)
	v_pk_fma_f32 v[68:69], v[70:71], v[84:85], v[76:77]
	v_pk_fma_f32 v[62:63], v[72:73], v[58:59], v[62:63]
	v_cvt_pk_bf16_f32 v56, v66, v67
	v_cvt_pk_bf16_f32 v57, v60, v61
	v_cvt_pk_bf16_f32 v58, v68, v69
	v_cvt_pk_bf16_f32 v59, v62, v63
	global_store_dwordx4 v[120:121], v[56:59], off
	global_load_dwordx4 v[60:63], v[78:79], off offset:2048
	global_load_dwordx4 v[66:69], v[78:79], off offset:2064
	v_lshlrev_b32_e32 v74, 16, v48
	v_and_b32_e32 v75, 0xffff0000, v48
	v_lshlrev_b32_e32 v76, 16, v50
	v_and_b32_e32 v77, 0xffff0000, v50
	v_lshl_add_u64 v[84:85], v[104:105], 0, v[64:65]
	v_pk_mul_f32 v[64:65], v[86:87], v[74:75] op_sel_hi:[0,1]
	v_pk_mul_f32 v[74:75], v[86:87], v[76:77] op_sel_hi:[0,1]
	v_and_b32_e32 v77, 0xffff0000, v56
	v_lshlrev_b32_e32 v48, 16, v49
	v_and_b32_e32 v49, 0xffff0000, v49
	v_lshlrev_b32_e32 v50, 16, v51
	v_and_b32_e32 v51, 0xffff0000, v51
	v_lshlrev_b32_e32 v76, 16, v56
	v_mul_f32_e32 v56, v77, v77
	v_pk_mul_f32 v[48:49], v[86:87], v[48:49] op_sel_hi:[0,1]
	v_pk_mul_f32 v[50:51], v[86:87], v[50:51] op_sel_hi:[0,1]
	v_lshlrev_b32_e32 v86, 16, v57
	v_and_b32_e32 v87, 0xffff0000, v57
	v_pk_fma_f32 v[56:57], v[76:77], v[76:77], v[56:57] op_sel_hi:[1,1,0]
	v_lshlrev_b32_e32 v90, 16, v58
	v_and_b32_e32 v91, 0xffff0000, v58
	v_mul_f32_e32 v58, v87, v87
	v_pk_fma_f32 v[56:57], v[86:87], v[86:87], v[56:57]
	v_lshlrev_b32_e32 v70, 16, v52
	v_pk_add_f32 v[56:57], v[58:59], v[56:57] op_sel_hi:[0,1]
	v_and_b32_e32 v71, 0xffff0000, v52
	v_lshlrev_b32_e32 v52, 16, v53
	v_and_b32_e32 v53, 0xffff0000, v53
	v_lshlrev_b32_e32 v72, 16, v54
	v_and_b32_e32 v73, 0xffff0000, v54
	v_lshlrev_b32_e32 v54, 16, v55
	v_and_b32_e32 v55, 0xffff0000, v55
	v_pk_mul_f32 v[64:65], v[12:13], v[64:65]
	v_pk_mul_f32 v[48:49], v[14:15], v[48:49]
	v_pk_mul_f32 v[74:75], v[8:9], v[74:75]
	v_pk_mul_f32 v[50:51], v[10:11], v[50:51]
	v_mul_f32_e32 v94, v91, v91
	v_pk_fma_f32 v[56:57], v[90:91], v[90:91], v[56:57]
	v_lshlrev_b32_e32 v92, 16, v59
	v_and_b32_e32 v93, 0xffff0000, v59
	v_pk_add_f32 v[94:95], v[94:95], v[56:57] op_sel_hi:[0,1]
	v_mov_b32_e32 v78, v123
	s_nop 1
	v_permlane32_swap_b32_e32 v123, v78
	v_mul_f32_e32 v122, v93, v93
	v_add_f32_e32 v78, v123, v78
	v_mov_b32_e32 v82, v78
	s_nop 1
	v_permlane16_swap_b32_e32 v78, v82
	s_waitcnt vmcnt(1)
	v_pk_fma_f32 v[56:57], v[64:65], v[60:61], v[70:71]
	v_pk_fma_f32 v[52:53], v[48:49], v[62:63], v[52:53]
	s_waitcnt vmcnt(0)
	v_pk_fma_f32 v[58:59], v[74:75], v[66:67], v[72:73]
	v_pk_fma_f32 v[54:55], v[50:51], v[68:69], v[54:55]
	v_cvt_pk_bf16_f32 v48, v56, v57
	v_cvt_pk_bf16_f32 v49, v52, v53
	v_cvt_pk_bf16_f32 v50, v58, v59
	v_cvt_pk_bf16_f32 v51, v54, v55
	global_store_dwordx4 v[120:121], v[48:51], off offset:1024
	global_load_dwordx4 v[52:55], v[88:89], off offset:16
	global_load_dwordx4 v[56:59], v[88:89], off
	global_load_dwordx4 v[60:63], v[84:85], off offset:16
	global_load_dwordx4 v[64:67], v[84:85], off
	v_pk_fma_f32 v[68:69], v[92:93], v[92:93], v[94:95]
	v_lshlrev_b32_e32 v70, 16, v48
	v_pk_add_f32 v[68:69], v[122:123], v[68:69] op_sel_hi:[0,1]
	v_and_b32_e32 v71, 0xffff0000, v48
	v_lshlrev_b32_e32 v72, 16, v49
	v_and_b32_e32 v73, 0xffff0000, v49
	v_lshlrev_b32_e32 v74, 16, v50
	v_and_b32_e32 v75, 0xffff0000, v50
	v_pk_fma_f32 v[48:49], v[70:71], v[70:71], v[68:69]
	v_mul_f32_e32 v50, v71, v71
	v_pk_add_f32 v[48:49], v[50:51], v[48:49] op_sel_hi:[0,1]
	v_mul_f32_e32 v68, v73, v73
	v_pk_fma_f32 v[48:49], v[72:73], v[72:73], v[48:49]
	v_mul_f32_e32 v120, v75, v75
	v_pk_add_f32 v[48:49], v[68:69], v[48:49] op_sel_hi:[0,1]
	v_pk_fma_f32 v[48:49], v[74:75], v[74:75], v[48:49]
	v_lshlrev_b32_e32 v94, 16, v51
	v_and_b32_e32 v95, 0xffff0000, v51
	v_pk_add_f32 v[48:49], v[120:121], v[48:49] op_sel_hi:[0,1]
	v_mul_f32_e32 v122, v95, v95
	v_pk_fma_f32 v[48:49], v[94:95], v[94:95], v[48:49]
	s_waitcnt vmcnt(3)
	v_pk_add_f32 v[52:53], v[52:53], 1.0 op_sel_hi:[1,0]
	v_pk_add_f32 v[48:49], v[122:123], v[48:49] op_sel_hi:[0,1]
	v_mov_b32_e32 v49, v48
	s_nop 1
	v_permlane32_swap_b32_e32 v48, v49
	v_add_f32_e32 v79, v48, v49
	v_mov_b32_e32 v83, v79
	s_nop 1
	v_permlane16_swap_b32_e32 v79, v83
	v_pk_add_f32 v[48:49], v[78:79], v[82:83]
	s_nop 1
	v_mov_b32_dpp v51, v49 row_ror:8 row_mask:0xf bank_mask:0xf
	s_nop 1
	v_mov_b32_dpp v50, v48 row_ror:8 row_mask:0xf bank_mask:0xf
	s_waitcnt vmcnt(2)
	v_pk_add_f32 v[58:59], v[58:59], 1.0 op_sel_hi:[1,0]
	v_pk_add_f32 v[56:57], v[56:57], 1.0 op_sel_hi:[1,0]
	v_pk_add_f32 v[54:55], v[54:55], 1.0 op_sel_hi:[1,0]
	v_lshl_add_u64 v[78:79], v[108:109], 0, v[118:119]
	s_waitcnt lgkmcnt(0)
	v_pk_add_f32 v[48:49], v[48:49], v[50:51]
	s_nop 1
	v_mov_b32_dpp v51, v49 row_ror:4 row_mask:0xf bank_mask:0xf
	s_nop 1
	v_mov_b32_dpp v50, v48 row_ror:4 row_mask:0xf bank_mask:0xf
	s_waitcnt lgkmcnt(0)
	v_pk_add_f32 v[48:49], v[48:49], v[50:51]
	s_nop 1
	v_mov_b32_dpp v51, v49 row_ror:2 row_mask:0xf bank_mask:0xf
	s_nop 1
	v_mov_b32_dpp v50, v48 row_ror:2 row_mask:0xf bank_mask:0xf
	s_waitcnt lgkmcnt(0)
	v_pk_add_f32 v[48:49], v[48:49], v[50:51]
	s_nop 1
	v_mov_b32_dpp v51, v49 row_ror:1 row_mask:0xf bank_mask:0xf
	s_nop 1
	v_mov_b32_dpp v50, v48 row_ror:1 row_mask:0xf bank_mask:0xf
	s_waitcnt lgkmcnt(0)
	v_pk_add_f32 v[48:49], v[48:49], v[50:51]
	s_nop 0
	v_pk_fma_f32 v[68:69], v[48:49], s[62:63], v[80:81] op_sel_hi:[1,0,0]
	s_nop 0
	v_mul_f32_e32 v48, 0x4b800000, v69
	v_cmp_gt_f32_e32 vcc, s67, v69
	s_nop 1
	v_cndmask_b32_e32 v48, v69, v48, vcc
	v_rsq_f32_e32 v48, v48
	s_nop 0
	v_mul_f32_e32 v49, 0x45800000, v48
	v_cndmask_b32_e32 v80, v48, v49, vcc
	v_pk_mul_f32 v[48:49], v[80:81], v[76:77] op_sel_hi:[0,1]
	v_pk_mul_f32 v[50:51], v[80:81], v[86:87] op_sel_hi:[0,1]
	v_pk_mul_f32 v[76:77], v[80:81], v[90:91] op_sel_hi:[0,1]
	v_pk_mul_f32 v[82:83], v[80:81], v[92:93] op_sel_hi:[0,1]
	v_pk_mul_f32 v[48:49], v[16:17], v[48:49]
	v_pk_mul_f32 v[50:51], v[18:19], v[50:51]
	v_pk_mul_f32 v[76:77], v[24:25], v[76:77]
	v_pk_mul_f32 v[82:83], v[26:27], v[82:83]
	s_waitcnt vmcnt(0)
	v_pk_fma_f32 v[48:49], v[56:57], v[48:49], v[64:65]
	v_pk_fma_f32 v[50:51], v[50:51], v[58:59], v[66:67]
	v_pk_fma_f32 v[52:53], v[76:77], v[52:53], v[60:61]
	v_pk_fma_f32 v[54:55], v[82:83], v[54:55], v[62:63]
	v_cvt_pk_bf16_f32 v48, v48, v49
	v_cvt_pk_bf16_f32 v49, v50, v51
	v_cvt_pk_bf16_f32 v50, v52, v53
	v_cvt_pk_bf16_f32 v51, v54, v55
	global_store_dwordx4 v[78:79], v[48:51], off
	global_load_dwordx4 v[48:51], v[88:89], off offset:2048
	s_nop 0
	global_load_dwordx4 v[52:55], v[88:89], off offset:2064
	global_load_dwordx4 v[56:59], v[84:85], off offset:2048
	global_load_dwordx4 v[60:63], v[84:85], off offset:2064
	v_add_u32_e32 v81, s66, v129
	v_ashrrev_i32_e32 v64, 31, v81
	v_lshrrev_b32_e32 v64, 20, v64
	v_add_u32_e32 v64, v81, v64
	v_pk_mul_f32 v[70:71], v[80:81], v[70:71] op_sel_hi:[0,1]
	v_pk_mul_f32 v[72:73], v[80:81], v[72:73] op_sel_hi:[0,1]
	v_pk_mul_f32 v[74:75], v[80:81], v[74:75] op_sel_hi:[0,1]
	v_pk_mul_f32 v[76:77], v[80:81], v[94:95] op_sel_hi:[0,1]
	v_ashrrev_i32_e32 v64, 12, v64
	v_pk_mul_f32 v[70:71], v[28:29], v[70:71]
	v_pk_mul_f32 v[72:73], v[30:31], v[72:73]
	v_pk_mul_f32 v[74:75], v[20:21], v[74:75]
	v_pk_mul_f32 v[76:77], v[22:23], v[76:77]
	v_mul_hi_i32_i24_e32 v65, 0x1800, v64
	v_mul_i32_i24_e32 v64, 0x1800, v64
	v_lshlrev_b64 v[64:65], 2, v[64:65]
	v_lshl_add_u64 v[66:67], v[102:103], 0, v[64:65]
	v_cmp_gt_f32_e32 vcc, s67, v68
	v_add_u32_e32 v130, s66, v81
	s_waitcnt vmcnt(3)
	v_pk_add_f32 v[48:49], v[48:49], 1.0 op_sel_hi:[1,0]
	v_pk_add_f32 v[50:51], v[50:51], 1.0 op_sel_hi:[1,0]
	s_waitcnt vmcnt(2)
	v_pk_add_f32 v[52:53], v[52:53], 1.0 op_sel_hi:[1,0]
	v_pk_add_f32 v[54:55], v[54:55], 1.0 op_sel_hi:[1,0]
	s_waitcnt vmcnt(1)
	v_pk_fma_f32 v[48:49], v[70:71], v[48:49], v[56:57]
	v_pk_fma_f32 v[50:51], v[72:73], v[50:51], v[58:59]
	s_waitcnt vmcnt(0)
	v_pk_fma_f32 v[52:53], v[74:75], v[52:53], v[60:61]
	v_pk_fma_f32 v[54:55], v[76:77], v[54:55], v[62:63]
	v_cvt_pk_bf16_f32 v48, v48, v49
	v_cvt_pk_bf16_f32 v49, v50, v51
	v_cvt_pk_bf16_f32 v50, v52, v53
	v_cvt_pk_bf16_f32 v51, v54, v55
	global_store_dwordx4 v[78:79], v[48:51], off offset:1024
	global_load_dwordx4 v[48:51], v[66:67], off
	s_nop 0
	global_load_dwordx4 v[52:55], v[66:67], off offset:16
	v_mul_f32_e32 v63, 0x4b800000, v68
	v_cndmask_b32_e32 v63, v68, v63, vcc
	v_rsq_f32_e32 v68, v63
	v_lshlrev_b32_e32 v60, 16, v40
	v_and_b32_e32 v61, 0xffff0000, v40
	v_lshlrev_b32_e32 v40, 16, v41
	v_mul_f32_e32 v69, 0x45800000, v68
	v_and_b32_e32 v41, 0xffff0000, v41
	v_lshlrev_b32_e32 v62, 16, v42
	v_and_b32_e32 v63, 0xffff0000, v42
	v_lshlrev_b32_e32 v42, 16, v43
	v_and_b32_e32 v43, 0xffff0000, v43
	v_cndmask_b32_e32 v68, v68, v69, vcc
	v_pk_mul_f32 v[60:61], v[68:69], v[60:61] op_sel_hi:[0,1]
	v_pk_mul_f32 v[40:41], v[68:69], v[40:41] op_sel_hi:[0,1]
	v_pk_mul_f32 v[62:63], v[68:69], v[62:63] op_sel_hi:[0,1]
	v_pk_mul_f32 v[42:43], v[68:69], v[42:43] op_sel_hi:[0,1]
	v_lshlrev_b32_e32 v56, 16, v44
	v_and_b32_e32 v57, 0xffff0000, v44
	v_lshlrev_b32_e32 v44, 16, v45
	v_and_b32_e32 v45, 0xffff0000, v45
	v_lshlrev_b32_e32 v58, 16, v46
	v_and_b32_e32 v59, 0xffff0000, v46
	v_lshlrev_b32_e32 v46, 16, v47
	v_and_b32_e32 v47, 0xffff0000, v47
	v_pk_mul_f32 v[60:61], v[4:5], v[60:61]
	v_pk_mul_f32 v[40:41], v[6:7], v[40:41]
	v_pk_mul_f32 v[62:63], v[0:1], v[62:63]
	v_pk_mul_f32 v[42:43], v[2:3], v[42:43]
	s_waitcnt vmcnt(1)
	v_pk_fma_f32 v[48:49], v[48:49], v[60:61], v[56:57]
	v_pk_fma_f32 v[44:45], v[50:51], v[40:41], v[44:45]
	s_waitcnt vmcnt(0)
	v_pk_fma_f32 v[50:51], v[52:53], v[62:63], v[58:59]
	v_pk_fma_f32 v[46:47], v[54:55], v[42:43], v[46:47]
	v_cvt_pk_bf16_f32 v40, v48, v49
	v_cvt_pk_bf16_f32 v41, v44, v45
	v_cvt_pk_bf16_f32 v42, v50, v51
	v_cvt_pk_bf16_f32 v43, v46, v47
	global_store_dwordx4 v[116:117], v[40:43], off
	global_load_dwordx4 v[44:47], v[66:67], off offset:2048
	global_load_dwordx4 v[48:51], v[66:67], off offset:2064
	v_lshlrev_b32_e32 v56, 16, v32
	v_and_b32_e32 v57, 0xffff0000, v32
	v_lshlrev_b32_e32 v32, 16, v33
	v_and_b32_e32 v33, 0xffff0000, v33
	v_lshlrev_b32_e32 v58, 16, v34
	v_and_b32_e32 v59, 0xffff0000, v34
	v_lshlrev_b32_e32 v34, 16, v35
	v_and_b32_e32 v35, 0xffff0000, v35
	v_lshl_add_u64 v[60:61], v[104:105], 0, v[64:65]
	v_lshl_add_u64 v[62:63], v[106:107], 0, v[64:65]
	v_pk_mul_f32 v[56:57], v[68:69], v[56:57] op_sel_hi:[0,1]
	v_pk_mul_f32 v[32:33], v[68:69], v[32:33] op_sel_hi:[0,1]
	v_pk_mul_f32 v[58:59], v[68:69], v[58:59] op_sel_hi:[0,1]
	v_pk_mul_f32 v[34:35], v[68:69], v[34:35] op_sel_hi:[0,1]
	v_and_b32_e32 v65, 0xffff0000, v40
	v_lshlrev_b32_e32 v52, 16, v36
	v_and_b32_e32 v53, 0xffff0000, v36
	v_lshlrev_b32_e32 v36, 16, v37
	v_and_b32_e32 v37, 0xffff0000, v37
	v_lshlrev_b32_e32 v54, 16, v38
	v_and_b32_e32 v55, 0xffff0000, v38
	v_lshlrev_b32_e32 v38, 16, v39
	v_and_b32_e32 v39, 0xffff0000, v39
	v_pk_mul_f32 v[56:57], v[12:13], v[56:57]
	v_pk_mul_f32 v[32:33], v[14:15], v[32:33]
	v_pk_mul_f32 v[58:59], v[8:9], v[58:59]
	v_pk_mul_f32 v[34:35], v[10:11], v[34:35]
	v_lshlrev_b32_e32 v64, 16, v40
	v_mul_f32_e32 v40, v65, v65
	v_lshlrev_b32_e32 v66, 16, v41
	v_and_b32_e32 v67, 0xffff0000, v41
	v_lshlrev_b32_e32 v68, 16, v42
	v_and_b32_e32 v69, 0xffff0000, v42
	v_lshlrev_b32_e32 v70, 16, v43
	v_and_b32_e32 v71, 0xffff0000, v43
	v_pk_fma_f32 v[78:79], v[64:65], v[64:65], v[40:41] op_sel_hi:[1,1,0]
	v_mul_f32_e32 v72, v67, v67
	v_mul_f32_e32 v74, v69, v69
	v_mul_f32_e32 v76, v71, v71
	s_waitcnt vmcnt(1)
	v_pk_fma_f32 v[40:41], v[56:57], v[44:45], v[52:53]
	v_pk_fma_f32 v[36:37], v[32:33], v[46:47], v[36:37]
	s_waitcnt vmcnt(0)
	v_pk_fma_f32 v[42:43], v[58:59], v[48:49], v[54:55]
	v_pk_fma_f32 v[38:39], v[34:35], v[50:51], v[38:39]
	v_cvt_pk_bf16_f32 v32, v40, v41
	v_cvt_pk_bf16_f32 v33, v36, v37
	v_cvt_pk_bf16_f32 v34, v42, v43
	v_cvt_pk_bf16_f32 v35, v38, v39
	global_store_dwordx4 v[116:117], v[32:35], off offset:1024
	global_load_dwordx4 v[36:39], v[62:63], off offset:16
	global_load_dwordx4 v[40:43], v[62:63], off
	global_load_dwordx4 v[44:47], v[60:61], off offset:16
	global_load_dwordx4 v[48:51], v[60:61], off
	v_pk_fma_f32 v[52:53], v[66:67], v[66:67], v[78:79]
	v_lshlrev_b32_e32 v54, 16, v32
	v_pk_add_f32 v[52:53], v[72:73], v[52:53] op_sel_hi:[0,1]
	v_pk_fma_f32 v[52:53], v[68:69], v[68:69], v[52:53]
	v_and_b32_e32 v55, 0xffff0000, v32
	v_pk_add_f32 v[52:53], v[74:75], v[52:53] op_sel_hi:[0,1]
	v_pk_fma_f32 v[52:53], v[70:71], v[70:71], v[52:53]
	v_lshlrev_b32_e32 v56, 16, v33
	v_pk_add_f32 v[52:53], v[76:77], v[52:53] op_sel_hi:[0,1]
	v_and_b32_e32 v57, 0xffff0000, v33
	v_lshlrev_b32_e32 v58, 16, v34
	v_and_b32_e32 v59, 0xffff0000, v34
	v_pk_fma_f32 v[32:33], v[54:55], v[54:55], v[52:53]
	v_mul_f32_e32 v34, v55, v55
	v_pk_add_f32 v[32:33], v[34:35], v[32:33] op_sel_hi:[0,1]
	v_mul_f32_e32 v52, v57, v57
	v_pk_fma_f32 v[32:33], v[56:57], v[56:57], v[32:33]
	v_mul_f32_e32 v74, v59, v59
	v_pk_add_f32 v[32:33], v[52:53], v[32:33] op_sel_hi:[0,1]
	v_pk_fma_f32 v[32:33], v[58:59], v[58:59], v[32:33]
	v_lshlrev_b32_e32 v72, 16, v35
	v_and_b32_e32 v73, 0xffff0000, v35
	v_pk_add_f32 v[32:33], v[74:75], v[32:33] op_sel_hi:[0,1]
	v_mul_f32_e32 v76, v73, v73
	v_pk_fma_f32 v[32:33], v[72:73], v[72:73], v[32:33]
	v_lshl_add_u64 v[52:53], v[108:109], 0, v[114:115]
	v_pk_add_f32 v[32:33], v[76:77], v[32:33] op_sel_hi:[0,1]
	v_mov_b32_e32 v33, v32
	s_nop 1
	v_permlane32_swap_b32_e32 v32, v33
	v_add_f32_e32 v32, v32, v33
	v_mov_b32_e32 v33, v32
	s_nop 1
	v_permlane16_swap_b32_e32 v32, v33
	v_add_f32_e32 v32, v32, v33
	s_nop 1
	v_mov_b32_dpp v33, v32 row_ror:8 row_mask:0xf bank_mask:0xf
	s_waitcnt lgkmcnt(0)
	v_add_f32_e32 v32, v32, v33
	s_nop 1
	v_mov_b32_dpp v33, v32 row_ror:4 row_mask:0xf bank_mask:0xf
	s_waitcnt lgkmcnt(0)
	v_add_f32_e32 v32, v32, v33
	s_nop 1
	v_mov_b32_dpp v33, v32 row_ror:2 row_mask:0xf bank_mask:0xf
	s_waitcnt lgkmcnt(0)
	v_add_f32_e32 v32, v32, v33
	s_nop 1
	v_mov_b32_dpp v33, v32 row_ror:1 row_mask:0xf bank_mask:0xf
	s_waitcnt lgkmcnt(0)
	v_add_f32_e32 v32, v32, v33
	v_fmamk_f32 v32, v32, 0x3a800000, v188
	v_mul_f32_e32 v33, 0x4b800000, v32
	v_cmp_gt_f32_e32 vcc, s67, v32
	s_waitcnt vmcnt(3)
	v_pk_add_f32 v[36:37], v[36:37], 1.0 op_sel_hi:[1,0]
	v_cndmask_b32_e32 v32, v32, v33, vcc
	v_rsq_f32_e32 v32, v32
	s_waitcnt vmcnt(2)
	v_pk_add_f32 v[42:43], v[42:43], 1.0 op_sel_hi:[1,0]
	v_pk_add_f32 v[40:41], v[40:41], 1.0 op_sel_hi:[1,0]
	v_pk_add_f32 v[38:39], v[38:39], 1.0 op_sel_hi:[1,0]
	v_mul_f32_e32 v33, 0x45800000, v32
	v_cndmask_b32_e32 v74, v32, v33, vcc
	v_pk_mul_f32 v[32:33], v[74:75], v[64:65] op_sel_hi:[0,1]
	v_pk_mul_f32 v[34:35], v[74:75], v[66:67] op_sel_hi:[0,1]
	v_pk_mul_f32 v[64:65], v[74:75], v[68:69] op_sel_hi:[0,1]
	v_pk_mul_f32 v[66:67], v[74:75], v[70:71] op_sel_hi:[0,1]
	v_pk_mul_f32 v[32:33], v[16:17], v[32:33]
	v_pk_mul_f32 v[34:35], v[18:19], v[34:35]
	v_pk_mul_f32 v[64:65], v[24:25], v[64:65]
	v_pk_mul_f32 v[66:67], v[26:27], v[66:67]
	s_waitcnt vmcnt(0)
	v_pk_fma_f32 v[32:33], v[40:41], v[32:33], v[48:49]
	v_pk_fma_f32 v[34:35], v[34:35], v[42:43], v[50:51]
	v_pk_fma_f32 v[36:37], v[64:65], v[36:37], v[44:45]
	v_pk_fma_f32 v[38:39], v[66:67], v[38:39], v[46:47]
	v_cvt_pk_bf16_f32 v32, v32, v33
	v_cvt_pk_bf16_f32 v33, v34, v35
	v_cvt_pk_bf16_f32 v34, v36, v37
	v_cvt_pk_bf16_f32 v35, v38, v39
	global_store_dwordx4 v[52:53], v[32:35], off
	global_load_dwordx4 v[32:35], v[62:63], off offset:2048
	s_nop 0
	global_load_dwordx4 v[36:39], v[62:63], off offset:2064
	global_load_dwordx4 v[40:43], v[60:61], off offset:2048
	global_load_dwordx4 v[44:47], v[60:61], off offset:2064
	v_pk_mul_f32 v[48:49], v[74:75], v[54:55] op_sel_hi:[0,1]
	v_pk_mul_f32 v[50:51], v[74:75], v[56:57] op_sel_hi:[0,1]
	v_pk_mul_f32 v[54:55], v[74:75], v[58:59] op_sel_hi:[0,1]
	v_pk_mul_f32 v[56:57], v[74:75], v[72:73] op_sel_hi:[0,1]
	v_pk_mul_f32 v[48:49], v[28:29], v[48:49]
	v_pk_mul_f32 v[50:51], v[30:31], v[50:51]
	v_pk_mul_f32 v[54:55], v[20:21], v[54:55]
	v_pk_mul_f32 v[56:57], v[22:23], v[56:57]
	v_cmp_lt_i32_e32 vcc, s46, v130
	s_or_b64 s[12:13], vcc, s[12:13]
	s_waitcnt vmcnt(3)
	v_pk_add_f32 v[32:33], v[32:33], 1.0 op_sel_hi:[1,0]
	v_pk_add_f32 v[34:35], v[34:35], 1.0 op_sel_hi:[1,0]
	s_waitcnt vmcnt(2)
	v_pk_add_f32 v[36:37], v[36:37], 1.0 op_sel_hi:[1,0]
	v_pk_add_f32 v[38:39], v[38:39], 1.0 op_sel_hi:[1,0]
	s_waitcnt vmcnt(1)
	v_pk_fma_f32 v[32:33], v[48:49], v[32:33], v[40:41]
	v_pk_fma_f32 v[34:35], v[50:51], v[34:35], v[42:43]
	s_waitcnt vmcnt(0)
	v_pk_fma_f32 v[36:37], v[54:55], v[36:37], v[44:45]
	v_pk_fma_f32 v[38:39], v[56:57], v[38:39], v[46:47]
	v_cvt_pk_bf16_f32 v32, v32, v33
	v_cvt_pk_bf16_f32 v33, v34, v35
	v_cvt_pk_bf16_f32 v34, v36, v37
	v_cvt_pk_bf16_f32 v35, v38, v39
	global_store_dwordx4 v[52:53], v[32:35], off offset:1024
	s_andn2_b64 exec, exec, s[12:13]
	s_cbranch_execz .LBB0_2461
